# v17 with attention fast path v4: softmax of sub-step 0 interleaved under the QK MFMAs of sub-step 1 (second S block), windowed register-slot allocator for LDS fragments
# speedup vs baseline: 1.0103x; 1.0103x over previous
.LBB0_847:
	s_cmp_gt_i32 s43, s84
	s_cbranch_scc1 .LBB0_858
	s_add_i32 s100, s43, 63
	s_cmp_le_i32 s100, s83
	s_cbranch_scc0 .Latt_slow_0
	s_lshl_b32 s98, s88, 14
	s_lshl_b32 s99, s88, 15
	s_add_i32 s99, s99, 0xc000
	v_add_u32_e32 v206, s98, v194
	ds_read_b128 v[206:209], v206
	v_add_u32_e32 v210, s98, v195
	ds_read_b128 v[210:213], v210
	v_add_u32_e32 v214, s98, v196
	ds_read_b128 v[214:217], v214
	v_add_u32_e32 v238, s98, v197
	ds_read_b128 v[238:241], v238
	v_add_u32_e32 v242, s98, v198
	ds_read_b128 v[242:245], v242
	v_add_u32_e32 v250, s98, v199
	ds_read_b128 v[250:253], v250
	v_add_u32_e32 v222, s98, v200
	ds_read_b128 v[222:225], v222
	v_add_u32_e32 v226, s98, v201
	ds_read_b128 v[226:229], v226
	v_bfe_u32 v246, v203, 2, 2
	v_bfe_u32 v247, v203, 5, 1
	v_lshl_or_b32 v247, v247, 2, v246
	v_and_b32_e32 v249, 3, v203
	v_and_b32_e32 v254, 16, v203
	v_lshl_or_b32 v249, v249, 2, v254
	v_lshlrev_b32_e32 v249, 1, v249
	v_lshl_add_u32 v247, v247, 9, v249
	v_add_u32_e32 v247, s99, v247
	v_lshlrev_b32_e32 v246, 6, v246
	v_add_u32_e32 v205, v247, v246
	v_xor_b32_e32 v249, 64, v246
	v_add_u32_e32 v218, v247, v249
	v_xor_b32_e32 v249, 0x80, v246
	v_add_u32_e32 v219, v247, v249
	v_xor_b32_e32 v249, 0xc0, v246
	v_add_u32_e32 v221, v247, v249
	s_waitcnt lgkmcnt(7)
	v_mfma_f32_32x32x16_bf16 v[128:143], v[206:209], v[144:147], 0
	v_add_u32_e32 v206, s98, v194
	ds_read_b128 v[206:209], v206 offset:8192
	s_waitcnt lgkmcnt(7)
	v_mfma_f32_32x32x16_bf16 v[128:143], v[210:213], v[148:151], v[128:143]
	v_add_u32_e32 v210, s98, v195
	ds_read_b128 v[210:213], v210 offset:8192
	s_waitcnt lgkmcnt(7)
	v_mfma_f32_32x32x16_bf16 v[128:143], v[214:217], v[152:155], v[128:143]
	v_add_u32_e32 v214, s98, v196
	ds_read_b128 v[214:217], v214 offset:8192
	s_waitcnt lgkmcnt(7)
	v_mfma_f32_32x32x16_bf16 v[128:143], v[238:241], v[156:159], v[128:143]
	v_add_u32_e32 v238, s98, v197
	ds_read_b128 v[238:241], v238 offset:8192
	s_waitcnt lgkmcnt(7)
	v_mfma_f32_32x32x16_bf16 v[128:143], v[242:245], v[160:163], v[128:143]
	v_add_u32_e32 v242, s98, v198
	ds_read_b128 v[242:245], v242 offset:8192
	s_waitcnt lgkmcnt(7)
	v_mfma_f32_32x32x16_bf16 v[128:143], v[250:253], v[164:167], v[128:143]
	v_add_u32_e32 v250, s98, v199
	ds_read_b128 v[250:253], v250 offset:8192
	s_waitcnt lgkmcnt(7)
	v_mfma_f32_32x32x16_bf16 v[128:143], v[222:225], v[168:171], v[128:143]
	s_waitcnt lgkmcnt(6)
	v_mfma_f32_32x32x16_bf16 v[128:143], v[226:229], v[172:175], v[128:143]
	s_waitcnt lgkmcnt(5)
	v_mfma_f32_32x32x16_bf16 v[222:237], v[206:209], v[144:147], 0
	v_add_u32_e32 v206, s98, v200
	ds_read_b128 v[206:209], v206 offset:8192
	s_nop 7
	v_max3_f32 v246, v128, v129, v130
	v_max3_f32 v247, v131, v132, v133
	v_max3_f32 v246, v246, v134, v135
	v_max3_f32 v247, v247, v136, v137
	v_max3_f32 v246, v246, v138, v139
	v_max3_f32 v247, v247, v140, v141
	v_max3_f32 v246, v246, v142, v143
	s_waitcnt lgkmcnt(5)
	v_mfma_f32_32x32x16_bf16 v[222:237], v[210:213], v[148:151], v[222:237]
	v_add_u32_e32 v210, s98, v201
	ds_read_b128 v[210:213], v210 offset:8192
	v_max_f32_e32 v246, v246, v247
	v_mov_b32_e32 v247, v246
	v_add_f32_e32 v249, 0x41000000, v190
	s_nop 1
	v_permlane32_swap_b32_e32 v246, v247
	v_max_f32_e32 v246, v246, v247
	v_cmp_gt_f32_e32 vcc, v246, v249
	s_cbranch_vccz .Latt_nr0_0
	v_max_f32_e32 v246, v190, v246
	v_sub_f32_e32 v190, v190, v246
	v_exp_f32_e32 v190, v190
	s_nop 0
	v_pk_mul_f32 v[126:127], v[126:127], v[190:191] op_sel_hi:[1,0]
	v_pk_mul_f32 v[124:125], v[124:125], v[190:191] op_sel_hi:[1,0]
	v_pk_mul_f32 v[122:123], v[122:123], v[190:191] op_sel_hi:[1,0]
	v_pk_mul_f32 v[120:121], v[120:121], v[190:191] op_sel_hi:[1,0]
	v_pk_mul_f32 v[118:119], v[118:119], v[190:191] op_sel_hi:[1,0]
	v_pk_mul_f32 v[116:117], v[116:117], v[190:191] op_sel_hi:[1,0]
	v_pk_mul_f32 v[114:115], v[114:115], v[190:191] op_sel_hi:[1,0]
	v_pk_mul_f32 v[112:113], v[112:113], v[190:191] op_sel_hi:[1,0]
	v_pk_mul_f32 v[110:111], v[110:111], v[190:191] op_sel_hi:[1,0]
	v_pk_mul_f32 v[108:109], v[108:109], v[190:191] op_sel_hi:[1,0]
	v_pk_mul_f32 v[106:107], v[106:107], v[190:191] op_sel_hi:[1,0]
	v_pk_mul_f32 v[104:105], v[104:105], v[190:191] op_sel_hi:[1,0]
	v_pk_mul_f32 v[102:103], v[102:103], v[190:191] op_sel_hi:[1,0]
	v_pk_mul_f32 v[100:101], v[100:101], v[190:191] op_sel_hi:[1,0]
	v_pk_mul_f32 v[98:99], v[98:99], v[190:191] op_sel_hi:[1,0]
	v_pk_mul_f32 v[96:97], v[96:97], v[190:191] op_sel_hi:[1,0]
	v_pk_mul_f32 v[94:95], v[94:95], v[190:191] op_sel_hi:[1,0]
	v_pk_mul_f32 v[92:93], v[92:93], v[190:191] op_sel_hi:[1,0]
	v_pk_mul_f32 v[90:91], v[90:91], v[190:191] op_sel_hi:[1,0]
	v_pk_mul_f32 v[88:89], v[88:89], v[190:191] op_sel_hi:[1,0]
	v_pk_mul_f32 v[86:87], v[86:87], v[190:191] op_sel_hi:[1,0]
	v_pk_mul_f32 v[84:85], v[84:85], v[190:191] op_sel_hi:[1,0]
	v_pk_mul_f32 v[82:83], v[82:83], v[190:191] op_sel_hi:[1,0]
	v_pk_mul_f32 v[80:81], v[80:81], v[190:191] op_sel_hi:[1,0]
	v_pk_mul_f32 v[78:79], v[78:79], v[190:191] op_sel_hi:[1,0]
	v_pk_mul_f32 v[76:77], v[76:77], v[190:191] op_sel_hi:[1,0]
	v_pk_mul_f32 v[74:75], v[74:75], v[190:191] op_sel_hi:[1,0]
	v_pk_mul_f32 v[72:73], v[72:73], v[190:191] op_sel_hi:[1,0]
	v_pk_mul_f32 v[70:71], v[70:71], v[190:191] op_sel_hi:[1,0]
	v_pk_mul_f32 v[68:69], v[68:69], v[190:191] op_sel_hi:[1,0]
	v_pk_mul_f32 v[66:67], v[66:67], v[190:191] op_sel_hi:[1,0]
	v_pk_mul_f32 v[64:65], v[64:65], v[190:191] op_sel_hi:[1,0]
	v_pk_mul_f32 v[62:63], v[62:63], v[190:191] op_sel_hi:[1,0]
	v_pk_mul_f32 v[60:61], v[60:61], v[190:191] op_sel_hi:[1,0]
	v_pk_mul_f32 v[58:59], v[58:59], v[190:191] op_sel_hi:[1,0]
	v_pk_mul_f32 v[56:57], v[56:57], v[190:191] op_sel_hi:[1,0]
	v_pk_mul_f32 v[54:55], v[54:55], v[190:191] op_sel_hi:[1,0]
	v_pk_mul_f32 v[52:53], v[52:53], v[190:191] op_sel_hi:[1,0]
	v_pk_mul_f32 v[50:51], v[50:51], v[190:191] op_sel_hi:[1,0]
	v_pk_mul_f32 v[48:49], v[48:49], v[190:191] op_sel_hi:[1,0]
	v_pk_mul_f32 v[46:47], v[46:47], v[190:191] op_sel_hi:[1,0]
	v_pk_mul_f32 v[44:45], v[44:45], v[190:191] op_sel_hi:[1,0]
	v_pk_mul_f32 v[42:43], v[42:43], v[190:191] op_sel_hi:[1,0]
	v_pk_mul_f32 v[40:41], v[40:41], v[190:191] op_sel_hi:[1,0]
	v_pk_mul_f32 v[38:39], v[38:39], v[190:191] op_sel_hi:[1,0]
	v_pk_mul_f32 v[36:37], v[36:37], v[190:191] op_sel_hi:[1,0]
	v_pk_mul_f32 v[34:35], v[34:35], v[190:191] op_sel_hi:[1,0]
	v_pk_mul_f32 v[32:33], v[32:33], v[190:191] op_sel_hi:[1,0]
	v_pk_mul_f32 v[30:31], v[30:31], v[190:191] op_sel_hi:[1,0]
	v_pk_mul_f32 v[28:29], v[28:29], v[190:191] op_sel_hi:[1,0]
	v_pk_mul_f32 v[26:27], v[26:27], v[190:191] op_sel_hi:[1,0]
	v_pk_mul_f32 v[24:25], v[24:25], v[190:191] op_sel_hi:[1,0]
	v_pk_mul_f32 v[22:23], v[22:23], v[190:191] op_sel_hi:[1,0]
	v_pk_mul_f32 v[20:21], v[20:21], v[190:191] op_sel_hi:[1,0]
	v_pk_mul_f32 v[18:19], v[18:19], v[190:191] op_sel_hi:[1,0]
	v_pk_mul_f32 v[16:17], v[16:17], v[190:191] op_sel_hi:[1,0]
	v_pk_mul_f32 v[14:15], v[14:15], v[190:191] op_sel_hi:[1,0]
	v_pk_mul_f32 v[12:13], v[12:13], v[190:191] op_sel_hi:[1,0]
	v_pk_mul_f32 v[10:11], v[10:11], v[190:191] op_sel_hi:[1,0]
	v_pk_mul_f32 v[8:9], v[8:9], v[190:191] op_sel_hi:[1,0]
	v_pk_mul_f32 v[6:7], v[6:7], v[190:191] op_sel_hi:[1,0]
	v_pk_mul_f32 v[4:5], v[4:5], v[190:191] op_sel_hi:[1,0]
	v_pk_mul_f32 v[2:3], v[2:3], v[190:191] op_sel_hi:[1,0]
	v_pk_mul_f32 v[0:1], v[0:1], v[190:191] op_sel_hi:[1,0]
	v_mul_f32_e32 v202, v202, v190
	v_mov_b32_e32 v190, v246
.Latt_nr0_0:
	s_waitcnt lgkmcnt(5)
	v_mfma_f32_32x32x16_bf16 v[222:237], v[214:217], v[152:155], v[222:237]
	ds_read_b64_tr_b16 v[214:215], v205
	ds_read_b64_tr_b16 v[216:217], v205 offset:4096
	v_sub_f32_e32 v128, v128, v190
	v_exp_f32_e32 v128, v128
	v_sub_f32_e32 v129, v129, v190
	v_exp_f32_e32 v129, v129
	v_sub_f32_e32 v130, v130, v190
	v_add_f32_e32 v254, 0, v128
	v_exp_f32_e32 v130, v130
	v_sub_f32_e32 v131, v131, v190
	s_waitcnt lgkmcnt(6)
	v_mfma_f32_32x32x16_bf16 v[222:237], v[238:241], v[156:159], v[222:237]
	ds_read_b64_tr_b16 v[238:239], v218
	ds_read_b64_tr_b16 v[240:241], v218 offset:4096
	v_add_f32_e32 v254, v129, v254
	v_exp_f32_e32 v131, v131
	v_sub_f32_e32 v132, v132, v190
	v_add_f32_e32 v254, v130, v254
	v_exp_f32_e32 v132, v132
	v_sub_f32_e32 v133, v133, v190
	v_add_f32_e32 v254, v131, v254
	v_exp_f32_e32 v133, v133
	s_waitcnt lgkmcnt(7)
	v_mfma_f32_32x32x16_bf16 v[222:237], v[242:245], v[160:163], v[222:237]
	v_sub_f32_e32 v134, v134, v190
	v_add_f32_e32 v254, v132, v254
	v_exp_f32_e32 v134, v134
	v_sub_f32_e32 v135, v135, v190
	v_add_f32_e32 v254, v133, v254
	v_exp_f32_e32 v135, v135
	v_sub_f32_e32 v136, v136, v190
	v_add_f32_e32 v254, v134, v254
	s_waitcnt lgkmcnt(6)
	v_mfma_f32_32x32x16_bf16 v[222:237], v[250:253], v[164:167], v[222:237]
	v_exp_f32_e32 v136, v136
	v_sub_f32_e32 v137, v137, v190
	v_add_f32_e32 v254, v135, v254
	v_exp_f32_e32 v137, v137
	v_sub_f32_e32 v138, v138, v190
	v_add_f32_e32 v254, v136, v254
	v_exp_f32_e32 v138, v138
	v_sub_f32_e32 v139, v139, v190
	s_waitcnt lgkmcnt(5)
	v_mfma_f32_32x32x16_bf16 v[222:237], v[206:209], v[168:171], v[222:237]
	ds_read_b64_tr_b16 v[206:207], v219
	ds_read_b64_tr_b16 v[208:209], v219 offset:4096
	v_add_f32_e32 v254, v137, v254
	v_exp_f32_e32 v139, v139
	v_sub_f32_e32 v140, v140, v190
	v_add_f32_e32 v254, v138, v254
	v_exp_f32_e32 v140, v140
	v_sub_f32_e32 v141, v141, v190
	v_add_f32_e32 v254, v139, v254
	v_exp_f32_e32 v141, v141
	s_waitcnt lgkmcnt(6)
	v_mfma_f32_32x32x16_bf16 v[222:237], v[210:213], v[172:175], v[222:237]
	ds_read_b64_tr_b16 v[210:211], v221
	ds_read_b64_tr_b16 v[212:213], v221 offset:4096
	v_sub_f32_e32 v142, v142, v190
	v_add_f32_e32 v254, v140, v254
	v_exp_f32_e32 v142, v142
	v_sub_f32_e32 v143, v143, v190
	v_add_f32_e32 v254, v141, v254
	v_exp_f32_e32 v143, v143
	v_add_f32_e32 v254, v142, v254
	v_add_f32_e32 v254, v143, v254
	v_cvt_pk_bf16_f32 v242, v128, v129
	v_cvt_pk_bf16_f32 v243, v130, v131
	v_cvt_pk_bf16_f32 v244, v132, v133
	v_cvt_pk_bf16_f32 v245, v134, v135
	v_cvt_pk_bf16_f32 v250, v136, v137
	v_cvt_pk_bf16_f32 v251, v138, v139
	v_cvt_pk_bf16_f32 v252, v140, v141
	v_cvt_pk_bf16_f32 v253, v142, v143
	v_add_f32_e32 v202, v202, v254
	s_nop 1
	ds_read_b64_tr_b16 v[128:129], v205 offset:256
	ds_read_b64_tr_b16 v[130:131], v205 offset:4352
	s_waitcnt lgkmcnt(8)
	v_mfma_f32_32x32x16_bf16 v[112:127], v[214:217], v[242:245], v[112:127]
	ds_read_b64_tr_b16 v[214:215], v218 offset:256
	ds_read_b64_tr_b16 v[216:217], v218 offset:4352
	s_waitcnt lgkmcnt(8)
	v_mfma_f32_32x32x16_bf16 v[96:111], v[238:241], v[242:245], v[96:111]
	ds_read_b64_tr_b16 v[238:239], v219 offset:256
	ds_read_b64_tr_b16 v[240:241], v219 offset:4352
	s_waitcnt lgkmcnt(8)
	v_mfma_f32_32x32x16_bf16 v[80:95], v[206:209], v[242:245], v[80:95]
	ds_read_b64_tr_b16 v[206:207], v221 offset:256
	ds_read_b64_tr_b16 v[208:209], v221 offset:4352
	v_max3_f32 v246, v222, v223, v224
	v_max3_f32 v247, v225, v226, v227
	v_max3_f32 v246, v246, v228, v229
	v_max3_f32 v247, v247, v230, v231
	v_max3_f32 v246, v246, v232, v233
	v_max3_f32 v247, v247, v234, v235
	s_waitcnt lgkmcnt(8)
	v_mfma_f32_32x32x16_bf16 v[64:79], v[210:213], v[242:245], v[64:79]
	ds_read_b64_tr_b16 v[210:211], v205 offset:8192
	ds_read_b64_tr_b16 v[212:213], v205 offset:12288
	v_max3_f32 v246, v246, v236, v237
	v_max_f32_e32 v246, v246, v247
	v_mov_b32_e32 v247, v246
	v_add_f32_e32 v249, 0x41000000, v190
	s_nop 1
	s_waitcnt lgkmcnt(8)
	v_mfma_f32_32x32x16_bf16 v[48:63], v[128:131], v[242:245], v[48:63]
	ds_read_b64_tr_b16 v[128:129], v218 offset:8192
	ds_read_b64_tr_b16 v[130:131], v218 offset:12288
	v_permlane32_swap_b32_e32 v246, v247
	v_max_f32_e32 v246, v246, v247
	v_cmp_gt_f32_e32 vcc, v246, v249
	s_cbranch_vccnz .Latt_rs1_0
	s_waitcnt lgkmcnt(8)
	v_mfma_f32_32x32x16_bf16 v[32:47], v[214:217], v[242:245], v[32:47]
	ds_read_b64_tr_b16 v[214:215], v219 offset:8192
	ds_read_b64_tr_b16 v[216:217], v219 offset:12288
	v_sub_f32_e32 v222, v222, v190
	v_exp_f32_e32 v222, v222
	v_sub_f32_e32 v223, v223, v190
	v_exp_f32_e32 v223, v223
	v_sub_f32_e32 v224, v224, v190
	s_waitcnt lgkmcnt(8)
	v_mfma_f32_32x32x16_bf16 v[16:31], v[238:241], v[242:245], v[16:31]
	ds_read_b64_tr_b16 v[238:239], v221 offset:8192
	ds_read_b64_tr_b16 v[240:241], v221 offset:12288
	v_add_f32_e32 v254, 0, v222
	v_exp_f32_e32 v224, v224
	v_sub_f32_e32 v225, v225, v190
	v_add_f32_e32 v254, v223, v254
	v_exp_f32_e32 v225, v225
	s_waitcnt lgkmcnt(8)
	v_mfma_f32_32x32x16_bf16 v[0:15], v[206:209], v[242:245], v[0:15]
	ds_read_b64_tr_b16 v[206:207], v205 offset:8448
	ds_read_b64_tr_b16 v[208:209], v205 offset:12544
	v_sub_f32_e32 v226, v226, v190
	v_add_f32_e32 v254, v224, v254
	v_exp_f32_e32 v226, v226
	v_sub_f32_e32 v227, v227, v190
	v_add_f32_e32 v254, v225, v254
	s_waitcnt lgkmcnt(8)
	v_mfma_f32_32x32x16_bf16 v[112:127], v[210:213], v[250:253], v[112:127]
	ds_read_b64_tr_b16 v[210:211], v218 offset:8448
	ds_read_b64_tr_b16 v[212:213], v218 offset:12544
	v_exp_f32_e32 v227, v227
	v_sub_f32_e32 v228, v228, v190
	v_add_f32_e32 v254, v226, v254
	v_exp_f32_e32 v228, v228
	v_sub_f32_e32 v229, v229, v190
	s_waitcnt lgkmcnt(8)
	v_mfma_f32_32x32x16_bf16 v[96:111], v[128:131], v[250:253], v[96:111]
	ds_read_b64_tr_b16 v[128:129], v219 offset:8448
	ds_read_b64_tr_b16 v[130:131], v219 offset:12544
	v_add_f32_e32 v254, v227, v254
	v_exp_f32_e32 v229, v229
	v_sub_f32_e32 v230, v230, v190
	v_add_f32_e32 v254, v228, v254
	s_waitcnt lgkmcnt(8)
	v_mfma_f32_32x32x16_bf16 v[80:95], v[214:217], v[250:253], v[80:95]
	ds_read_b64_tr_b16 v[214:215], v221 offset:8448
	ds_read_b64_tr_b16 v[216:217], v221 offset:12544
	v_exp_f32_e32 v230, v230
	v_sub_f32_e32 v231, v231, v190
	v_add_f32_e32 v254, v229, v254
	v_exp_f32_e32 v231, v231
	s_waitcnt lgkmcnt(8)
	v_mfma_f32_32x32x16_bf16 v[64:79], v[238:241], v[250:253], v[64:79]
	ds_read_b64_tr_b16 v[238:239], v205 offset:16384
	ds_read_b64_tr_b16 v[240:241], v205 offset:20480
	v_sub_f32_e32 v232, v232, v190
	v_add_f32_e32 v254, v230, v254
	v_exp_f32_e32 v232, v232
	v_sub_f32_e32 v233, v233, v190
	s_waitcnt lgkmcnt(8)
	v_mfma_f32_32x32x16_bf16 v[48:63], v[206:209], v[250:253], v[48:63]
	ds_read_b64_tr_b16 v[206:207], v218 offset:16384
	ds_read_b64_tr_b16 v[208:209], v218 offset:20480
	v_add_f32_e32 v254, v231, v254
	v_exp_f32_e32 v233, v233
	v_sub_f32_e32 v234, v234, v190
	v_add_f32_e32 v254, v232, v254
	s_waitcnt lgkmcnt(8)
	v_mfma_f32_32x32x16_bf16 v[32:47], v[210:213], v[250:253], v[32:47]
	ds_read_b64_tr_b16 v[210:211], v219 offset:16384
	ds_read_b64_tr_b16 v[212:213], v219 offset:20480
	v_exp_f32_e32 v234, v234
	v_sub_f32_e32 v235, v235, v190
	v_add_f32_e32 v254, v233, v254
	v_exp_f32_e32 v235, v235
	s_waitcnt lgkmcnt(8)
	v_mfma_f32_32x32x16_bf16 v[16:31], v[128:131], v[250:253], v[16:31]
	ds_read_b64_tr_b16 v[128:129], v221 offset:16384
	ds_read_b64_tr_b16 v[130:131], v221 offset:20480
	v_sub_f32_e32 v236, v236, v190
	v_add_f32_e32 v254, v234, v254
	v_exp_f32_e32 v236, v236
	v_sub_f32_e32 v237, v237, v190
	s_waitcnt lgkmcnt(8)
	v_mfma_f32_32x32x16_bf16 v[0:15], v[214:217], v[250:253], v[0:15]
	ds_read_b64_tr_b16 v[214:215], v205 offset:16640
	ds_read_b64_tr_b16 v[216:217], v205 offset:20736
	v_add_f32_e32 v254, v235, v254
	v_exp_f32_e32 v237, v237
	v_add_f32_e32 v254, v236, v254
	v_add_f32_e32 v254, v237, v254
	v_cvt_pk_bf16_f32 v242, v222, v223
	v_cvt_pk_bf16_f32 v243, v224, v225
	v_cvt_pk_bf16_f32 v244, v226, v227
	v_cvt_pk_bf16_f32 v245, v228, v229
	v_cvt_pk_bf16_f32 v250, v230, v231
	v_cvt_pk_bf16_f32 v251, v232, v233
	v_cvt_pk_bf16_f32 v252, v234, v235
	v_cvt_pk_bf16_f32 v253, v236, v237
	v_add_f32_e32 v202, v202, v254
	s_nop 1
.Latt_pv1_0:
	s_waitcnt lgkmcnt(8)
	v_mfma_f32_32x32x16_bf16 v[112:127], v[238:241], v[242:245], v[112:127]
	ds_read_b64_tr_b16 v[238:239], v218 offset:16640
	ds_read_b64_tr_b16 v[240:241], v218 offset:20736
	s_waitcnt lgkmcnt(8)
	v_mfma_f32_32x32x16_bf16 v[96:111], v[206:209], v[242:245], v[96:111]
	ds_read_b64_tr_b16 v[206:207], v219 offset:16640
	ds_read_b64_tr_b16 v[208:209], v219 offset:20736
	s_cmp_lg_u64 s[18:19], 0
	s_cbranch_scc1 .Latt_nd0_0
	s_sub_i32 s100, s88, 1
	s_cmp_eq_u32 s88, 0
	s_cselect_b32 s100, 2, s100
	s_lshl_b32 s101, s100, 14
	s_add_i32 m0, s85, s101
	s_nop 0
	global_load_lds_dwordx4 v178, s[14:15]
.Latt_nd0_0:
	s_waitcnt lgkmcnt(8)
	v_mfma_f32_32x32x16_bf16 v[80:95], v[210:213], v[242:245], v[80:95]
	ds_read_b64_tr_b16 v[210:211], v221 offset:16640
	ds_read_b64_tr_b16 v[212:213], v221 offset:20736
	s_waitcnt lgkmcnt(8)
	v_mfma_f32_32x32x16_bf16 v[64:79], v[128:131], v[242:245], v[64:79]
	ds_read_b64_tr_b16 v[222:223], v205 offset:24576
	ds_read_b64_tr_b16 v[224:225], v205 offset:28672
	s_cmp_lg_u64 s[18:19], 0
	s_cbranch_scc1 .Latt_nd1_0
	s_add_i32 m0, m0, 0x400
	s_nop 0
	global_load_lds_dwordx4 v180, s[14:15]
.Latt_nd1_0:
	s_waitcnt lgkmcnt(8)
	v_mfma_f32_32x32x16_bf16 v[48:63], v[214:217], v[242:245], v[48:63]
	ds_read_b64_tr_b16 v[214:215], v218 offset:24576
	ds_read_b64_tr_b16 v[216:217], v218 offset:28672
	s_waitcnt lgkmcnt(8)
	v_mfma_f32_32x32x16_bf16 v[32:47], v[238:241], v[242:245], v[32:47]
	ds_read_b64_tr_b16 v[238:239], v219 offset:24576
	ds_read_b64_tr_b16 v[240:241], v219 offset:28672
	s_cmp_lg_u64 s[18:19], 0
	s_cbranch_scc1 .Latt_nd2_0
	s_lshl_b32 s101, s100, 15
	s_add_i32 m0, s86, s101
	s_add_u32 s100, s14, 0x1000
	s_addc_u32 s101, s15, 0
	global_load_lds_dwordx4 v182, s[100:101]
.Latt_nd2_0:
	s_waitcnt lgkmcnt(8)
	v_mfma_f32_32x32x16_bf16 v[16:31], v[206:209], v[242:245], v[16:31]
	ds_read_b64_tr_b16 v[206:207], v221 offset:24576
	ds_read_b64_tr_b16 v[208:209], v221 offset:28672
	s_waitcnt lgkmcnt(8)
	v_mfma_f32_32x32x16_bf16 v[0:15], v[210:213], v[242:245], v[0:15]
	ds_read_b64_tr_b16 v[210:211], v205 offset:24832
	ds_read_b64_tr_b16 v[212:213], v205 offset:28928
	s_cmp_lg_u64 s[18:19], 0
	s_cbranch_scc1 .Latt_nd3_0
	s_add_i32 m0, m0, 0x400
	s_nop 0
	global_load_lds_dwordx4 v184, s[100:101]
.Latt_nd3_0:
	s_waitcnt lgkmcnt(8)
	v_mfma_f32_32x32x16_bf16 v[112:127], v[222:225], v[250:253], v[112:127]
	ds_read_b64_tr_b16 v[222:223], v218 offset:24832
	ds_read_b64_tr_b16 v[224:225], v218 offset:28928
	s_waitcnt lgkmcnt(8)
	v_mfma_f32_32x32x16_bf16 v[96:111], v[214:217], v[250:253], v[96:111]
	ds_read_b64_tr_b16 v[214:215], v219 offset:24832
	ds_read_b64_tr_b16 v[216:217], v219 offset:28928
	s_cmp_lg_u64 s[18:19], 0
	s_cbranch_scc1 .Latt_nd4_0
	s_add_i32 m0, m0, 0x400
	s_nop 0
	global_load_lds_dwordx4 v186, s[100:101]
.Latt_nd4_0:
	s_waitcnt lgkmcnt(8)
	v_mfma_f32_32x32x16_bf16 v[80:95], v[238:241], v[250:253], v[80:95]
	ds_read_b64_tr_b16 v[238:239], v221 offset:24832
	ds_read_b64_tr_b16 v[240:241], v221 offset:28928
	s_waitcnt lgkmcnt(8)
	v_mfma_f32_32x32x16_bf16 v[64:79], v[206:209], v[250:253], v[64:79]
	s_cmp_lg_u64 s[18:19], 0
	s_cbranch_scc1 .Latt_nd5_0
	s_add_i32 m0, m0, 0x400
	s_nop 0
	global_load_lds_dwordx4 v188, s[100:101]
.Latt_nd5_0:
	s_waitcnt lgkmcnt(6)
	v_mfma_f32_32x32x16_bf16 v[48:63], v[210:213], v[250:253], v[48:63]
	s_waitcnt lgkmcnt(4)
	v_mfma_f32_32x32x16_bf16 v[32:47], v[222:225], v[250:253], v[32:47]
	s_waitcnt lgkmcnt(2)
	v_mfma_f32_32x32x16_bf16 v[16:31], v[214:217], v[250:253], v[16:31]
	s_waitcnt lgkmcnt(0)
	v_mfma_f32_32x32x16_bf16 v[0:15], v[238:241], v[250:253], v[0:15]
	s_branch .LBB0_858
.Latt_rs1_0:
	s_waitcnt lgkmcnt(8)
	v_mfma_f32_32x32x16_bf16 v[32:47], v[214:217], v[242:245], v[32:47]
	ds_read_b64_tr_b16 v[214:215], v219 offset:8192
	ds_read_b64_tr_b16 v[216:217], v219 offset:12288
	s_waitcnt lgkmcnt(8)
	v_mfma_f32_32x32x16_bf16 v[16:31], v[238:241], v[242:245], v[16:31]
	ds_read_b64_tr_b16 v[238:239], v221 offset:8192
	ds_read_b64_tr_b16 v[240:241], v221 offset:12288
	s_waitcnt lgkmcnt(8)
	v_mfma_f32_32x32x16_bf16 v[0:15], v[206:209], v[242:245], v[0:15]
	ds_read_b64_tr_b16 v[206:207], v205 offset:8448
	ds_read_b64_tr_b16 v[208:209], v205 offset:12544
	s_waitcnt lgkmcnt(8)
	v_mfma_f32_32x32x16_bf16 v[112:127], v[210:213], v[250:253], v[112:127]
	ds_read_b64_tr_b16 v[210:211], v218 offset:8448
	ds_read_b64_tr_b16 v[212:213], v218 offset:12544
	s_waitcnt lgkmcnt(8)
	v_mfma_f32_32x32x16_bf16 v[96:111], v[128:131], v[250:253], v[96:111]
	ds_read_b64_tr_b16 v[128:129], v219 offset:8448
	ds_read_b64_tr_b16 v[130:131], v219 offset:12544
	s_waitcnt lgkmcnt(8)
	v_mfma_f32_32x32x16_bf16 v[80:95], v[214:217], v[250:253], v[80:95]
	ds_read_b64_tr_b16 v[214:215], v221 offset:8448
	ds_read_b64_tr_b16 v[216:217], v221 offset:12544
	s_waitcnt lgkmcnt(8)
	v_mfma_f32_32x32x16_bf16 v[64:79], v[238:241], v[250:253], v[64:79]
	ds_read_b64_tr_b16 v[238:239], v205 offset:16384
	ds_read_b64_tr_b16 v[240:241], v205 offset:20480
	s_waitcnt lgkmcnt(8)
	v_mfma_f32_32x32x16_bf16 v[48:63], v[206:209], v[250:253], v[48:63]
	ds_read_b64_tr_b16 v[206:207], v218 offset:16384
	ds_read_b64_tr_b16 v[208:209], v218 offset:20480
	s_waitcnt lgkmcnt(8)
	v_mfma_f32_32x32x16_bf16 v[32:47], v[210:213], v[250:253], v[32:47]
	ds_read_b64_tr_b16 v[210:211], v219 offset:16384
	ds_read_b64_tr_b16 v[212:213], v219 offset:20480
	s_waitcnt lgkmcnt(8)
	v_mfma_f32_32x32x16_bf16 v[16:31], v[128:131], v[250:253], v[16:31]
	ds_read_b64_tr_b16 v[128:129], v221 offset:16384
	ds_read_b64_tr_b16 v[130:131], v221 offset:20480
	s_waitcnt lgkmcnt(8)
	v_mfma_f32_32x32x16_bf16 v[0:15], v[214:217], v[250:253], v[0:15]
	ds_read_b64_tr_b16 v[214:215], v205 offset:16640
	ds_read_b64_tr_b16 v[216:217], v205 offset:20736
	s_nop 11
	v_max_f32_e32 v246, v190, v246
	v_sub_f32_e32 v190, v190, v246
	v_exp_f32_e32 v190, v190
	s_nop 0
	v_pk_mul_f32 v[126:127], v[126:127], v[190:191] op_sel_hi:[1,0]
	v_pk_mul_f32 v[124:125], v[124:125], v[190:191] op_sel_hi:[1,0]
	v_pk_mul_f32 v[122:123], v[122:123], v[190:191] op_sel_hi:[1,0]
	v_pk_mul_f32 v[120:121], v[120:121], v[190:191] op_sel_hi:[1,0]
	v_pk_mul_f32 v[118:119], v[118:119], v[190:191] op_sel_hi:[1,0]
	v_pk_mul_f32 v[116:117], v[116:117], v[190:191] op_sel_hi:[1,0]
	v_pk_mul_f32 v[114:115], v[114:115], v[190:191] op_sel_hi:[1,0]
	v_pk_mul_f32 v[112:113], v[112:113], v[190:191] op_sel_hi:[1,0]
	v_pk_mul_f32 v[110:111], v[110:111], v[190:191] op_sel_hi:[1,0]
	v_pk_mul_f32 v[108:109], v[108:109], v[190:191] op_sel_hi:[1,0]
	v_pk_mul_f32 v[106:107], v[106:107], v[190:191] op_sel_hi:[1,0]
	v_pk_mul_f32 v[104:105], v[104:105], v[190:191] op_sel_hi:[1,0]
	v_pk_mul_f32 v[102:103], v[102:103], v[190:191] op_sel_hi:[1,0]
	v_pk_mul_f32 v[100:101], v[100:101], v[190:191] op_sel_hi:[1,0]
	v_pk_mul_f32 v[98:99], v[98:99], v[190:191] op_sel_hi:[1,0]
	v_pk_mul_f32 v[96:97], v[96:97], v[190:191] op_sel_hi:[1,0]
	v_pk_mul_f32 v[94:95], v[94:95], v[190:191] op_sel_hi:[1,0]
	v_pk_mul_f32 v[92:93], v[92:93], v[190:191] op_sel_hi:[1,0]
	v_pk_mul_f32 v[90:91], v[90:91], v[190:191] op_sel_hi:[1,0]
	v_pk_mul_f32 v[88:89], v[88:89], v[190:191] op_sel_hi:[1,0]
	v_pk_mul_f32 v[86:87], v[86:87], v[190:191] op_sel_hi:[1,0]
	v_pk_mul_f32 v[84:85], v[84:85], v[190:191] op_sel_hi:[1,0]
	v_pk_mul_f32 v[82:83], v[82:83], v[190:191] op_sel_hi:[1,0]
	v_pk_mul_f32 v[80:81], v[80:81], v[190:191] op_sel_hi:[1,0]
	v_pk_mul_f32 v[78:79], v[78:79], v[190:191] op_sel_hi:[1,0]
	v_pk_mul_f32 v[76:77], v[76:77], v[190:191] op_sel_hi:[1,0]
	v_pk_mul_f32 v[74:75], v[74:75], v[190:191] op_sel_hi:[1,0]
	v_pk_mul_f32 v[72:73], v[72:73], v[190:191] op_sel_hi:[1,0]
	v_pk_mul_f32 v[70:71], v[70:71], v[190:191] op_sel_hi:[1,0]
	v_pk_mul_f32 v[68:69], v[68:69], v[190:191] op_sel_hi:[1,0]
	v_pk_mul_f32 v[66:67], v[66:67], v[190:191] op_sel_hi:[1,0]
	v_pk_mul_f32 v[64:65], v[64:65], v[190:191] op_sel_hi:[1,0]
	v_pk_mul_f32 v[62:63], v[62:63], v[190:191] op_sel_hi:[1,0]
	v_pk_mul_f32 v[60:61], v[60:61], v[190:191] op_sel_hi:[1,0]
	v_pk_mul_f32 v[58:59], v[58:59], v[190:191] op_sel_hi:[1,0]
	v_pk_mul_f32 v[56:57], v[56:57], v[190:191] op_sel_hi:[1,0]
	v_pk_mul_f32 v[54:55], v[54:55], v[190:191] op_sel_hi:[1,0]
	v_pk_mul_f32 v[52:53], v[52:53], v[190:191] op_sel_hi:[1,0]
	v_pk_mul_f32 v[50:51], v[50:51], v[190:191] op_sel_hi:[1,0]
	v_pk_mul_f32 v[48:49], v[48:49], v[190:191] op_sel_hi:[1,0]
	v_pk_mul_f32 v[46:47], v[46:47], v[190:191] op_sel_hi:[1,0]
	v_pk_mul_f32 v[44:45], v[44:45], v[190:191] op_sel_hi:[1,0]
	v_pk_mul_f32 v[42:43], v[42:43], v[190:191] op_sel_hi:[1,0]
	v_pk_mul_f32 v[40:41], v[40:41], v[190:191] op_sel_hi:[1,0]
	v_pk_mul_f32 v[38:39], v[38:39], v[190:191] op_sel_hi:[1,0]
	v_pk_mul_f32 v[36:37], v[36:37], v[190:191] op_sel_hi:[1,0]
	v_pk_mul_f32 v[34:35], v[34:35], v[190:191] op_sel_hi:[1,0]
	v_pk_mul_f32 v[32:33], v[32:33], v[190:191] op_sel_hi:[1,0]
	v_pk_mul_f32 v[30:31], v[30:31], v[190:191] op_sel_hi:[1,0]
	v_pk_mul_f32 v[28:29], v[28:29], v[190:191] op_sel_hi:[1,0]
	v_pk_mul_f32 v[26:27], v[26:27], v[190:191] op_sel_hi:[1,0]
	v_pk_mul_f32 v[24:25], v[24:25], v[190:191] op_sel_hi:[1,0]
	v_pk_mul_f32 v[22:23], v[22:23], v[190:191] op_sel_hi:[1,0]
	v_pk_mul_f32 v[20:21], v[20:21], v[190:191] op_sel_hi:[1,0]
	v_pk_mul_f32 v[18:19], v[18:19], v[190:191] op_sel_hi:[1,0]
	v_pk_mul_f32 v[16:17], v[16:17], v[190:191] op_sel_hi:[1,0]
	v_pk_mul_f32 v[14:15], v[14:15], v[190:191] op_sel_hi:[1,0]
	v_pk_mul_f32 v[12:13], v[12:13], v[190:191] op_sel_hi:[1,0]
	v_pk_mul_f32 v[10:11], v[10:11], v[190:191] op_sel_hi:[1,0]
	v_pk_mul_f32 v[8:9], v[8:9], v[190:191] op_sel_hi:[1,0]
	v_pk_mul_f32 v[6:7], v[6:7], v[190:191] op_sel_hi:[1,0]
	v_pk_mul_f32 v[4:5], v[4:5], v[190:191] op_sel_hi:[1,0]
	v_pk_mul_f32 v[2:3], v[2:3], v[190:191] op_sel_hi:[1,0]
	v_pk_mul_f32 v[0:1], v[0:1], v[190:191] op_sel_hi:[1,0]
	v_mul_f32_e32 v202, v202, v190
	v_mov_b32_e32 v190, v246
	v_sub_f32_e32 v222, v222, v190
	v_exp_f32_e32 v222, v222
	v_sub_f32_e32 v223, v223, v190
	v_exp_f32_e32 v223, v223
	v_sub_f32_e32 v224, v224, v190
	v_add_f32_e32 v254, 0, v222
	v_exp_f32_e32 v224, v224
	v_sub_f32_e32 v225, v225, v190
	v_add_f32_e32 v254, v223, v254
	v_exp_f32_e32 v225, v225
	v_sub_f32_e32 v226, v226, v190
	v_add_f32_e32 v254, v224, v254
	v_exp_f32_e32 v226, v226
	v_sub_f32_e32 v227, v227, v190
	v_add_f32_e32 v254, v225, v254
	v_exp_f32_e32 v227, v227
	v_sub_f32_e32 v228, v228, v190
	v_add_f32_e32 v254, v226, v254
	v_exp_f32_e32 v228, v228
	v_sub_f32_e32 v229, v229, v190
	v_add_f32_e32 v254, v227, v254
	v_exp_f32_e32 v229, v229
	v_sub_f32_e32 v230, v230, v190
	v_add_f32_e32 v254, v228, v254
	v_exp_f32_e32 v230, v230
	v_sub_f32_e32 v231, v231, v190
	v_add_f32_e32 v254, v229, v254
	v_exp_f32_e32 v231, v231
	v_sub_f32_e32 v232, v232, v190
	v_add_f32_e32 v254, v230, v254
	v_exp_f32_e32 v232, v232
	v_sub_f32_e32 v233, v233, v190
	v_add_f32_e32 v254, v231, v254
	v_exp_f32_e32 v233, v233
	v_sub_f32_e32 v234, v234, v190
	v_add_f32_e32 v254, v232, v254
	v_exp_f32_e32 v234, v234
	v_sub_f32_e32 v235, v235, v190
	v_add_f32_e32 v254, v233, v254
	v_exp_f32_e32 v235, v235
	v_sub_f32_e32 v236, v236, v190
	v_add_f32_e32 v254, v234, v254
	v_exp_f32_e32 v236, v236
	v_sub_f32_e32 v237, v237, v190
	v_add_f32_e32 v254, v235, v254
	v_exp_f32_e32 v237, v237
	v_add_f32_e32 v254, v236, v254
	v_add_f32_e32 v254, v237, v254
	v_cvt_pk_bf16_f32 v242, v222, v223
	v_cvt_pk_bf16_f32 v243, v224, v225
	v_cvt_pk_bf16_f32 v244, v226, v227
	v_cvt_pk_bf16_f32 v245, v228, v229
	v_cvt_pk_bf16_f32 v250, v230, v231
	v_cvt_pk_bf16_f32 v251, v232, v233
	v_cvt_pk_bf16_f32 v252, v234, v235
	v_cvt_pk_bf16_f32 v253, v236, v237
	v_add_f32_e32 v202, v202, v254
	s_nop 1
	s_branch .Latt_pv1_0

.LBB0_866:
	s_cmp_gt_i32 s4, s84
	s_cbranch_scc1 .LBB0_877
	s_add_i32 s100, s4, 63
	s_cmp_le_i32 s100, s83
	s_cbranch_scc0 .Latt_slow_1
	s_lshl_b32 s98, s33, 14
	s_lshl_b32 s99, s33, 15
	s_add_i32 s99, s99, 0xc000
	v_add_u32_e32 v206, s98, v196
	ds_read_b128 v[206:209], v206
	v_add_u32_e32 v210, s98, v197
	ds_read_b128 v[210:213], v210
	v_add_u32_e32 v214, s98, v198
	ds_read_b128 v[214:217], v214
	v_add_u32_e32 v238, s98, v199
	ds_read_b128 v[238:241], v238
	v_add_u32_e32 v242, s98, v200
	ds_read_b128 v[242:245], v242
	v_add_u32_e32 v250, s98, v201
	ds_read_b128 v[250:253], v250
	v_add_u32_e32 v222, s98, v202
	ds_read_b128 v[222:225], v222
	v_add_u32_e32 v226, s98, v203
	ds_read_b128 v[226:229], v226
	v_bfe_u32 v246, v204, 2, 2
	v_bfe_u32 v247, v204, 5, 1
	v_lshl_or_b32 v247, v247, 2, v246
	v_and_b32_e32 v249, 3, v204
	v_and_b32_e32 v254, 16, v204
	v_lshl_or_b32 v249, v249, 2, v254
	v_lshlrev_b32_e32 v249, 1, v249
	v_lshl_add_u32 v247, v247, 9, v249
	v_add_u32_e32 v247, s99, v247
	v_lshlrev_b32_e32 v246, 6, v246
	v_add_u32_e32 v205, v247, v246
	v_xor_b32_e32 v249, 64, v246
	v_add_u32_e32 v218, v247, v249
	v_xor_b32_e32 v249, 0x80, v246
	v_add_u32_e32 v219, v247, v249
	v_xor_b32_e32 v249, 0xc0, v246
	v_add_u32_e32 v221, v247, v249
	s_waitcnt lgkmcnt(7)
	v_mfma_f32_32x32x16_bf16 v[128:143], v[206:209], v[144:147], 0
	v_add_u32_e32 v206, s98, v196
	ds_read_b128 v[206:209], v206 offset:8192
	s_waitcnt lgkmcnt(7)
	v_mfma_f32_32x32x16_bf16 v[128:143], v[210:213], v[148:151], v[128:143]
	v_add_u32_e32 v210, s98, v197
	ds_read_b128 v[210:213], v210 offset:8192
	s_waitcnt lgkmcnt(7)
	v_mfma_f32_32x32x16_bf16 v[128:143], v[214:217], v[152:155], v[128:143]
	v_add_u32_e32 v214, s98, v198
	ds_read_b128 v[214:217], v214 offset:8192
	s_waitcnt lgkmcnt(7)
	v_mfma_f32_32x32x16_bf16 v[128:143], v[238:241], v[156:159], v[128:143]
	v_add_u32_e32 v238, s98, v199
	ds_read_b128 v[238:241], v238 offset:8192
	s_waitcnt lgkmcnt(7)
	v_mfma_f32_32x32x16_bf16 v[128:143], v[242:245], v[160:163], v[128:143]
	v_add_u32_e32 v242, s98, v200
	ds_read_b128 v[242:245], v242 offset:8192
	s_waitcnt lgkmcnt(7)
	v_mfma_f32_32x32x16_bf16 v[128:143], v[250:253], v[164:167], v[128:143]
	v_add_u32_e32 v250, s98, v201
	ds_read_b128 v[250:253], v250 offset:8192
	s_waitcnt lgkmcnt(7)
	v_mfma_f32_32x32x16_bf16 v[128:143], v[222:225], v[168:171], v[128:143]
	s_waitcnt lgkmcnt(6)
	v_mfma_f32_32x32x16_bf16 v[128:143], v[226:229], v[172:175], v[128:143]
	s_waitcnt lgkmcnt(5)
	v_mfma_f32_32x32x16_bf16 v[222:237], v[206:209], v[144:147], 0
	v_add_u32_e32 v206, s98, v202
	ds_read_b128 v[206:209], v206 offset:8192
	s_nop 7
	v_max3_f32 v246, v128, v129, v130
	v_max3_f32 v247, v131, v132, v133
	v_max3_f32 v246, v246, v134, v135
	v_max3_f32 v247, v247, v136, v137
	v_max3_f32 v246, v246, v138, v139
	v_max3_f32 v247, v247, v140, v141
	v_max3_f32 v246, v246, v142, v143
	s_waitcnt lgkmcnt(5)
	v_mfma_f32_32x32x16_bf16 v[222:237], v[210:213], v[148:151], v[222:237]
	v_add_u32_e32 v210, s98, v203
	ds_read_b128 v[210:213], v210 offset:8192
	v_max_f32_e32 v246, v246, v247
	v_mov_b32_e32 v247, v246
	v_add_f32_e32 v249, 0x41000000, v190
	s_nop 1
	v_permlane32_swap_b32_e32 v246, v247
	v_max_f32_e32 v246, v246, v247
	v_cmp_gt_f32_e32 vcc, v246, v249
	s_cbranch_vccz .Latt_nr0_1
	v_max_f32_e32 v246, v190, v246
	v_sub_f32_e32 v190, v190, v246
	v_exp_f32_e32 v190, v190
	s_nop 0
	v_pk_mul_f32 v[126:127], v[126:127], v[190:191] op_sel_hi:[1,0]
	v_pk_mul_f32 v[124:125], v[124:125], v[190:191] op_sel_hi:[1,0]
	v_pk_mul_f32 v[122:123], v[122:123], v[190:191] op_sel_hi:[1,0]
	v_pk_mul_f32 v[120:121], v[120:121], v[190:191] op_sel_hi:[1,0]
	v_pk_mul_f32 v[118:119], v[118:119], v[190:191] op_sel_hi:[1,0]
	v_pk_mul_f32 v[116:117], v[116:117], v[190:191] op_sel_hi:[1,0]
	v_pk_mul_f32 v[114:115], v[114:115], v[190:191] op_sel_hi:[1,0]
	v_pk_mul_f32 v[112:113], v[112:113], v[190:191] op_sel_hi:[1,0]
	v_pk_mul_f32 v[110:111], v[110:111], v[190:191] op_sel_hi:[1,0]
	v_pk_mul_f32 v[108:109], v[108:109], v[190:191] op_sel_hi:[1,0]
	v_pk_mul_f32 v[106:107], v[106:107], v[190:191] op_sel_hi:[1,0]
	v_pk_mul_f32 v[104:105], v[104:105], v[190:191] op_sel_hi:[1,0]
	v_pk_mul_f32 v[102:103], v[102:103], v[190:191] op_sel_hi:[1,0]
	v_pk_mul_f32 v[100:101], v[100:101], v[190:191] op_sel_hi:[1,0]
	v_pk_mul_f32 v[98:99], v[98:99], v[190:191] op_sel_hi:[1,0]
	v_pk_mul_f32 v[96:97], v[96:97], v[190:191] op_sel_hi:[1,0]
	v_pk_mul_f32 v[94:95], v[94:95], v[190:191] op_sel_hi:[1,0]
	v_pk_mul_f32 v[92:93], v[92:93], v[190:191] op_sel_hi:[1,0]
	v_pk_mul_f32 v[90:91], v[90:91], v[190:191] op_sel_hi:[1,0]
	v_pk_mul_f32 v[88:89], v[88:89], v[190:191] op_sel_hi:[1,0]
	v_pk_mul_f32 v[86:87], v[86:87], v[190:191] op_sel_hi:[1,0]
	v_pk_mul_f32 v[84:85], v[84:85], v[190:191] op_sel_hi:[1,0]
	v_pk_mul_f32 v[82:83], v[82:83], v[190:191] op_sel_hi:[1,0]
	v_pk_mul_f32 v[80:81], v[80:81], v[190:191] op_sel_hi:[1,0]
	v_pk_mul_f32 v[78:79], v[78:79], v[190:191] op_sel_hi:[1,0]
	v_pk_mul_f32 v[76:77], v[76:77], v[190:191] op_sel_hi:[1,0]
	v_pk_mul_f32 v[74:75], v[74:75], v[190:191] op_sel_hi:[1,0]
	v_pk_mul_f32 v[72:73], v[72:73], v[190:191] op_sel_hi:[1,0]
	v_pk_mul_f32 v[70:71], v[70:71], v[190:191] op_sel_hi:[1,0]
	v_pk_mul_f32 v[68:69], v[68:69], v[190:191] op_sel_hi:[1,0]
	v_pk_mul_f32 v[66:67], v[66:67], v[190:191] op_sel_hi:[1,0]
	v_pk_mul_f32 v[64:65], v[64:65], v[190:191] op_sel_hi:[1,0]
	v_pk_mul_f32 v[62:63], v[62:63], v[190:191] op_sel_hi:[1,0]
	v_pk_mul_f32 v[60:61], v[60:61], v[190:191] op_sel_hi:[1,0]
	v_pk_mul_f32 v[58:59], v[58:59], v[190:191] op_sel_hi:[1,0]
	v_pk_mul_f32 v[56:57], v[56:57], v[190:191] op_sel_hi:[1,0]
	v_pk_mul_f32 v[54:55], v[54:55], v[190:191] op_sel_hi:[1,0]
	v_pk_mul_f32 v[52:53], v[52:53], v[190:191] op_sel_hi:[1,0]
	v_pk_mul_f32 v[50:51], v[50:51], v[190:191] op_sel_hi:[1,0]
	v_pk_mul_f32 v[48:49], v[48:49], v[190:191] op_sel_hi:[1,0]
	v_pk_mul_f32 v[46:47], v[46:47], v[190:191] op_sel_hi:[1,0]
	v_pk_mul_f32 v[44:45], v[44:45], v[190:191] op_sel_hi:[1,0]
	v_pk_mul_f32 v[42:43], v[42:43], v[190:191] op_sel_hi:[1,0]
	v_pk_mul_f32 v[40:41], v[40:41], v[190:191] op_sel_hi:[1,0]
	v_pk_mul_f32 v[38:39], v[38:39], v[190:191] op_sel_hi:[1,0]
	v_pk_mul_f32 v[36:37], v[36:37], v[190:191] op_sel_hi:[1,0]
	v_pk_mul_f32 v[34:35], v[34:35], v[190:191] op_sel_hi:[1,0]
	v_pk_mul_f32 v[32:33], v[32:33], v[190:191] op_sel_hi:[1,0]
	v_pk_mul_f32 v[30:31], v[30:31], v[190:191] op_sel_hi:[1,0]
	v_pk_mul_f32 v[28:29], v[28:29], v[190:191] op_sel_hi:[1,0]
	v_pk_mul_f32 v[26:27], v[26:27], v[190:191] op_sel_hi:[1,0]
	v_pk_mul_f32 v[24:25], v[24:25], v[190:191] op_sel_hi:[1,0]
	v_pk_mul_f32 v[22:23], v[22:23], v[190:191] op_sel_hi:[1,0]
	v_pk_mul_f32 v[20:21], v[20:21], v[190:191] op_sel_hi:[1,0]
	v_pk_mul_f32 v[18:19], v[18:19], v[190:191] op_sel_hi:[1,0]
	v_pk_mul_f32 v[16:17], v[16:17], v[190:191] op_sel_hi:[1,0]
	v_pk_mul_f32 v[14:15], v[14:15], v[190:191] op_sel_hi:[1,0]
	v_pk_mul_f32 v[12:13], v[12:13], v[190:191] op_sel_hi:[1,0]
	v_pk_mul_f32 v[10:11], v[10:11], v[190:191] op_sel_hi:[1,0]
	v_pk_mul_f32 v[8:9], v[8:9], v[190:191] op_sel_hi:[1,0]
	v_pk_mul_f32 v[6:7], v[6:7], v[190:191] op_sel_hi:[1,0]
	v_pk_mul_f32 v[4:5], v[4:5], v[190:191] op_sel_hi:[1,0]
	v_pk_mul_f32 v[2:3], v[2:3], v[190:191] op_sel_hi:[1,0]
	v_pk_mul_f32 v[0:1], v[0:1], v[190:191] op_sel_hi:[1,0]
	v_mul_f32_e32 v195, v195, v190
	v_mov_b32_e32 v190, v246
.Latt_nr0_1:
	s_waitcnt lgkmcnt(5)
	v_mfma_f32_32x32x16_bf16 v[222:237], v[214:217], v[152:155], v[222:237]
	ds_read_b64_tr_b16 v[214:215], v205
	ds_read_b64_tr_b16 v[216:217], v205 offset:4096
	v_sub_f32_e32 v128, v128, v190
	v_exp_f32_e32 v128, v128
	v_sub_f32_e32 v129, v129, v190
	v_exp_f32_e32 v129, v129
	v_sub_f32_e32 v130, v130, v190
	v_add_f32_e32 v254, 0, v128
	v_exp_f32_e32 v130, v130
	v_sub_f32_e32 v131, v131, v190
	s_waitcnt lgkmcnt(6)
	v_mfma_f32_32x32x16_bf16 v[222:237], v[238:241], v[156:159], v[222:237]
	ds_read_b64_tr_b16 v[238:239], v218
	ds_read_b64_tr_b16 v[240:241], v218 offset:4096
	v_add_f32_e32 v254, v129, v254
	v_exp_f32_e32 v131, v131
	v_sub_f32_e32 v132, v132, v190
	v_add_f32_e32 v254, v130, v254
	v_exp_f32_e32 v132, v132
	v_sub_f32_e32 v133, v133, v190
	v_add_f32_e32 v254, v131, v254
	v_exp_f32_e32 v133, v133
	s_waitcnt lgkmcnt(7)
	v_mfma_f32_32x32x16_bf16 v[222:237], v[242:245], v[160:163], v[222:237]
	v_sub_f32_e32 v134, v134, v190
	v_add_f32_e32 v254, v132, v254
	v_exp_f32_e32 v134, v134
	v_sub_f32_e32 v135, v135, v190
	v_add_f32_e32 v254, v133, v254
	v_exp_f32_e32 v135, v135
	v_sub_f32_e32 v136, v136, v190
	v_add_f32_e32 v254, v134, v254
	s_waitcnt lgkmcnt(6)
	v_mfma_f32_32x32x16_bf16 v[222:237], v[250:253], v[164:167], v[222:237]
	v_exp_f32_e32 v136, v136
	v_sub_f32_e32 v137, v137, v190
	v_add_f32_e32 v254, v135, v254
	v_exp_f32_e32 v137, v137
	v_sub_f32_e32 v138, v138, v190
	v_add_f32_e32 v254, v136, v254
	v_exp_f32_e32 v138, v138
	v_sub_f32_e32 v139, v139, v190
	s_waitcnt lgkmcnt(5)
	v_mfma_f32_32x32x16_bf16 v[222:237], v[206:209], v[168:171], v[222:237]
	ds_read_b64_tr_b16 v[206:207], v219
	ds_read_b64_tr_b16 v[208:209], v219 offset:4096
	v_add_f32_e32 v254, v137, v254
	v_exp_f32_e32 v139, v139
	v_sub_f32_e32 v140, v140, v190
	v_add_f32_e32 v254, v138, v254
	v_exp_f32_e32 v140, v140
	v_sub_f32_e32 v141, v141, v190
	v_add_f32_e32 v254, v139, v254
	v_exp_f32_e32 v141, v141
	s_waitcnt lgkmcnt(6)
	v_mfma_f32_32x32x16_bf16 v[222:237], v[210:213], v[172:175], v[222:237]
	ds_read_b64_tr_b16 v[210:211], v221
	ds_read_b64_tr_b16 v[212:213], v221 offset:4096
	v_sub_f32_e32 v142, v142, v190
	v_add_f32_e32 v254, v140, v254
	v_exp_f32_e32 v142, v142
	v_sub_f32_e32 v143, v143, v190
	v_add_f32_e32 v254, v141, v254
	v_exp_f32_e32 v143, v143
	v_add_f32_e32 v254, v142, v254
	v_add_f32_e32 v254, v143, v254
	v_cvt_pk_bf16_f32 v242, v128, v129
	v_cvt_pk_bf16_f32 v243, v130, v131
	v_cvt_pk_bf16_f32 v244, v132, v133
	v_cvt_pk_bf16_f32 v245, v134, v135
	v_cvt_pk_bf16_f32 v250, v136, v137
	v_cvt_pk_bf16_f32 v251, v138, v139
	v_cvt_pk_bf16_f32 v252, v140, v141
	v_cvt_pk_bf16_f32 v253, v142, v143
	v_add_f32_e32 v195, v195, v254
	s_nop 1
	ds_read_b64_tr_b16 v[128:129], v205 offset:256
	ds_read_b64_tr_b16 v[130:131], v205 offset:4352
	s_waitcnt lgkmcnt(8)
	v_mfma_f32_32x32x16_bf16 v[112:127], v[214:217], v[242:245], v[112:127]
	ds_read_b64_tr_b16 v[214:215], v218 offset:256
	ds_read_b64_tr_b16 v[216:217], v218 offset:4352
	s_waitcnt lgkmcnt(8)
	v_mfma_f32_32x32x16_bf16 v[96:111], v[238:241], v[242:245], v[96:111]
	ds_read_b64_tr_b16 v[238:239], v219 offset:256
	ds_read_b64_tr_b16 v[240:241], v219 offset:4352
	s_waitcnt lgkmcnt(8)
	v_mfma_f32_32x32x16_bf16 v[80:95], v[206:209], v[242:245], v[80:95]
	ds_read_b64_tr_b16 v[206:207], v221 offset:256
	ds_read_b64_tr_b16 v[208:209], v221 offset:4352
	v_max3_f32 v246, v222, v223, v224
	v_max3_f32 v247, v225, v226, v227
	v_max3_f32 v246, v246, v228, v229
	v_max3_f32 v247, v247, v230, v231
	v_max3_f32 v246, v246, v232, v233
	v_max3_f32 v247, v247, v234, v235
	s_waitcnt lgkmcnt(8)
	v_mfma_f32_32x32x16_bf16 v[64:79], v[210:213], v[242:245], v[64:79]
	ds_read_b64_tr_b16 v[210:211], v205 offset:8192
	ds_read_b64_tr_b16 v[212:213], v205 offset:12288
	v_max3_f32 v246, v246, v236, v237
	v_max_f32_e32 v246, v246, v247
	v_mov_b32_e32 v247, v246
	v_add_f32_e32 v249, 0x41000000, v190
	s_nop 1
	s_waitcnt lgkmcnt(8)
	v_mfma_f32_32x32x16_bf16 v[48:63], v[128:131], v[242:245], v[48:63]
	ds_read_b64_tr_b16 v[128:129], v218 offset:8192
	ds_read_b64_tr_b16 v[130:131], v218 offset:12288
	v_permlane32_swap_b32_e32 v246, v247
	v_max_f32_e32 v246, v246, v247
	v_cmp_gt_f32_e32 vcc, v246, v249
	s_cbranch_vccnz .Latt_rs1_1
	s_waitcnt lgkmcnt(8)
	v_mfma_f32_32x32x16_bf16 v[32:47], v[214:217], v[242:245], v[32:47]
	ds_read_b64_tr_b16 v[214:215], v219 offset:8192
	ds_read_b64_tr_b16 v[216:217], v219 offset:12288
	v_sub_f32_e32 v222, v222, v190
	v_exp_f32_e32 v222, v222
	v_sub_f32_e32 v223, v223, v190
	v_exp_f32_e32 v223, v223
	v_sub_f32_e32 v224, v224, v190
	s_waitcnt lgkmcnt(8)
	v_mfma_f32_32x32x16_bf16 v[16:31], v[238:241], v[242:245], v[16:31]
	ds_read_b64_tr_b16 v[238:239], v221 offset:8192
	ds_read_b64_tr_b16 v[240:241], v221 offset:12288
	v_add_f32_e32 v254, 0, v222
	v_exp_f32_e32 v224, v224
	v_sub_f32_e32 v225, v225, v190
	v_add_f32_e32 v254, v223, v254
	v_exp_f32_e32 v225, v225
	s_waitcnt lgkmcnt(8)
	v_mfma_f32_32x32x16_bf16 v[0:15], v[206:209], v[242:245], v[0:15]
	ds_read_b64_tr_b16 v[206:207], v205 offset:8448
	ds_read_b64_tr_b16 v[208:209], v205 offset:12544
	v_sub_f32_e32 v226, v226, v190
	v_add_f32_e32 v254, v224, v254
	v_exp_f32_e32 v226, v226
	v_sub_f32_e32 v227, v227, v190
	v_add_f32_e32 v254, v225, v254
	s_waitcnt lgkmcnt(8)
	v_mfma_f32_32x32x16_bf16 v[112:127], v[210:213], v[250:253], v[112:127]
	ds_read_b64_tr_b16 v[210:211], v218 offset:8448
	ds_read_b64_tr_b16 v[212:213], v218 offset:12544
	v_exp_f32_e32 v227, v227
	v_sub_f32_e32 v228, v228, v190
	v_add_f32_e32 v254, v226, v254
	v_exp_f32_e32 v228, v228
	v_sub_f32_e32 v229, v229, v190
	s_waitcnt lgkmcnt(8)
	v_mfma_f32_32x32x16_bf16 v[96:111], v[128:131], v[250:253], v[96:111]
	ds_read_b64_tr_b16 v[128:129], v219 offset:8448
	ds_read_b64_tr_b16 v[130:131], v219 offset:12544
	v_add_f32_e32 v254, v227, v254
	v_exp_f32_e32 v229, v229
	v_sub_f32_e32 v230, v230, v190
	v_add_f32_e32 v254, v228, v254
	s_waitcnt lgkmcnt(8)
	v_mfma_f32_32x32x16_bf16 v[80:95], v[214:217], v[250:253], v[80:95]
	ds_read_b64_tr_b16 v[214:215], v221 offset:8448
	ds_read_b64_tr_b16 v[216:217], v221 offset:12544
	v_exp_f32_e32 v230, v230
	v_sub_f32_e32 v231, v231, v190
	v_add_f32_e32 v254, v229, v254
	v_exp_f32_e32 v231, v231
	s_waitcnt lgkmcnt(8)
	v_mfma_f32_32x32x16_bf16 v[64:79], v[238:241], v[250:253], v[64:79]
	ds_read_b64_tr_b16 v[238:239], v205 offset:16384
	ds_read_b64_tr_b16 v[240:241], v205 offset:20480
	v_sub_f32_e32 v232, v232, v190
	v_add_f32_e32 v254, v230, v254
	v_exp_f32_e32 v232, v232
	v_sub_f32_e32 v233, v233, v190
	s_waitcnt lgkmcnt(8)
	v_mfma_f32_32x32x16_bf16 v[48:63], v[206:209], v[250:253], v[48:63]
	ds_read_b64_tr_b16 v[206:207], v218 offset:16384
	ds_read_b64_tr_b16 v[208:209], v218 offset:20480
	v_add_f32_e32 v254, v231, v254
	v_exp_f32_e32 v233, v233
	v_sub_f32_e32 v234, v234, v190
	v_add_f32_e32 v254, v232, v254
	s_waitcnt lgkmcnt(8)
	v_mfma_f32_32x32x16_bf16 v[32:47], v[210:213], v[250:253], v[32:47]
	ds_read_b64_tr_b16 v[210:211], v219 offset:16384
	ds_read_b64_tr_b16 v[212:213], v219 offset:20480
	v_exp_f32_e32 v234, v234
	v_sub_f32_e32 v235, v235, v190
	v_add_f32_e32 v254, v233, v254
	v_exp_f32_e32 v235, v235
	s_waitcnt lgkmcnt(8)
	v_mfma_f32_32x32x16_bf16 v[16:31], v[128:131], v[250:253], v[16:31]
	ds_read_b64_tr_b16 v[128:129], v221 offset:16384
	ds_read_b64_tr_b16 v[130:131], v221 offset:20480
	v_sub_f32_e32 v236, v236, v190
	v_add_f32_e32 v254, v234, v254
	v_exp_f32_e32 v236, v236
	v_sub_f32_e32 v237, v237, v190
	s_waitcnt lgkmcnt(8)
	v_mfma_f32_32x32x16_bf16 v[0:15], v[214:217], v[250:253], v[0:15]
	ds_read_b64_tr_b16 v[214:215], v205 offset:16640
	ds_read_b64_tr_b16 v[216:217], v205 offset:20736
	v_add_f32_e32 v254, v235, v254
	v_exp_f32_e32 v237, v237
	v_add_f32_e32 v254, v236, v254
	v_add_f32_e32 v254, v237, v254
	v_cvt_pk_bf16_f32 v242, v222, v223
	v_cvt_pk_bf16_f32 v243, v224, v225
	v_cvt_pk_bf16_f32 v244, v226, v227
	v_cvt_pk_bf16_f32 v245, v228, v229
	v_cvt_pk_bf16_f32 v250, v230, v231
	v_cvt_pk_bf16_f32 v251, v232, v233
	v_cvt_pk_bf16_f32 v252, v234, v235
	v_cvt_pk_bf16_f32 v253, v236, v237
	v_add_f32_e32 v195, v195, v254
	s_nop 1
.Latt_pv1_1:
	s_waitcnt lgkmcnt(8)
	v_mfma_f32_32x32x16_bf16 v[112:127], v[238:241], v[242:245], v[112:127]
	ds_read_b64_tr_b16 v[238:239], v218 offset:16640
	ds_read_b64_tr_b16 v[240:241], v218 offset:20736
	s_waitcnt lgkmcnt(8)
	v_mfma_f32_32x32x16_bf16 v[96:111], v[206:209], v[242:245], v[96:111]
	ds_read_b64_tr_b16 v[206:207], v219 offset:16640
	ds_read_b64_tr_b16 v[208:209], v219 offset:20736
	s_cmp_lg_u64 s[18:19], 0
	s_cbranch_scc1 .Latt_nd0_1
	s_sub_i32 s100, s33, 1
	s_cmp_eq_u32 s33, 0
	s_cselect_b32 s100, 2, s100
	s_lshl_b32 s101, s100, 14
	s_add_i32 m0, s85, s101
	s_nop 0
	global_load_lds_dwordx4 v178, s[12:13]
.Latt_nd0_1:
	s_waitcnt lgkmcnt(8)
	v_mfma_f32_32x32x16_bf16 v[80:95], v[210:213], v[242:245], v[80:95]
	ds_read_b64_tr_b16 v[210:211], v221 offset:16640
	ds_read_b64_tr_b16 v[212:213], v221 offset:20736
	s_waitcnt lgkmcnt(8)
	v_mfma_f32_32x32x16_bf16 v[64:79], v[128:131], v[242:245], v[64:79]
	ds_read_b64_tr_b16 v[222:223], v205 offset:24576
	ds_read_b64_tr_b16 v[224:225], v205 offset:28672
	s_cmp_lg_u64 s[18:19], 0
	s_cbranch_scc1 .Latt_nd1_1
	s_add_i32 m0, m0, 0x400
	s_nop 0
	global_load_lds_dwordx4 v180, s[12:13]
.Latt_nd1_1:
	s_waitcnt lgkmcnt(8)
	v_mfma_f32_32x32x16_bf16 v[48:63], v[214:217], v[242:245], v[48:63]
	ds_read_b64_tr_b16 v[214:215], v218 offset:24576
	ds_read_b64_tr_b16 v[216:217], v218 offset:28672
	s_waitcnt lgkmcnt(8)
	v_mfma_f32_32x32x16_bf16 v[32:47], v[238:241], v[242:245], v[32:47]
	ds_read_b64_tr_b16 v[238:239], v219 offset:24576
	ds_read_b64_tr_b16 v[240:241], v219 offset:28672
	s_cmp_lg_u64 s[18:19], 0
	s_cbranch_scc1 .Latt_nd2_1
	s_lshl_b32 s101, s100, 15
	s_add_i32 m0, s86, s101
	s_add_u32 s100, s12, 0xf00
	s_addc_u32 s101, s13, 0
	global_load_lds_dwordx4 v182, s[100:101]

.Latt_rs1_1:
	s_waitcnt lgkmcnt(8)
	v_mfma_f32_32x32x16_bf16 v[32:47], v[214:217], v[242:245], v[32:47]
	ds_read_b64_tr_b16 v[214:215], v219 offset:8192
	ds_read_b64_tr_b16 v[216:217], v219 offset:12288
	s_waitcnt lgkmcnt(8)
	v_mfma_f32_32x32x16_bf16 v[16:31], v[238:241], v[242:245], v[16:31]
	ds_read_b64_tr_b16 v[238:239], v221 offset:8192
	ds_read_b64_tr_b16 v[240:241], v221 offset:12288
	s_waitcnt lgkmcnt(8)
	v_mfma_f32_32x32x16_bf16 v[0:15], v[206:209], v[242:245], v[0:15]
	ds_read_b64_tr_b16 v[206:207], v205 offset:8448
	ds_read_b64_tr_b16 v[208:209], v205 offset:12544
	s_waitcnt lgkmcnt(8)
	v_mfma_f32_32x32x16_bf16 v[112:127], v[210:213], v[250:253], v[112:127]
	ds_read_b64_tr_b16 v[210:211], v218 offset:8448
	ds_read_b64_tr_b16 v[212:213], v218 offset:12544
	s_waitcnt lgkmcnt(8)
	v_mfma_f32_32x32x16_bf16 v[96:111], v[128:131], v[250:253], v[96:111]
	ds_read_b64_tr_b16 v[128:129], v219 offset:8448
	ds_read_b64_tr_b16 v[130:131], v219 offset:12544
	s_waitcnt lgkmcnt(8)
	v_mfma_f32_32x32x16_bf16 v[80:95], v[214:217], v[250:253], v[80:95]
	ds_read_b64_tr_b16 v[214:215], v221 offset:8448
	ds_read_b64_tr_b16 v[216:217], v221 offset:12544
	s_waitcnt lgkmcnt(8)
	v_mfma_f32_32x32x16_bf16 v[64:79], v[238:241], v[250:253], v[64:79]
	ds_read_b64_tr_b16 v[238:239], v205 offset:16384
	ds_read_b64_tr_b16 v[240:241], v205 offset:20480
	s_waitcnt lgkmcnt(8)
	v_mfma_f32_32x32x16_bf16 v[48:63], v[206:209], v[250:253], v[48:63]
	ds_read_b64_tr_b16 v[206:207], v218 offset:16384
	ds_read_b64_tr_b16 v[208:209], v218 offset:20480
	s_waitcnt lgkmcnt(8)
	v_mfma_f32_32x32x16_bf16 v[32:47], v[210:213], v[250:253], v[32:47]
	ds_read_b64_tr_b16 v[210:211], v219 offset:16384
	ds_read_b64_tr_b16 v[212:213], v219 offset:20480
	s_waitcnt lgkmcnt(8)
	v_mfma_f32_32x32x16_bf16 v[16:31], v[128:131], v[250:253], v[16:31]
	ds_read_b64_tr_b16 v[128:129], v221 offset:16384
	ds_read_b64_tr_b16 v[130:131], v221 offset:20480
	s_waitcnt lgkmcnt(8)
	v_mfma_f32_32x32x16_bf16 v[0:15], v[214:217], v[250:253], v[0:15]
	ds_read_b64_tr_b16 v[214:215], v205 offset:16640
	ds_read_b64_tr_b16 v[216:217], v205 offset:20736
	s_nop 11
	v_max_f32_e32 v246, v190, v246
	v_sub_f32_e32 v190, v190, v246
	v_exp_f32_e32 v190, v190
	s_nop 0
	v_pk_mul_f32 v[126:127], v[126:127], v[190:191] op_sel_hi:[1,0]
	v_pk_mul_f32 v[124:125], v[124:125], v[190:191] op_sel_hi:[1,0]
	v_pk_mul_f32 v[122:123], v[122:123], v[190:191] op_sel_hi:[1,0]
	v_pk_mul_f32 v[120:121], v[120:121], v[190:191] op_sel_hi:[1,0]
	v_pk_mul_f32 v[118:119], v[118:119], v[190:191] op_sel_hi:[1,0]
	v_pk_mul_f32 v[116:117], v[116:117], v[190:191] op_sel_hi:[1,0]
	v_pk_mul_f32 v[114:115], v[114:115], v[190:191] op_sel_hi:[1,0]
	v_pk_mul_f32 v[112:113], v[112:113], v[190:191] op_sel_hi:[1,0]
	v_pk_mul_f32 v[110:111], v[110:111], v[190:191] op_sel_hi:[1,0]
	v_pk_mul_f32 v[108:109], v[108:109], v[190:191] op_sel_hi:[1,0]
	v_pk_mul_f32 v[106:107], v[106:107], v[190:191] op_sel_hi:[1,0]
	v_pk_mul_f32 v[104:105], v[104:105], v[190:191] op_sel_hi:[1,0]
	v_pk_mul_f32 v[102:103], v[102:103], v[190:191] op_sel_hi:[1,0]
	v_pk_mul_f32 v[100:101], v[100:101], v[190:191] op_sel_hi:[1,0]
	v_pk_mul_f32 v[98:99], v[98:99], v[190:191] op_sel_hi:[1,0]
	v_pk_mul_f32 v[96:97], v[96:97], v[190:191] op_sel_hi:[1,0]
	v_pk_mul_f32 v[94:95], v[94:95], v[190:191] op_sel_hi:[1,0]
	v_pk_mul_f32 v[92:93], v[92:93], v[190:191] op_sel_hi:[1,0]
	v_pk_mul_f32 v[90:91], v[90:91], v[190:191] op_sel_hi:[1,0]
	v_pk_mul_f32 v[88:89], v[88:89], v[190:191] op_sel_hi:[1,0]
	v_pk_mul_f32 v[86:87], v[86:87], v[190:191] op_sel_hi:[1,0]
	v_pk_mul_f32 v[84:85], v[84:85], v[190:191] op_sel_hi:[1,0]
	v_pk_mul_f32 v[82:83], v[82:83], v[190:191] op_sel_hi:[1,0]
	v_pk_mul_f32 v[80:81], v[80:81], v[190:191] op_sel_hi:[1,0]
	v_pk_mul_f32 v[78:79], v[78:79], v[190:191] op_sel_hi:[1,0]
	v_pk_mul_f32 v[76:77], v[76:77], v[190:191] op_sel_hi:[1,0]
	v_pk_mul_f32 v[74:75], v[74:75], v[190:191] op_sel_hi:[1,0]
	v_pk_mul_f32 v[72:73], v[72:73], v[190:191] op_sel_hi:[1,0]
	v_pk_mul_f32 v[70:71], v[70:71], v[190:191] op_sel_hi:[1,0]
	v_pk_mul_f32 v[68:69], v[68:69], v[190:191] op_sel_hi:[1,0]
	v_pk_mul_f32 v[66:67], v[66:67], v[190:191] op_sel_hi:[1,0]
	v_pk_mul_f32 v[64:65], v[64:65], v[190:191] op_sel_hi:[1,0]
	v_pk_mul_f32 v[62:63], v[62:63], v[190:191] op_sel_hi:[1,0]
	v_pk_mul_f32 v[60:61], v[60:61], v[190:191] op_sel_hi:[1,0]
	v_pk_mul_f32 v[58:59], v[58:59], v[190:191] op_sel_hi:[1,0]
	v_pk_mul_f32 v[56:57], v[56:57], v[190:191] op_sel_hi:[1,0]
	v_pk_mul_f32 v[54:55], v[54:55], v[190:191] op_sel_hi:[1,0]
	v_pk_mul_f32 v[52:53], v[52:53], v[190:191] op_sel_hi:[1,0]
	v_pk_mul_f32 v[50:51], v[50:51], v[190:191] op_sel_hi:[1,0]
	v_pk_mul_f32 v[48:49], v[48:49], v[190:191] op_sel_hi:[1,0]
	v_pk_mul_f32 v[46:47], v[46:47], v[190:191] op_sel_hi:[1,0]
	v_pk_mul_f32 v[44:45], v[44:45], v[190:191] op_sel_hi:[1,0]
	v_pk_mul_f32 v[42:43], v[42:43], v[190:191] op_sel_hi:[1,0]
	v_pk_mul_f32 v[40:41], v[40:41], v[190:191] op_sel_hi:[1,0]
	v_pk_mul_f32 v[38:39], v[38:39], v[190:191] op_sel_hi:[1,0]
	v_pk_mul_f32 v[36:37], v[36:37], v[190:191] op_sel_hi:[1,0]
	v_pk_mul_f32 v[34:35], v[34:35], v[190:191] op_sel_hi:[1,0]
	v_pk_mul_f32 v[32:33], v[32:33], v[190:191] op_sel_hi:[1,0]
	v_pk_mul_f32 v[30:31], v[30:31], v[190:191] op_sel_hi:[1,0]
	v_pk_mul_f32 v[28:29], v[28:29], v[190:191] op_sel_hi:[1,0]
	v_pk_mul_f32 v[26:27], v[26:27], v[190:191] op_sel_hi:[1,0]
	v_pk_mul_f32 v[24:25], v[24:25], v[190:191] op_sel_hi:[1,0]
	v_pk_mul_f32 v[22:23], v[22:23], v[190:191] op_sel_hi:[1,0]
	v_pk_mul_f32 v[20:21], v[20:21], v[190:191] op_sel_hi:[1,0]
	v_pk_mul_f32 v[18:19], v[18:19], v[190:191] op_sel_hi:[1,0]
	v_pk_mul_f32 v[16:17], v[16:17], v[190:191] op_sel_hi:[1,0]
	v_pk_mul_f32 v[14:15], v[14:15], v[190:191] op_sel_hi:[1,0]
	v_pk_mul_f32 v[12:13], v[12:13], v[190:191] op_sel_hi:[1,0]
	v_pk_mul_f32 v[10:11], v[10:11], v[190:191] op_sel_hi:[1,0]
	v_pk_mul_f32 v[8:9], v[8:9], v[190:191] op_sel_hi:[1,0]
	v_pk_mul_f32 v[6:7], v[6:7], v[190:191] op_sel_hi:[1,0]
	v_pk_mul_f32 v[4:5], v[4:5], v[190:191] op_sel_hi:[1,0]
	v_pk_mul_f32 v[2:3], v[2:3], v[190:191] op_sel_hi:[1,0]
	v_pk_mul_f32 v[0:1], v[0:1], v[190:191] op_sel_hi:[1,0]
	v_mul_f32_e32 v195, v195, v190
	v_mov_b32_e32 v190, v246
	v_sub_f32_e32 v222, v222, v190
	v_exp_f32_e32 v222, v222
	v_sub_f32_e32 v223, v223, v190
	v_exp_f32_e32 v223, v223
	v_sub_f32_e32 v224, v224, v190
	v_add_f32_e32 v254, 0, v222
	v_exp_f32_e32 v224, v224
	v_sub_f32_e32 v225, v225, v190
	v_add_f32_e32 v254, v223, v254
	v_exp_f32_e32 v225, v225
	v_sub_f32_e32 v226, v226, v190
	v_add_f32_e32 v254, v224, v254
	v_exp_f32_e32 v226, v226
	v_sub_f32_e32 v227, v227, v190
	v_add_f32_e32 v254, v225, v254
	v_exp_f32_e32 v227, v227
	v_sub_f32_e32 v228, v228, v190
	v_add_f32_e32 v254, v226, v254
	v_exp_f32_e32 v228, v228
	v_sub_f32_e32 v229, v229, v190
	v_add_f32_e32 v254, v227, v254
	v_exp_f32_e32 v229, v229
	v_sub_f32_e32 v230, v230, v190
	v_add_f32_e32 v254, v228, v254
	v_exp_f32_e32 v230, v230
	v_sub_f32_e32 v231, v231, v190
	v_add_f32_e32 v254, v229, v254
	v_exp_f32_e32 v231, v231
	v_sub_f32_e32 v232, v232, v190
	v_add_f32_e32 v254, v230, v254
	v_exp_f32_e32 v232, v232
	v_sub_f32_e32 v233, v233, v190
	v_add_f32_e32 v254, v231, v254
	v_exp_f32_e32 v233, v233
	v_sub_f32_e32 v234, v234, v190
	v_add_f32_e32 v254, v232, v254
	v_exp_f32_e32 v234, v234
	v_sub_f32_e32 v235, v235, v190
	v_add_f32_e32 v254, v233, v254
	v_exp_f32_e32 v235, v235
	v_sub_f32_e32 v236, v236, v190
	v_add_f32_e32 v254, v234, v254
	v_exp_f32_e32 v236, v236
	v_sub_f32_e32 v237, v237, v190
	v_add_f32_e32 v254, v235, v254
	v_exp_f32_e32 v237, v237
	v_add_f32_e32 v254, v236, v254
	v_add_f32_e32 v254, v237, v254
	v_cvt_pk_bf16_f32 v242, v222, v223
	v_cvt_pk_bf16_f32 v243, v224, v225
	v_cvt_pk_bf16_f32 v244, v226, v227
	v_cvt_pk_bf16_f32 v245, v228, v229
	v_cvt_pk_bf16_f32 v250, v230, v231
	v_cvt_pk_bf16_f32 v251, v232, v233
	v_cvt_pk_bf16_f32 v252, v234, v235
	v_cvt_pk_bf16_f32 v253, v236, v237
	v_add_f32_e32 v195, v195, v254
	s_nop 1
	s_branch .Latt_pv1_1

.LBB0_885:
	s_cmp_gt_i32 s84, s81
	s_cbranch_scc1 .LBB0_896
	s_add_i32 s100, s84, 63
	s_cmp_le_i32 s100, s80
	s_cbranch_scc0 .Latt_slow_2
	s_lshl_b32 s98, s38, 14
	s_lshl_b32 s99, s38, 15
	s_add_i32 s99, s99, 0xc000
	v_add_u32_e32 v206, s98, v195
	ds_read_b128 v[206:209], v206
	v_add_u32_e32 v210, s98, v196
	ds_read_b128 v[210:213], v210
	v_add_u32_e32 v214, s98, v197
	ds_read_b128 v[214:217], v214
	v_add_u32_e32 v238, s98, v198
	ds_read_b128 v[238:241], v238
	v_add_u32_e32 v242, s98, v199
	ds_read_b128 v[242:245], v242
	v_add_u32_e32 v250, s98, v200
	ds_read_b128 v[250:253], v250
	v_add_u32_e32 v222, s98, v201
	ds_read_b128 v[222:225], v222
	v_add_u32_e32 v226, s98, v202
	ds_read_b128 v[226:229], v226
	v_bfe_u32 v246, v204, 2, 2
	v_bfe_u32 v247, v204, 5, 1
	v_lshl_or_b32 v247, v247, 2, v246
	v_and_b32_e32 v249, 3, v204
	v_and_b32_e32 v254, 16, v204
	v_lshl_or_b32 v249, v249, 2, v254
	v_lshlrev_b32_e32 v249, 1, v249
	v_lshl_add_u32 v247, v247, 9, v249
	v_add_u32_e32 v247, s99, v247
	v_lshlrev_b32_e32 v246, 6, v246
	v_add_u32_e32 v205, v247, v246
	v_xor_b32_e32 v249, 64, v246
	v_add_u32_e32 v218, v247, v249
	v_xor_b32_e32 v249, 0x80, v246
	v_add_u32_e32 v219, v247, v249
	v_xor_b32_e32 v249, 0xc0, v246
	v_add_u32_e32 v221, v247, v249
	s_waitcnt lgkmcnt(7)
	v_mfma_f32_32x32x16_bf16 v[128:143], v[206:209], v[144:147], 0
	v_add_u32_e32 v206, s98, v195
	ds_read_b128 v[206:209], v206 offset:8192
	s_waitcnt lgkmcnt(7)
	v_mfma_f32_32x32x16_bf16 v[128:143], v[210:213], v[148:151], v[128:143]
	v_add_u32_e32 v210, s98, v196
	ds_read_b128 v[210:213], v210 offset:8192
	s_waitcnt lgkmcnt(7)
	v_mfma_f32_32x32x16_bf16 v[128:143], v[214:217], v[152:155], v[128:143]
	v_add_u32_e32 v214, s98, v197
	ds_read_b128 v[214:217], v214 offset:8192
	s_waitcnt lgkmcnt(7)
	v_mfma_f32_32x32x16_bf16 v[128:143], v[238:241], v[156:159], v[128:143]
	v_add_u32_e32 v238, s98, v198
	ds_read_b128 v[238:241], v238 offset:8192
	s_waitcnt lgkmcnt(7)
	v_mfma_f32_32x32x16_bf16 v[128:143], v[242:245], v[160:163], v[128:143]
	v_add_u32_e32 v242, s98, v199
	ds_read_b128 v[242:245], v242 offset:8192
	s_waitcnt lgkmcnt(7)
	v_mfma_f32_32x32x16_bf16 v[128:143], v[250:253], v[164:167], v[128:143]
	v_add_u32_e32 v250, s98, v200
	ds_read_b128 v[250:253], v250 offset:8192
	s_waitcnt lgkmcnt(7)
	v_mfma_f32_32x32x16_bf16 v[128:143], v[222:225], v[168:171], v[128:143]
	s_waitcnt lgkmcnt(6)
	v_mfma_f32_32x32x16_bf16 v[128:143], v[226:229], v[172:175], v[128:143]
	s_waitcnt lgkmcnt(5)
	v_mfma_f32_32x32x16_bf16 v[222:237], v[206:209], v[144:147], 0
	v_add_u32_e32 v206, s98, v201
	ds_read_b128 v[206:209], v206 offset:8192
	s_nop 7
	v_max3_f32 v246, v128, v129, v130
	v_max3_f32 v247, v131, v132, v133
	v_max3_f32 v246, v246, v134, v135
	v_max3_f32 v247, v247, v136, v137
	v_max3_f32 v246, v246, v138, v139
	v_max3_f32 v247, v247, v140, v141
	v_max3_f32 v246, v246, v142, v143
	s_waitcnt lgkmcnt(5)
	v_mfma_f32_32x32x16_bf16 v[222:237], v[210:213], v[148:151], v[222:237]
	v_add_u32_e32 v210, s98, v202
	ds_read_b128 v[210:213], v210 offset:8192
	v_max_f32_e32 v246, v246, v247
	v_mov_b32_e32 v247, v246
	v_add_f32_e32 v249, 0x41000000, v190
	s_nop 1
	v_permlane32_swap_b32_e32 v246, v247
	v_max_f32_e32 v246, v246, v247
	v_cmp_gt_f32_e32 vcc, v246, v249
	s_cbranch_vccz .Latt_nr0_2
	v_max_f32_e32 v246, v190, v246
	v_sub_f32_e32 v190, v190, v246
	v_exp_f32_e32 v190, v190
	s_nop 0
	v_pk_mul_f32 v[126:127], v[126:127], v[190:191] op_sel_hi:[1,0]
	v_pk_mul_f32 v[124:125], v[124:125], v[190:191] op_sel_hi:[1,0]
	v_pk_mul_f32 v[122:123], v[122:123], v[190:191] op_sel_hi:[1,0]
	v_pk_mul_f32 v[120:121], v[120:121], v[190:191] op_sel_hi:[1,0]
	v_pk_mul_f32 v[118:119], v[118:119], v[190:191] op_sel_hi:[1,0]
	v_pk_mul_f32 v[116:117], v[116:117], v[190:191] op_sel_hi:[1,0]
	v_pk_mul_f32 v[114:115], v[114:115], v[190:191] op_sel_hi:[1,0]
	v_pk_mul_f32 v[112:113], v[112:113], v[190:191] op_sel_hi:[1,0]
	v_pk_mul_f32 v[110:111], v[110:111], v[190:191] op_sel_hi:[1,0]
	v_pk_mul_f32 v[108:109], v[108:109], v[190:191] op_sel_hi:[1,0]
	v_pk_mul_f32 v[106:107], v[106:107], v[190:191] op_sel_hi:[1,0]
	v_pk_mul_f32 v[104:105], v[104:105], v[190:191] op_sel_hi:[1,0]
	v_pk_mul_f32 v[102:103], v[102:103], v[190:191] op_sel_hi:[1,0]
	v_pk_mul_f32 v[100:101], v[100:101], v[190:191] op_sel_hi:[1,0]
	v_pk_mul_f32 v[98:99], v[98:99], v[190:191] op_sel_hi:[1,0]
	v_pk_mul_f32 v[96:97], v[96:97], v[190:191] op_sel_hi:[1,0]
	v_pk_mul_f32 v[94:95], v[94:95], v[190:191] op_sel_hi:[1,0]
	v_pk_mul_f32 v[92:93], v[92:93], v[190:191] op_sel_hi:[1,0]
	v_pk_mul_f32 v[90:91], v[90:91], v[190:191] op_sel_hi:[1,0]
	v_pk_mul_f32 v[88:89], v[88:89], v[190:191] op_sel_hi:[1,0]
	v_pk_mul_f32 v[86:87], v[86:87], v[190:191] op_sel_hi:[1,0]
	v_pk_mul_f32 v[84:85], v[84:85], v[190:191] op_sel_hi:[1,0]
	v_pk_mul_f32 v[82:83], v[82:83], v[190:191] op_sel_hi:[1,0]
	v_pk_mul_f32 v[80:81], v[80:81], v[190:191] op_sel_hi:[1,0]
	v_pk_mul_f32 v[78:79], v[78:79], v[190:191] op_sel_hi:[1,0]
	v_pk_mul_f32 v[76:77], v[76:77], v[190:191] op_sel_hi:[1,0]
	v_pk_mul_f32 v[74:75], v[74:75], v[190:191] op_sel_hi:[1,0]
	v_pk_mul_f32 v[72:73], v[72:73], v[190:191] op_sel_hi:[1,0]
	v_pk_mul_f32 v[70:71], v[70:71], v[190:191] op_sel_hi:[1,0]
	v_pk_mul_f32 v[68:69], v[68:69], v[190:191] op_sel_hi:[1,0]
	v_pk_mul_f32 v[66:67], v[66:67], v[190:191] op_sel_hi:[1,0]
	v_pk_mul_f32 v[64:65], v[64:65], v[190:191] op_sel_hi:[1,0]
	v_pk_mul_f32 v[62:63], v[62:63], v[190:191] op_sel_hi:[1,0]
	v_pk_mul_f32 v[60:61], v[60:61], v[190:191] op_sel_hi:[1,0]
	v_pk_mul_f32 v[58:59], v[58:59], v[190:191] op_sel_hi:[1,0]
	v_pk_mul_f32 v[56:57], v[56:57], v[190:191] op_sel_hi:[1,0]
	v_pk_mul_f32 v[54:55], v[54:55], v[190:191] op_sel_hi:[1,0]
	v_pk_mul_f32 v[52:53], v[52:53], v[190:191] op_sel_hi:[1,0]
	v_pk_mul_f32 v[50:51], v[50:51], v[190:191] op_sel_hi:[1,0]
	v_pk_mul_f32 v[48:49], v[48:49], v[190:191] op_sel_hi:[1,0]
	v_pk_mul_f32 v[46:47], v[46:47], v[190:191] op_sel_hi:[1,0]
	v_pk_mul_f32 v[44:45], v[44:45], v[190:191] op_sel_hi:[1,0]
	v_pk_mul_f32 v[42:43], v[42:43], v[190:191] op_sel_hi:[1,0]
	v_pk_mul_f32 v[40:41], v[40:41], v[190:191] op_sel_hi:[1,0]
	v_pk_mul_f32 v[38:39], v[38:39], v[190:191] op_sel_hi:[1,0]
	v_pk_mul_f32 v[36:37], v[36:37], v[190:191] op_sel_hi:[1,0]
	v_pk_mul_f32 v[34:35], v[34:35], v[190:191] op_sel_hi:[1,0]
	v_pk_mul_f32 v[32:33], v[32:33], v[190:191] op_sel_hi:[1,0]
	v_pk_mul_f32 v[30:31], v[30:31], v[190:191] op_sel_hi:[1,0]
	v_pk_mul_f32 v[28:29], v[28:29], v[190:191] op_sel_hi:[1,0]
	v_pk_mul_f32 v[26:27], v[26:27], v[190:191] op_sel_hi:[1,0]
	v_pk_mul_f32 v[24:25], v[24:25], v[190:191] op_sel_hi:[1,0]
	v_pk_mul_f32 v[22:23], v[22:23], v[190:191] op_sel_hi:[1,0]
	v_pk_mul_f32 v[20:21], v[20:21], v[190:191] op_sel_hi:[1,0]
	v_pk_mul_f32 v[18:19], v[18:19], v[190:191] op_sel_hi:[1,0]
	v_pk_mul_f32 v[16:17], v[16:17], v[190:191] op_sel_hi:[1,0]
	v_pk_mul_f32 v[14:15], v[14:15], v[190:191] op_sel_hi:[1,0]
	v_pk_mul_f32 v[12:13], v[12:13], v[190:191] op_sel_hi:[1,0]
	v_pk_mul_f32 v[10:11], v[10:11], v[190:191] op_sel_hi:[1,0]
	v_pk_mul_f32 v[8:9], v[8:9], v[190:191] op_sel_hi:[1,0]
	v_pk_mul_f32 v[6:7], v[6:7], v[190:191] op_sel_hi:[1,0]
	v_pk_mul_f32 v[4:5], v[4:5], v[190:191] op_sel_hi:[1,0]
	v_pk_mul_f32 v[2:3], v[2:3], v[190:191] op_sel_hi:[1,0]
	v_pk_mul_f32 v[0:1], v[0:1], v[190:191] op_sel_hi:[1,0]
	v_mul_f32_e32 v203, v203, v190
	v_mov_b32_e32 v190, v246
.Latt_nr0_2:
	s_waitcnt lgkmcnt(5)
	v_mfma_f32_32x32x16_bf16 v[222:237], v[214:217], v[152:155], v[222:237]
	ds_read_b64_tr_b16 v[214:215], v205
	ds_read_b64_tr_b16 v[216:217], v205 offset:4096
	v_sub_f32_e32 v128, v128, v190
	v_exp_f32_e32 v128, v128
	v_sub_f32_e32 v129, v129, v190
	v_exp_f32_e32 v129, v129
	v_sub_f32_e32 v130, v130, v190
	v_add_f32_e32 v254, 0, v128
	v_exp_f32_e32 v130, v130
	v_sub_f32_e32 v131, v131, v190
	s_waitcnt lgkmcnt(6)
	v_mfma_f32_32x32x16_bf16 v[222:237], v[238:241], v[156:159], v[222:237]
	ds_read_b64_tr_b16 v[238:239], v218
	ds_read_b64_tr_b16 v[240:241], v218 offset:4096
	v_add_f32_e32 v254, v129, v254
	v_exp_f32_e32 v131, v131
	v_sub_f32_e32 v132, v132, v190
	v_add_f32_e32 v254, v130, v254
	v_exp_f32_e32 v132, v132
	v_sub_f32_e32 v133, v133, v190
	v_add_f32_e32 v254, v131, v254
	v_exp_f32_e32 v133, v133
	s_waitcnt lgkmcnt(7)
	v_mfma_f32_32x32x16_bf16 v[222:237], v[242:245], v[160:163], v[222:237]
	v_sub_f32_e32 v134, v134, v190
	v_add_f32_e32 v254, v132, v254
	v_exp_f32_e32 v134, v134
	v_sub_f32_e32 v135, v135, v190
	v_add_f32_e32 v254, v133, v254
	v_exp_f32_e32 v135, v135
	v_sub_f32_e32 v136, v136, v190
	v_add_f32_e32 v254, v134, v254
	s_waitcnt lgkmcnt(6)
	v_mfma_f32_32x32x16_bf16 v[222:237], v[250:253], v[164:167], v[222:237]
	v_exp_f32_e32 v136, v136
	v_sub_f32_e32 v137, v137, v190
	v_add_f32_e32 v254, v135, v254
	v_exp_f32_e32 v137, v137
	v_sub_f32_e32 v138, v138, v190
	v_add_f32_e32 v254, v136, v254
	v_exp_f32_e32 v138, v138
	v_sub_f32_e32 v139, v139, v190
	s_waitcnt lgkmcnt(5)
	v_mfma_f32_32x32x16_bf16 v[222:237], v[206:209], v[168:171], v[222:237]
	ds_read_b64_tr_b16 v[206:207], v219
	ds_read_b64_tr_b16 v[208:209], v219 offset:4096
	v_add_f32_e32 v254, v137, v254
	v_exp_f32_e32 v139, v139
	v_sub_f32_e32 v140, v140, v190
	v_add_f32_e32 v254, v138, v254
	v_exp_f32_e32 v140, v140
	v_sub_f32_e32 v141, v141, v190
	v_add_f32_e32 v254, v139, v254
	v_exp_f32_e32 v141, v141
	s_waitcnt lgkmcnt(6)
	v_mfma_f32_32x32x16_bf16 v[222:237], v[210:213], v[172:175], v[222:237]
	ds_read_b64_tr_b16 v[210:211], v221
	ds_read_b64_tr_b16 v[212:213], v221 offset:4096
	v_sub_f32_e32 v142, v142, v190
	v_add_f32_e32 v254, v140, v254
	v_exp_f32_e32 v142, v142
	v_sub_f32_e32 v143, v143, v190
	v_add_f32_e32 v254, v141, v254
	v_exp_f32_e32 v143, v143
	v_add_f32_e32 v254, v142, v254
	v_add_f32_e32 v254, v143, v254
	v_cvt_pk_bf16_f32 v242, v128, v129
	v_cvt_pk_bf16_f32 v243, v130, v131
	v_cvt_pk_bf16_f32 v244, v132, v133
	v_cvt_pk_bf16_f32 v245, v134, v135
	v_cvt_pk_bf16_f32 v250, v136, v137
	v_cvt_pk_bf16_f32 v251, v138, v139
	v_cvt_pk_bf16_f32 v252, v140, v141
	v_cvt_pk_bf16_f32 v253, v142, v143
	v_add_f32_e32 v203, v203, v254
	s_nop 1
	ds_read_b64_tr_b16 v[128:129], v205 offset:256
	ds_read_b64_tr_b16 v[130:131], v205 offset:4352
	s_waitcnt lgkmcnt(8)
	v_mfma_f32_32x32x16_bf16 v[112:127], v[214:217], v[242:245], v[112:127]
	ds_read_b64_tr_b16 v[214:215], v218 offset:256
	ds_read_b64_tr_b16 v[216:217], v218 offset:4352
	s_waitcnt lgkmcnt(8)
	v_mfma_f32_32x32x16_bf16 v[96:111], v[238:241], v[242:245], v[96:111]
	ds_read_b64_tr_b16 v[238:239], v219 offset:256
	ds_read_b64_tr_b16 v[240:241], v219 offset:4352
	s_waitcnt lgkmcnt(8)
	v_mfma_f32_32x32x16_bf16 v[80:95], v[206:209], v[242:245], v[80:95]
	ds_read_b64_tr_b16 v[206:207], v221 offset:256
	ds_read_b64_tr_b16 v[208:209], v221 offset:4352
	v_max3_f32 v246, v222, v223, v224
	v_max3_f32 v247, v225, v226, v227
	v_max3_f32 v246, v246, v228, v229
	v_max3_f32 v247, v247, v230, v231
	v_max3_f32 v246, v246, v232, v233
	v_max3_f32 v247, v247, v234, v235
	s_waitcnt lgkmcnt(8)
	v_mfma_f32_32x32x16_bf16 v[64:79], v[210:213], v[242:245], v[64:79]
	ds_read_b64_tr_b16 v[210:211], v205 offset:8192
	ds_read_b64_tr_b16 v[212:213], v205 offset:12288
	v_max3_f32 v246, v246, v236, v237
	v_max_f32_e32 v246, v246, v247
	v_mov_b32_e32 v247, v246
	v_add_f32_e32 v249, 0x41000000, v190
	s_nop 1
	s_waitcnt lgkmcnt(8)
	v_mfma_f32_32x32x16_bf16 v[48:63], v[128:131], v[242:245], v[48:63]
	ds_read_b64_tr_b16 v[128:129], v218 offset:8192
	ds_read_b64_tr_b16 v[130:131], v218 offset:12288
	v_permlane32_swap_b32_e32 v246, v247
	v_max_f32_e32 v246, v246, v247
	v_cmp_gt_f32_e32 vcc, v246, v249
	s_cbranch_vccnz .Latt_rs1_2
	s_waitcnt lgkmcnt(8)
	v_mfma_f32_32x32x16_bf16 v[32:47], v[214:217], v[242:245], v[32:47]
	ds_read_b64_tr_b16 v[214:215], v219 offset:8192
	ds_read_b64_tr_b16 v[216:217], v219 offset:12288
	v_sub_f32_e32 v222, v222, v190
	v_exp_f32_e32 v222, v222
	v_sub_f32_e32 v223, v223, v190
	v_exp_f32_e32 v223, v223
	v_sub_f32_e32 v224, v224, v190
	s_waitcnt lgkmcnt(8)
	v_mfma_f32_32x32x16_bf16 v[16:31], v[238:241], v[242:245], v[16:31]
	ds_read_b64_tr_b16 v[238:239], v221 offset:8192
	ds_read_b64_tr_b16 v[240:241], v221 offset:12288
	v_add_f32_e32 v254, 0, v222
	v_exp_f32_e32 v224, v224
	v_sub_f32_e32 v225, v225, v190
	v_add_f32_e32 v254, v223, v254
	v_exp_f32_e32 v225, v225
	s_waitcnt lgkmcnt(8)
	v_mfma_f32_32x32x16_bf16 v[0:15], v[206:209], v[242:245], v[0:15]
	ds_read_b64_tr_b16 v[206:207], v205 offset:8448
	ds_read_b64_tr_b16 v[208:209], v205 offset:12544
	v_sub_f32_e32 v226, v226, v190
	v_add_f32_e32 v254, v224, v254
	v_exp_f32_e32 v226, v226
	v_sub_f32_e32 v227, v227, v190
	v_add_f32_e32 v254, v225, v254
	s_waitcnt lgkmcnt(8)
	v_mfma_f32_32x32x16_bf16 v[112:127], v[210:213], v[250:253], v[112:127]
	ds_read_b64_tr_b16 v[210:211], v218 offset:8448
	ds_read_b64_tr_b16 v[212:213], v218 offset:12544
	v_exp_f32_e32 v227, v227
	v_sub_f32_e32 v228, v228, v190
	v_add_f32_e32 v254, v226, v254
	v_exp_f32_e32 v228, v228
	v_sub_f32_e32 v229, v229, v190
	s_waitcnt lgkmcnt(8)
	v_mfma_f32_32x32x16_bf16 v[96:111], v[128:131], v[250:253], v[96:111]
	ds_read_b64_tr_b16 v[128:129], v219 offset:8448
	ds_read_b64_tr_b16 v[130:131], v219 offset:12544
	v_add_f32_e32 v254, v227, v254
	v_exp_f32_e32 v229, v229
	v_sub_f32_e32 v230, v230, v190
	v_add_f32_e32 v254, v228, v254
	s_waitcnt lgkmcnt(8)
	v_mfma_f32_32x32x16_bf16 v[80:95], v[214:217], v[250:253], v[80:95]
	ds_read_b64_tr_b16 v[214:215], v221 offset:8448
	ds_read_b64_tr_b16 v[216:217], v221 offset:12544
	v_exp_f32_e32 v230, v230
	v_sub_f32_e32 v231, v231, v190
	v_add_f32_e32 v254, v229, v254
	v_exp_f32_e32 v231, v231
	s_waitcnt lgkmcnt(8)
	v_mfma_f32_32x32x16_bf16 v[64:79], v[238:241], v[250:253], v[64:79]
	ds_read_b64_tr_b16 v[238:239], v205 offset:16384
	ds_read_b64_tr_b16 v[240:241], v205 offset:20480
	v_sub_f32_e32 v232, v232, v190
	v_add_f32_e32 v254, v230, v254
	v_exp_f32_e32 v232, v232
	v_sub_f32_e32 v233, v233, v190
	s_waitcnt lgkmcnt(8)
	v_mfma_f32_32x32x16_bf16 v[48:63], v[206:209], v[250:253], v[48:63]
	ds_read_b64_tr_b16 v[206:207], v218 offset:16384
	ds_read_b64_tr_b16 v[208:209], v218 offset:20480
	v_add_f32_e32 v254, v231, v254
	v_exp_f32_e32 v233, v233
	v_sub_f32_e32 v234, v234, v190
	v_add_f32_e32 v254, v232, v254
	s_waitcnt lgkmcnt(8)
	v_mfma_f32_32x32x16_bf16 v[32:47], v[210:213], v[250:253], v[32:47]
	ds_read_b64_tr_b16 v[210:211], v219 offset:16384
	ds_read_b64_tr_b16 v[212:213], v219 offset:20480
	v_exp_f32_e32 v234, v234
	v_sub_f32_e32 v235, v235, v190
	v_add_f32_e32 v254, v233, v254
	v_exp_f32_e32 v235, v235
	s_waitcnt lgkmcnt(8)
	v_mfma_f32_32x32x16_bf16 v[16:31], v[128:131], v[250:253], v[16:31]
	ds_read_b64_tr_b16 v[128:129], v221 offset:16384
	ds_read_b64_tr_b16 v[130:131], v221 offset:20480
	v_sub_f32_e32 v236, v236, v190
	v_add_f32_e32 v254, v234, v254
	v_exp_f32_e32 v236, v236
	v_sub_f32_e32 v237, v237, v190
	s_waitcnt lgkmcnt(8)
	v_mfma_f32_32x32x16_bf16 v[0:15], v[214:217], v[250:253], v[0:15]
	ds_read_b64_tr_b16 v[214:215], v205 offset:16640
	ds_read_b64_tr_b16 v[216:217], v205 offset:20736
	v_add_f32_e32 v254, v235, v254
	v_exp_f32_e32 v237, v237
	v_add_f32_e32 v254, v236, v254
	v_add_f32_e32 v254, v237, v254
	v_cvt_pk_bf16_f32 v242, v222, v223
	v_cvt_pk_bf16_f32 v243, v224, v225
	v_cvt_pk_bf16_f32 v244, v226, v227
	v_cvt_pk_bf16_f32 v245, v228, v229
	v_cvt_pk_bf16_f32 v250, v230, v231
	v_cvt_pk_bf16_f32 v251, v232, v233
	v_cvt_pk_bf16_f32 v252, v234, v235
	v_cvt_pk_bf16_f32 v253, v236, v237
	v_add_f32_e32 v203, v203, v254
	s_nop 1
.Latt_pv1_2:
	s_waitcnt lgkmcnt(8)
	v_mfma_f32_32x32x16_bf16 v[112:127], v[238:241], v[242:245], v[112:127]
	ds_read_b64_tr_b16 v[238:239], v218 offset:16640
	ds_read_b64_tr_b16 v[240:241], v218 offset:20736
	s_waitcnt lgkmcnt(8)
	v_mfma_f32_32x32x16_bf16 v[96:111], v[206:209], v[242:245], v[96:111]
	ds_read_b64_tr_b16 v[206:207], v219 offset:16640
	ds_read_b64_tr_b16 v[208:209], v219 offset:20736
	s_cmp_lg_u64 s[12:13], 0
	s_cbranch_scc1 .Latt_nd0_2
	s_sub_i32 s100, s38, 1
	s_cmp_eq_u32 s38, 0
	s_cselect_b32 s100, 2, s100
	s_lshl_b32 s101, s100, 14
	s_add_i32 m0, s40, s101
	s_nop 0
	global_load_lds_dwordx4 v178, s[22:23]
.Latt_nd0_2:
	s_waitcnt lgkmcnt(8)
	v_mfma_f32_32x32x16_bf16 v[80:95], v[210:213], v[242:245], v[80:95]
	ds_read_b64_tr_b16 v[210:211], v221 offset:16640
	ds_read_b64_tr_b16 v[212:213], v221 offset:20736
	s_waitcnt lgkmcnt(8)
	v_mfma_f32_32x32x16_bf16 v[64:79], v[128:131], v[242:245], v[64:79]
	ds_read_b64_tr_b16 v[222:223], v205 offset:24576
	ds_read_b64_tr_b16 v[224:225], v205 offset:28672
	s_cmp_lg_u64 s[12:13], 0
	s_cbranch_scc1 .Latt_nd1_2
	s_add_i32 m0, m0, 0x400
	s_nop 0
	global_load_lds_dwordx4 v180, s[22:23]
.Latt_nd1_2:
	s_waitcnt lgkmcnt(8)
	v_mfma_f32_32x32x16_bf16 v[48:63], v[214:217], v[242:245], v[48:63]
	ds_read_b64_tr_b16 v[214:215], v218 offset:24576
	ds_read_b64_tr_b16 v[216:217], v218 offset:28672
	s_waitcnt lgkmcnt(8)
	v_mfma_f32_32x32x16_bf16 v[32:47], v[238:241], v[242:245], v[32:47]
	ds_read_b64_tr_b16 v[238:239], v219 offset:24576
	ds_read_b64_tr_b16 v[240:241], v219 offset:28672
	s_cmp_lg_u64 s[12:13], 0
	s_cbranch_scc1 .Latt_nd2_2
	s_lshl_b32 s101, s100, 15
	s_add_i32 m0, s41, s101
	s_add_u32 s100, s22, 0x1000
	s_addc_u32 s101, s23, 0
	global_load_lds_dwordx4 v182, s[100:101]
.Latt_nd2_2:
	s_waitcnt lgkmcnt(8)
	v_mfma_f32_32x32x16_bf16 v[16:31], v[206:209], v[242:245], v[16:31]
	ds_read_b64_tr_b16 v[206:207], v221 offset:24576
	ds_read_b64_tr_b16 v[208:209], v221 offset:28672
	s_waitcnt lgkmcnt(8)
	v_mfma_f32_32x32x16_bf16 v[0:15], v[210:213], v[242:245], v[0:15]
	ds_read_b64_tr_b16 v[210:211], v205 offset:24832
	ds_read_b64_tr_b16 v[212:213], v205 offset:28928
	s_cmp_lg_u64 s[12:13], 0
	s_cbranch_scc1 .Latt_nd3_2
	s_add_i32 m0, m0, 0x400
	s_nop 0
	global_load_lds_dwordx4 v184, s[100:101]
.Latt_nd3_2:
	s_waitcnt lgkmcnt(8)
	v_mfma_f32_32x32x16_bf16 v[112:127], v[222:225], v[250:253], v[112:127]
	ds_read_b64_tr_b16 v[222:223], v218 offset:24832
	ds_read_b64_tr_b16 v[224:225], v218 offset:28928
	s_waitcnt lgkmcnt(8)
	v_mfma_f32_32x32x16_bf16 v[96:111], v[214:217], v[250:253], v[96:111]
	ds_read_b64_tr_b16 v[214:215], v219 offset:24832
	ds_read_b64_tr_b16 v[216:217], v219 offset:28928
	s_cmp_lg_u64 s[12:13], 0
	s_cbranch_scc1 .Latt_nd4_2
	s_add_i32 m0, m0, 0x400
	s_nop 0
	global_load_lds_dwordx4 v186, s[100:101]
.Latt_nd4_2:
	s_waitcnt lgkmcnt(8)
	v_mfma_f32_32x32x16_bf16 v[80:95], v[238:241], v[250:253], v[80:95]
	ds_read_b64_tr_b16 v[238:239], v221 offset:24832
	ds_read_b64_tr_b16 v[240:241], v221 offset:28928
	s_waitcnt lgkmcnt(8)
	v_mfma_f32_32x32x16_bf16 v[64:79], v[206:209], v[250:253], v[64:79]
	s_cmp_lg_u64 s[12:13], 0
	s_cbranch_scc1 .Latt_nd5_2
	s_add_i32 m0, m0, 0x400
	s_nop 0
	global_load_lds_dwordx4 v188, s[100:101]

.Latt_rs1_2:
	s_waitcnt lgkmcnt(8)
	v_mfma_f32_32x32x16_bf16 v[32:47], v[214:217], v[242:245], v[32:47]
	ds_read_b64_tr_b16 v[214:215], v219 offset:8192
	ds_read_b64_tr_b16 v[216:217], v219 offset:12288
	s_waitcnt lgkmcnt(8)
	v_mfma_f32_32x32x16_bf16 v[16:31], v[238:241], v[242:245], v[16:31]
	ds_read_b64_tr_b16 v[238:239], v221 offset:8192
	ds_read_b64_tr_b16 v[240:241], v221 offset:12288
	s_waitcnt lgkmcnt(8)
	v_mfma_f32_32x32x16_bf16 v[0:15], v[206:209], v[242:245], v[0:15]
	ds_read_b64_tr_b16 v[206:207], v205 offset:8448
	ds_read_b64_tr_b16 v[208:209], v205 offset:12544
	s_waitcnt lgkmcnt(8)
	v_mfma_f32_32x32x16_bf16 v[112:127], v[210:213], v[250:253], v[112:127]
	ds_read_b64_tr_b16 v[210:211], v218 offset:8448
	ds_read_b64_tr_b16 v[212:213], v218 offset:12544
	s_waitcnt lgkmcnt(8)
	v_mfma_f32_32x32x16_bf16 v[96:111], v[128:131], v[250:253], v[96:111]
	ds_read_b64_tr_b16 v[128:129], v219 offset:8448
	ds_read_b64_tr_b16 v[130:131], v219 offset:12544
	s_waitcnt lgkmcnt(8)
	v_mfma_f32_32x32x16_bf16 v[80:95], v[214:217], v[250:253], v[80:95]
	ds_read_b64_tr_b16 v[214:215], v221 offset:8448
	ds_read_b64_tr_b16 v[216:217], v221 offset:12544
	s_waitcnt lgkmcnt(8)
	v_mfma_f32_32x32x16_bf16 v[64:79], v[238:241], v[250:253], v[64:79]
	ds_read_b64_tr_b16 v[238:239], v205 offset:16384
	ds_read_b64_tr_b16 v[240:241], v205 offset:20480
	s_waitcnt lgkmcnt(8)
	v_mfma_f32_32x32x16_bf16 v[48:63], v[206:209], v[250:253], v[48:63]
	ds_read_b64_tr_b16 v[206:207], v218 offset:16384
	ds_read_b64_tr_b16 v[208:209], v218 offset:20480
	s_waitcnt lgkmcnt(8)
	v_mfma_f32_32x32x16_bf16 v[32:47], v[210:213], v[250:253], v[32:47]
	ds_read_b64_tr_b16 v[210:211], v219 offset:16384
	ds_read_b64_tr_b16 v[212:213], v219 offset:20480
	s_waitcnt lgkmcnt(8)
	v_mfma_f32_32x32x16_bf16 v[16:31], v[128:131], v[250:253], v[16:31]
	ds_read_b64_tr_b16 v[128:129], v221 offset:16384
	ds_read_b64_tr_b16 v[130:131], v221 offset:20480
	s_waitcnt lgkmcnt(8)
	v_mfma_f32_32x32x16_bf16 v[0:15], v[214:217], v[250:253], v[0:15]
	ds_read_b64_tr_b16 v[214:215], v205 offset:16640
	ds_read_b64_tr_b16 v[216:217], v205 offset:20736
	s_nop 11
	v_max_f32_e32 v246, v190, v246
	v_sub_f32_e32 v190, v190, v246
	v_exp_f32_e32 v190, v190
	s_nop 0
	v_pk_mul_f32 v[126:127], v[126:127], v[190:191] op_sel_hi:[1,0]
	v_pk_mul_f32 v[124:125], v[124:125], v[190:191] op_sel_hi:[1,0]
	v_pk_mul_f32 v[122:123], v[122:123], v[190:191] op_sel_hi:[1,0]
	v_pk_mul_f32 v[120:121], v[120:121], v[190:191] op_sel_hi:[1,0]
	v_pk_mul_f32 v[118:119], v[118:119], v[190:191] op_sel_hi:[1,0]
	v_pk_mul_f32 v[116:117], v[116:117], v[190:191] op_sel_hi:[1,0]
	v_pk_mul_f32 v[114:115], v[114:115], v[190:191] op_sel_hi:[1,0]
	v_pk_mul_f32 v[112:113], v[112:113], v[190:191] op_sel_hi:[1,0]
	v_pk_mul_f32 v[110:111], v[110:111], v[190:191] op_sel_hi:[1,0]
	v_pk_mul_f32 v[108:109], v[108:109], v[190:191] op_sel_hi:[1,0]
	v_pk_mul_f32 v[106:107], v[106:107], v[190:191] op_sel_hi:[1,0]
	v_pk_mul_f32 v[104:105], v[104:105], v[190:191] op_sel_hi:[1,0]
	v_pk_mul_f32 v[102:103], v[102:103], v[190:191] op_sel_hi:[1,0]
	v_pk_mul_f32 v[100:101], v[100:101], v[190:191] op_sel_hi:[1,0]
	v_pk_mul_f32 v[98:99], v[98:99], v[190:191] op_sel_hi:[1,0]
	v_pk_mul_f32 v[96:97], v[96:97], v[190:191] op_sel_hi:[1,0]
	v_pk_mul_f32 v[94:95], v[94:95], v[190:191] op_sel_hi:[1,0]
	v_pk_mul_f32 v[92:93], v[92:93], v[190:191] op_sel_hi:[1,0]
	v_pk_mul_f32 v[90:91], v[90:91], v[190:191] op_sel_hi:[1,0]
	v_pk_mul_f32 v[88:89], v[88:89], v[190:191] op_sel_hi:[1,0]
	v_pk_mul_f32 v[86:87], v[86:87], v[190:191] op_sel_hi:[1,0]
	v_pk_mul_f32 v[84:85], v[84:85], v[190:191] op_sel_hi:[1,0]
	v_pk_mul_f32 v[82:83], v[82:83], v[190:191] op_sel_hi:[1,0]
	v_pk_mul_f32 v[80:81], v[80:81], v[190:191] op_sel_hi:[1,0]
	v_pk_mul_f32 v[78:79], v[78:79], v[190:191] op_sel_hi:[1,0]
	v_pk_mul_f32 v[76:77], v[76:77], v[190:191] op_sel_hi:[1,0]
	v_pk_mul_f32 v[74:75], v[74:75], v[190:191] op_sel_hi:[1,0]
	v_pk_mul_f32 v[72:73], v[72:73], v[190:191] op_sel_hi:[1,0]
	v_pk_mul_f32 v[70:71], v[70:71], v[190:191] op_sel_hi:[1,0]
	v_pk_mul_f32 v[68:69], v[68:69], v[190:191] op_sel_hi:[1,0]
	v_pk_mul_f32 v[66:67], v[66:67], v[190:191] op_sel_hi:[1,0]
	v_pk_mul_f32 v[64:65], v[64:65], v[190:191] op_sel_hi:[1,0]
	v_pk_mul_f32 v[62:63], v[62:63], v[190:191] op_sel_hi:[1,0]
	v_pk_mul_f32 v[60:61], v[60:61], v[190:191] op_sel_hi:[1,0]
	v_pk_mul_f32 v[58:59], v[58:59], v[190:191] op_sel_hi:[1,0]
	v_pk_mul_f32 v[56:57], v[56:57], v[190:191] op_sel_hi:[1,0]
	v_pk_mul_f32 v[54:55], v[54:55], v[190:191] op_sel_hi:[1,0]
	v_pk_mul_f32 v[52:53], v[52:53], v[190:191] op_sel_hi:[1,0]
	v_pk_mul_f32 v[50:51], v[50:51], v[190:191] op_sel_hi:[1,0]
	v_pk_mul_f32 v[48:49], v[48:49], v[190:191] op_sel_hi:[1,0]
	v_pk_mul_f32 v[46:47], v[46:47], v[190:191] op_sel_hi:[1,0]
	v_pk_mul_f32 v[44:45], v[44:45], v[190:191] op_sel_hi:[1,0]
	v_pk_mul_f32 v[42:43], v[42:43], v[190:191] op_sel_hi:[1,0]
	v_pk_mul_f32 v[40:41], v[40:41], v[190:191] op_sel_hi:[1,0]
	v_pk_mul_f32 v[38:39], v[38:39], v[190:191] op_sel_hi:[1,0]
	v_pk_mul_f32 v[36:37], v[36:37], v[190:191] op_sel_hi:[1,0]
	v_pk_mul_f32 v[34:35], v[34:35], v[190:191] op_sel_hi:[1,0]
	v_pk_mul_f32 v[32:33], v[32:33], v[190:191] op_sel_hi:[1,0]
	v_pk_mul_f32 v[30:31], v[30:31], v[190:191] op_sel_hi:[1,0]
	v_pk_mul_f32 v[28:29], v[28:29], v[190:191] op_sel_hi:[1,0]
	v_pk_mul_f32 v[26:27], v[26:27], v[190:191] op_sel_hi:[1,0]
	v_pk_mul_f32 v[24:25], v[24:25], v[190:191] op_sel_hi:[1,0]
	v_pk_mul_f32 v[22:23], v[22:23], v[190:191] op_sel_hi:[1,0]
	v_pk_mul_f32 v[20:21], v[20:21], v[190:191] op_sel_hi:[1,0]
	v_pk_mul_f32 v[18:19], v[18:19], v[190:191] op_sel_hi:[1,0]
	v_pk_mul_f32 v[16:17], v[16:17], v[190:191] op_sel_hi:[1,0]
	v_pk_mul_f32 v[14:15], v[14:15], v[190:191] op_sel_hi:[1,0]
	v_pk_mul_f32 v[12:13], v[12:13], v[190:191] op_sel_hi:[1,0]
	v_pk_mul_f32 v[10:11], v[10:11], v[190:191] op_sel_hi:[1,0]
	v_pk_mul_f32 v[8:9], v[8:9], v[190:191] op_sel_hi:[1,0]
	v_pk_mul_f32 v[6:7], v[6:7], v[190:191] op_sel_hi:[1,0]
	v_pk_mul_f32 v[4:5], v[4:5], v[190:191] op_sel_hi:[1,0]
	v_pk_mul_f32 v[2:3], v[2:3], v[190:191] op_sel_hi:[1,0]
	v_pk_mul_f32 v[0:1], v[0:1], v[190:191] op_sel_hi:[1,0]
	v_mul_f32_e32 v203, v203, v190
	v_mov_b32_e32 v190, v246
	v_sub_f32_e32 v222, v222, v190
	v_exp_f32_e32 v222, v222
	v_sub_f32_e32 v223, v223, v190
	v_exp_f32_e32 v223, v223
	v_sub_f32_e32 v224, v224, v190
	v_add_f32_e32 v254, 0, v222
	v_exp_f32_e32 v224, v224
	v_sub_f32_e32 v225, v225, v190
	v_add_f32_e32 v254, v223, v254
	v_exp_f32_e32 v225, v225
	v_sub_f32_e32 v226, v226, v190
	v_add_f32_e32 v254, v224, v254
	v_exp_f32_e32 v226, v226
	v_sub_f32_e32 v227, v227, v190
	v_add_f32_e32 v254, v225, v254
	v_exp_f32_e32 v227, v227
	v_sub_f32_e32 v228, v228, v190
	v_add_f32_e32 v254, v226, v254
	v_exp_f32_e32 v228, v228
	v_sub_f32_e32 v229, v229, v190
	v_add_f32_e32 v254, v227, v254
	v_exp_f32_e32 v229, v229
	v_sub_f32_e32 v230, v230, v190
	v_add_f32_e32 v254, v228, v254
	v_exp_f32_e32 v230, v230
	v_sub_f32_e32 v231, v231, v190
	v_add_f32_e32 v254, v229, v254
	v_exp_f32_e32 v231, v231
	v_sub_f32_e32 v232, v232, v190
	v_add_f32_e32 v254, v230, v254
	v_exp_f32_e32 v232, v232
	v_sub_f32_e32 v233, v233, v190
	v_add_f32_e32 v254, v231, v254
	v_exp_f32_e32 v233, v233
	v_sub_f32_e32 v234, v234, v190
	v_add_f32_e32 v254, v232, v254
	v_exp_f32_e32 v234, v234
	v_sub_f32_e32 v235, v235, v190
	v_add_f32_e32 v254, v233, v254
	v_exp_f32_e32 v235, v235
	v_sub_f32_e32 v236, v236, v190
	v_add_f32_e32 v254, v234, v254
	v_exp_f32_e32 v236, v236
	v_sub_f32_e32 v237, v237, v190
	v_add_f32_e32 v254, v235, v254
	v_exp_f32_e32 v237, v237
	v_add_f32_e32 v254, v236, v254
	v_add_f32_e32 v254, v237, v254
	v_cvt_pk_bf16_f32 v242, v222, v223
	v_cvt_pk_bf16_f32 v243, v224, v225
	v_cvt_pk_bf16_f32 v244, v226, v227
	v_cvt_pk_bf16_f32 v245, v228, v229
	v_cvt_pk_bf16_f32 v250, v230, v231
	v_cvt_pk_bf16_f32 v251, v232, v233
	v_cvt_pk_bf16_f32 v252, v234, v235
	v_cvt_pk_bf16_f32 v253, v236, v237
	v_add_f32_e32 v203, v203, v254
	s_nop 1
	s_branch .Latt_pv1_2

.LBB0_904:
	s_cmp_gt_i32 s14, s81
	s_cbranch_scc1 .LBB0_915
	s_add_i32 s100, s14, 63
	s_cmp_le_i32 s100, s80
	s_cbranch_scc0 .Latt_slow_3
	s_lshl_b32 s98, s11, 14
	s_lshl_b32 s99, s11, 15
	s_add_i32 s99, s99, 0xc000
	v_add_u32_e32 v206, s98, v196
	ds_read_b128 v[206:209], v206
	v_add_u32_e32 v210, s98, v197
	ds_read_b128 v[210:213], v210
	v_add_u32_e32 v214, s98, v198
	ds_read_b128 v[214:217], v214
	v_add_u32_e32 v238, s98, v199
	ds_read_b128 v[238:241], v238
	v_add_u32_e32 v242, s98, v200
	ds_read_b128 v[242:245], v242
	v_add_u32_e32 v250, s98, v201
	ds_read_b128 v[250:253], v250
	v_add_u32_e32 v222, s98, v202
	ds_read_b128 v[222:225], v222
	v_add_u32_e32 v226, s98, v203
	ds_read_b128 v[226:229], v226
	v_bfe_u32 v246, v204, 2, 2
	v_bfe_u32 v247, v204, 5, 1
	v_lshl_or_b32 v247, v247, 2, v246
	v_and_b32_e32 v249, 3, v204
	v_and_b32_e32 v254, 16, v204
	v_lshl_or_b32 v249, v249, 2, v254
	v_lshlrev_b32_e32 v249, 1, v249
	v_lshl_add_u32 v247, v247, 9, v249
	v_add_u32_e32 v247, s99, v247
	v_lshlrev_b32_e32 v246, 6, v246
	v_add_u32_e32 v205, v247, v246
	v_xor_b32_e32 v249, 64, v246
	v_add_u32_e32 v218, v247, v249
	v_xor_b32_e32 v249, 0x80, v246
	v_add_u32_e32 v219, v247, v249
	v_xor_b32_e32 v249, 0xc0, v246
	v_add_u32_e32 v221, v247, v249
	s_waitcnt lgkmcnt(7)
	v_mfma_f32_32x32x16_bf16 v[128:143], v[206:209], v[144:147], 0
	v_add_u32_e32 v206, s98, v196
	ds_read_b128 v[206:209], v206 offset:8192
	s_waitcnt lgkmcnt(7)
	v_mfma_f32_32x32x16_bf16 v[128:143], v[210:213], v[148:151], v[128:143]
	v_add_u32_e32 v210, s98, v197
	ds_read_b128 v[210:213], v210 offset:8192
	s_waitcnt lgkmcnt(7)
	v_mfma_f32_32x32x16_bf16 v[128:143], v[214:217], v[152:155], v[128:143]
	v_add_u32_e32 v214, s98, v198
	ds_read_b128 v[214:217], v214 offset:8192
	s_waitcnt lgkmcnt(7)
	v_mfma_f32_32x32x16_bf16 v[128:143], v[238:241], v[156:159], v[128:143]
	v_add_u32_e32 v238, s98, v199
	ds_read_b128 v[238:241], v238 offset:8192
	s_waitcnt lgkmcnt(7)
	v_mfma_f32_32x32x16_bf16 v[128:143], v[242:245], v[160:163], v[128:143]
	v_add_u32_e32 v242, s98, v200
	ds_read_b128 v[242:245], v242 offset:8192
	s_waitcnt lgkmcnt(7)
	v_mfma_f32_32x32x16_bf16 v[128:143], v[250:253], v[164:167], v[128:143]
	v_add_u32_e32 v250, s98, v201
	ds_read_b128 v[250:253], v250 offset:8192
	s_waitcnt lgkmcnt(7)
	v_mfma_f32_32x32x16_bf16 v[128:143], v[222:225], v[168:171], v[128:143]
	s_waitcnt lgkmcnt(6)
	v_mfma_f32_32x32x16_bf16 v[128:143], v[226:229], v[172:175], v[128:143]
	s_waitcnt lgkmcnt(5)
	v_mfma_f32_32x32x16_bf16 v[222:237], v[206:209], v[144:147], 0
	v_add_u32_e32 v206, s98, v202
	ds_read_b128 v[206:209], v206 offset:8192
	s_nop 7
	v_max3_f32 v246, v128, v129, v130
	v_max3_f32 v247, v131, v132, v133
	v_max3_f32 v246, v246, v134, v135
	v_max3_f32 v247, v247, v136, v137
	v_max3_f32 v246, v246, v138, v139
	v_max3_f32 v247, v247, v140, v141
	v_max3_f32 v246, v246, v142, v143
	s_waitcnt lgkmcnt(5)
	v_mfma_f32_32x32x16_bf16 v[222:237], v[210:213], v[148:151], v[222:237]
	v_add_u32_e32 v210, s98, v203
	ds_read_b128 v[210:213], v210 offset:8192
	v_max_f32_e32 v246, v246, v247
	v_mov_b32_e32 v247, v246
	v_add_f32_e32 v249, 0x41000000, v190
	s_nop 1
	v_permlane32_swap_b32_e32 v246, v247
	v_max_f32_e32 v246, v246, v247
	v_cmp_gt_f32_e32 vcc, v246, v249
	s_cbranch_vccz .Latt_nr0_3
	v_max_f32_e32 v246, v190, v246
	v_sub_f32_e32 v190, v190, v246
	v_exp_f32_e32 v190, v190
	s_nop 0
	v_pk_mul_f32 v[126:127], v[126:127], v[190:191] op_sel_hi:[1,0]
	v_pk_mul_f32 v[124:125], v[124:125], v[190:191] op_sel_hi:[1,0]
	v_pk_mul_f32 v[122:123], v[122:123], v[190:191] op_sel_hi:[1,0]
	v_pk_mul_f32 v[120:121], v[120:121], v[190:191] op_sel_hi:[1,0]
	v_pk_mul_f32 v[118:119], v[118:119], v[190:191] op_sel_hi:[1,0]
	v_pk_mul_f32 v[116:117], v[116:117], v[190:191] op_sel_hi:[1,0]
	v_pk_mul_f32 v[114:115], v[114:115], v[190:191] op_sel_hi:[1,0]
	v_pk_mul_f32 v[112:113], v[112:113], v[190:191] op_sel_hi:[1,0]
	v_pk_mul_f32 v[110:111], v[110:111], v[190:191] op_sel_hi:[1,0]
	v_pk_mul_f32 v[108:109], v[108:109], v[190:191] op_sel_hi:[1,0]
	v_pk_mul_f32 v[106:107], v[106:107], v[190:191] op_sel_hi:[1,0]
	v_pk_mul_f32 v[104:105], v[104:105], v[190:191] op_sel_hi:[1,0]
	v_pk_mul_f32 v[102:103], v[102:103], v[190:191] op_sel_hi:[1,0]
	v_pk_mul_f32 v[100:101], v[100:101], v[190:191] op_sel_hi:[1,0]
	v_pk_mul_f32 v[98:99], v[98:99], v[190:191] op_sel_hi:[1,0]
	v_pk_mul_f32 v[96:97], v[96:97], v[190:191] op_sel_hi:[1,0]
	v_pk_mul_f32 v[94:95], v[94:95], v[190:191] op_sel_hi:[1,0]
	v_pk_mul_f32 v[92:93], v[92:93], v[190:191] op_sel_hi:[1,0]
	v_pk_mul_f32 v[90:91], v[90:91], v[190:191] op_sel_hi:[1,0]
	v_pk_mul_f32 v[88:89], v[88:89], v[190:191] op_sel_hi:[1,0]
	v_pk_mul_f32 v[86:87], v[86:87], v[190:191] op_sel_hi:[1,0]
	v_pk_mul_f32 v[84:85], v[84:85], v[190:191] op_sel_hi:[1,0]
	v_pk_mul_f32 v[82:83], v[82:83], v[190:191] op_sel_hi:[1,0]
	v_pk_mul_f32 v[80:81], v[80:81], v[190:191] op_sel_hi:[1,0]
	v_pk_mul_f32 v[78:79], v[78:79], v[190:191] op_sel_hi:[1,0]
	v_pk_mul_f32 v[76:77], v[76:77], v[190:191] op_sel_hi:[1,0]
	v_pk_mul_f32 v[74:75], v[74:75], v[190:191] op_sel_hi:[1,0]
	v_pk_mul_f32 v[72:73], v[72:73], v[190:191] op_sel_hi:[1,0]
	v_pk_mul_f32 v[70:71], v[70:71], v[190:191] op_sel_hi:[1,0]
	v_pk_mul_f32 v[68:69], v[68:69], v[190:191] op_sel_hi:[1,0]
	v_pk_mul_f32 v[66:67], v[66:67], v[190:191] op_sel_hi:[1,0]
	v_pk_mul_f32 v[64:65], v[64:65], v[190:191] op_sel_hi:[1,0]
	v_pk_mul_f32 v[62:63], v[62:63], v[190:191] op_sel_hi:[1,0]
	v_pk_mul_f32 v[60:61], v[60:61], v[190:191] op_sel_hi:[1,0]
	v_pk_mul_f32 v[58:59], v[58:59], v[190:191] op_sel_hi:[1,0]
	v_pk_mul_f32 v[56:57], v[56:57], v[190:191] op_sel_hi:[1,0]
	v_pk_mul_f32 v[54:55], v[54:55], v[190:191] op_sel_hi:[1,0]
	v_pk_mul_f32 v[52:53], v[52:53], v[190:191] op_sel_hi:[1,0]
	v_pk_mul_f32 v[50:51], v[50:51], v[190:191] op_sel_hi:[1,0]
	v_pk_mul_f32 v[48:49], v[48:49], v[190:191] op_sel_hi:[1,0]
	v_pk_mul_f32 v[46:47], v[46:47], v[190:191] op_sel_hi:[1,0]
	v_pk_mul_f32 v[44:45], v[44:45], v[190:191] op_sel_hi:[1,0]
	v_pk_mul_f32 v[42:43], v[42:43], v[190:191] op_sel_hi:[1,0]
	v_pk_mul_f32 v[40:41], v[40:41], v[190:191] op_sel_hi:[1,0]
	v_pk_mul_f32 v[38:39], v[38:39], v[190:191] op_sel_hi:[1,0]
	v_pk_mul_f32 v[36:37], v[36:37], v[190:191] op_sel_hi:[1,0]
	v_pk_mul_f32 v[34:35], v[34:35], v[190:191] op_sel_hi:[1,0]
	v_pk_mul_f32 v[32:33], v[32:33], v[190:191] op_sel_hi:[1,0]
	v_pk_mul_f32 v[30:31], v[30:31], v[190:191] op_sel_hi:[1,0]
	v_pk_mul_f32 v[28:29], v[28:29], v[190:191] op_sel_hi:[1,0]
	v_pk_mul_f32 v[26:27], v[26:27], v[190:191] op_sel_hi:[1,0]
	v_pk_mul_f32 v[24:25], v[24:25], v[190:191] op_sel_hi:[1,0]
	v_pk_mul_f32 v[22:23], v[22:23], v[190:191] op_sel_hi:[1,0]
	v_pk_mul_f32 v[20:21], v[20:21], v[190:191] op_sel_hi:[1,0]
	v_pk_mul_f32 v[18:19], v[18:19], v[190:191] op_sel_hi:[1,0]
	v_pk_mul_f32 v[16:17], v[16:17], v[190:191] op_sel_hi:[1,0]
	v_pk_mul_f32 v[14:15], v[14:15], v[190:191] op_sel_hi:[1,0]
	v_pk_mul_f32 v[12:13], v[12:13], v[190:191] op_sel_hi:[1,0]
	v_pk_mul_f32 v[10:11], v[10:11], v[190:191] op_sel_hi:[1,0]
	v_pk_mul_f32 v[8:9], v[8:9], v[190:191] op_sel_hi:[1,0]
	v_pk_mul_f32 v[6:7], v[6:7], v[190:191] op_sel_hi:[1,0]
	v_pk_mul_f32 v[4:5], v[4:5], v[190:191] op_sel_hi:[1,0]
	v_pk_mul_f32 v[2:3], v[2:3], v[190:191] op_sel_hi:[1,0]
	v_pk_mul_f32 v[0:1], v[0:1], v[190:191] op_sel_hi:[1,0]
	v_mul_f32_e32 v195, v195, v190
	v_mov_b32_e32 v190, v246

.Latt_pv1_3:
	s_waitcnt lgkmcnt(8)
	v_mfma_f32_32x32x16_bf16 v[112:127], v[238:241], v[242:245], v[112:127]
	ds_read_b64_tr_b16 v[238:239], v218 offset:16640
	ds_read_b64_tr_b16 v[240:241], v218 offset:20736
	s_waitcnt lgkmcnt(8)
	v_mfma_f32_32x32x16_bf16 v[96:111], v[206:209], v[242:245], v[96:111]
	ds_read_b64_tr_b16 v[206:207], v219 offset:16640
	ds_read_b64_tr_b16 v[208:209], v219 offset:20736
	s_cmp_lg_u64 s[8:9], 0
	s_cbranch_scc1 .Latt_nd0_3
	s_sub_i32 s100, s11, 1
	s_cmp_eq_u32 s11, 0
	s_cselect_b32 s100, 2, s100
	s_lshl_b32 s101, s100, 14
	s_add_i32 m0, s40, s101
	s_nop 0
	global_load_lds_dwordx4 v178, s[34:35]
.Latt_nd0_3:
	s_waitcnt lgkmcnt(8)
	v_mfma_f32_32x32x16_bf16 v[80:95], v[210:213], v[242:245], v[80:95]
	ds_read_b64_tr_b16 v[210:211], v221 offset:16640
	ds_read_b64_tr_b16 v[212:213], v221 offset:20736
	s_waitcnt lgkmcnt(8)
	v_mfma_f32_32x32x16_bf16 v[64:79], v[128:131], v[242:245], v[64:79]
	ds_read_b64_tr_b16 v[222:223], v205 offset:24576
	ds_read_b64_tr_b16 v[224:225], v205 offset:28672
	s_cmp_lg_u64 s[8:9], 0
	s_cbranch_scc1 .Latt_nd1_3
	s_add_i32 m0, m0, 0x400
	s_nop 0
	global_load_lds_dwordx4 v180, s[34:35]
.Latt_nd1_3:
	s_waitcnt lgkmcnt(8)
	v_mfma_f32_32x32x16_bf16 v[48:63], v[214:217], v[242:245], v[48:63]
	ds_read_b64_tr_b16 v[214:215], v218 offset:24576
	ds_read_b64_tr_b16 v[216:217], v218 offset:28672
	s_waitcnt lgkmcnt(8)
	v_mfma_f32_32x32x16_bf16 v[32:47], v[238:241], v[242:245], v[32:47]
	ds_read_b64_tr_b16 v[238:239], v219 offset:24576
	ds_read_b64_tr_b16 v[240:241], v219 offset:28672
	s_cmp_lg_u64 s[8:9], 0
	s_cbranch_scc1 .Latt_nd2_3
	s_lshl_b32 s101, s100, 15
	s_add_i32 m0, s41, s101
	s_add_u32 s100, s34, 0xf00
	s_addc_u32 s101, s35, 0
	global_load_lds_dwordx4 v182, s[100:101]
.Latt_nd2_3:
	s_waitcnt lgkmcnt(8)
	v_mfma_f32_32x32x16_bf16 v[16:31], v[206:209], v[242:245], v[16:31]
	ds_read_b64_tr_b16 v[206:207], v221 offset:24576
	ds_read_b64_tr_b16 v[208:209], v221 offset:28672
	s_waitcnt lgkmcnt(8)
	v_mfma_f32_32x32x16_bf16 v[0:15], v[210:213], v[242:245], v[0:15]
	ds_read_b64_tr_b16 v[210:211], v205 offset:24832
	ds_read_b64_tr_b16 v[212:213], v205 offset:28928
	s_cmp_lg_u64 s[8:9], 0
	s_cbranch_scc1 .Latt_nd3_3
	s_add_i32 m0, m0, 0x400
	s_nop 0
	global_load_lds_dwordx4 v184, s[100:101]
.Latt_nd3_3:
	s_waitcnt lgkmcnt(8)
	v_mfma_f32_32x32x16_bf16 v[112:127], v[222:225], v[250:253], v[112:127]
	ds_read_b64_tr_b16 v[222:223], v218 offset:24832
	ds_read_b64_tr_b16 v[224:225], v218 offset:28928
	s_waitcnt lgkmcnt(8)
	v_mfma_f32_32x32x16_bf16 v[96:111], v[214:217], v[250:253], v[96:111]
	ds_read_b64_tr_b16 v[214:215], v219 offset:24832
	ds_read_b64_tr_b16 v[216:217], v219 offset:28928
	s_cmp_lg_u64 s[8:9], 0
	s_cbranch_scc1 .Latt_nd4_3
	s_add_i32 m0, m0, 0x400
	s_nop 0
	global_load_lds_dwordx4 v186, s[100:101]
.Latt_nd4_3:
	s_waitcnt lgkmcnt(8)
	v_mfma_f32_32x32x16_bf16 v[80:95], v[238:241], v[250:253], v[80:95]
	ds_read_b64_tr_b16 v[238:239], v221 offset:24832
	ds_read_b64_tr_b16 v[240:241], v221 offset:28928
	s_waitcnt lgkmcnt(8)
	v_mfma_f32_32x32x16_bf16 v[64:79], v[206:209], v[250:253], v[64:79]
	s_cmp_lg_u64 s[8:9], 0
	s_cbranch_scc1 .Latt_nd5_3
	s_add_i32 m0, m0, 0x400
	s_nop 0
	global_load_lds_dwordx4 v188, s[100:101]

.LBB0_1801:
	s_cmp_gt_i32 s39, s72
	s_cbranch_scc1 .LBB0_1812
	s_add_i32 s100, s39, 63
	s_cmp_le_i32 s100, s71
	s_cbranch_scc0 .Latt_slow_4
	s_lshl_b32 s98, s76, 14
	s_lshl_b32 s99, s76, 15
	s_add_i32 s99, s99, 0xc000
	v_add_u32_e32 v206, s98, v194
	ds_read_b128 v[206:209], v206
	v_add_u32_e32 v210, s98, v195
	ds_read_b128 v[210:213], v210
	v_add_u32_e32 v214, s98, v196
	ds_read_b128 v[214:217], v214
	v_add_u32_e32 v238, s98, v197
	ds_read_b128 v[238:241], v238
	v_add_u32_e32 v242, s98, v198
	ds_read_b128 v[242:245], v242
	v_add_u32_e32 v250, s98, v199
	ds_read_b128 v[250:253], v250
	v_add_u32_e32 v222, s98, v200
	ds_read_b128 v[222:225], v222
	v_add_u32_e32 v226, s98, v201
	ds_read_b128 v[226:229], v226
	v_bfe_u32 v246, v203, 2, 2
	v_bfe_u32 v247, v203, 5, 1
	v_lshl_or_b32 v247, v247, 2, v246
	v_and_b32_e32 v249, 3, v203
	v_and_b32_e32 v254, 16, v203
	v_lshl_or_b32 v249, v249, 2, v254
	v_lshlrev_b32_e32 v249, 1, v249
	v_lshl_add_u32 v247, v247, 9, v249
	v_add_u32_e32 v247, s99, v247
	v_lshlrev_b32_e32 v246, 6, v246
	v_add_u32_e32 v205, v247, v246
	v_xor_b32_e32 v249, 64, v246
	v_add_u32_e32 v218, v247, v249
	v_xor_b32_e32 v249, 0x80, v246
	v_add_u32_e32 v219, v247, v249
	v_xor_b32_e32 v249, 0xc0, v246
	v_add_u32_e32 v221, v247, v249
	s_waitcnt lgkmcnt(7)
	v_mfma_f32_32x32x16_bf16 v[128:143], v[206:209], v[144:147], 0
	v_add_u32_e32 v206, s98, v194
	ds_read_b128 v[206:209], v206 offset:8192
	s_waitcnt lgkmcnt(7)
	v_mfma_f32_32x32x16_bf16 v[128:143], v[210:213], v[148:151], v[128:143]
	v_add_u32_e32 v210, s98, v195
	ds_read_b128 v[210:213], v210 offset:8192
	s_waitcnt lgkmcnt(7)
	v_mfma_f32_32x32x16_bf16 v[128:143], v[214:217], v[152:155], v[128:143]
	v_add_u32_e32 v214, s98, v196
	ds_read_b128 v[214:217], v214 offset:8192
	s_waitcnt lgkmcnt(7)
	v_mfma_f32_32x32x16_bf16 v[128:143], v[238:241], v[156:159], v[128:143]
	v_add_u32_e32 v238, s98, v197
	ds_read_b128 v[238:241], v238 offset:8192
	s_waitcnt lgkmcnt(7)
	v_mfma_f32_32x32x16_bf16 v[128:143], v[242:245], v[160:163], v[128:143]
	v_add_u32_e32 v242, s98, v198
	ds_read_b128 v[242:245], v242 offset:8192
	s_waitcnt lgkmcnt(7)
	v_mfma_f32_32x32x16_bf16 v[128:143], v[250:253], v[164:167], v[128:143]
	v_add_u32_e32 v250, s98, v199
	ds_read_b128 v[250:253], v250 offset:8192
	s_waitcnt lgkmcnt(7)
	v_mfma_f32_32x32x16_bf16 v[128:143], v[222:225], v[168:171], v[128:143]
	s_waitcnt lgkmcnt(6)
	v_mfma_f32_32x32x16_bf16 v[128:143], v[226:229], v[172:175], v[128:143]
	s_waitcnt lgkmcnt(5)
	v_mfma_f32_32x32x16_bf16 v[222:237], v[206:209], v[144:147], 0
	v_add_u32_e32 v206, s98, v200
	ds_read_b128 v[206:209], v206 offset:8192
	s_nop 7
	v_max3_f32 v246, v128, v129, v130
	v_max3_f32 v247, v131, v132, v133
	v_max3_f32 v246, v246, v134, v135
	v_max3_f32 v247, v247, v136, v137
	v_max3_f32 v246, v246, v138, v139
	v_max3_f32 v247, v247, v140, v141
	v_max3_f32 v246, v246, v142, v143
	s_waitcnt lgkmcnt(5)
	v_mfma_f32_32x32x16_bf16 v[222:237], v[210:213], v[148:151], v[222:237]
	v_add_u32_e32 v210, s98, v201
	ds_read_b128 v[210:213], v210 offset:8192
	v_max_f32_e32 v246, v246, v247
	v_mov_b32_e32 v247, v246
	v_add_f32_e32 v249, 0x41000000, v190
	s_nop 1
	v_permlane32_swap_b32_e32 v246, v247
	v_max_f32_e32 v246, v246, v247
	v_cmp_gt_f32_e32 vcc, v246, v249
	s_cbranch_vccz .Latt_nr0_4
	v_max_f32_e32 v246, v190, v246
	v_sub_f32_e32 v190, v190, v246
	v_exp_f32_e32 v190, v190
	s_nop 0
	v_pk_mul_f32 v[126:127], v[126:127], v[190:191] op_sel_hi:[1,0]
	v_pk_mul_f32 v[124:125], v[124:125], v[190:191] op_sel_hi:[1,0]
	v_pk_mul_f32 v[122:123], v[122:123], v[190:191] op_sel_hi:[1,0]
	v_pk_mul_f32 v[120:121], v[120:121], v[190:191] op_sel_hi:[1,0]
	v_pk_mul_f32 v[118:119], v[118:119], v[190:191] op_sel_hi:[1,0]
	v_pk_mul_f32 v[116:117], v[116:117], v[190:191] op_sel_hi:[1,0]
	v_pk_mul_f32 v[114:115], v[114:115], v[190:191] op_sel_hi:[1,0]
	v_pk_mul_f32 v[112:113], v[112:113], v[190:191] op_sel_hi:[1,0]
	v_pk_mul_f32 v[110:111], v[110:111], v[190:191] op_sel_hi:[1,0]
	v_pk_mul_f32 v[108:109], v[108:109], v[190:191] op_sel_hi:[1,0]
	v_pk_mul_f32 v[106:107], v[106:107], v[190:191] op_sel_hi:[1,0]
	v_pk_mul_f32 v[104:105], v[104:105], v[190:191] op_sel_hi:[1,0]
	v_pk_mul_f32 v[102:103], v[102:103], v[190:191] op_sel_hi:[1,0]
	v_pk_mul_f32 v[100:101], v[100:101], v[190:191] op_sel_hi:[1,0]
	v_pk_mul_f32 v[98:99], v[98:99], v[190:191] op_sel_hi:[1,0]
	v_pk_mul_f32 v[96:97], v[96:97], v[190:191] op_sel_hi:[1,0]
	v_pk_mul_f32 v[94:95], v[94:95], v[190:191] op_sel_hi:[1,0]
	v_pk_mul_f32 v[92:93], v[92:93], v[190:191] op_sel_hi:[1,0]
	v_pk_mul_f32 v[90:91], v[90:91], v[190:191] op_sel_hi:[1,0]
	v_pk_mul_f32 v[88:89], v[88:89], v[190:191] op_sel_hi:[1,0]
	v_pk_mul_f32 v[86:87], v[86:87], v[190:191] op_sel_hi:[1,0]
	v_pk_mul_f32 v[84:85], v[84:85], v[190:191] op_sel_hi:[1,0]
	v_pk_mul_f32 v[82:83], v[82:83], v[190:191] op_sel_hi:[1,0]
	v_pk_mul_f32 v[80:81], v[80:81], v[190:191] op_sel_hi:[1,0]
	v_pk_mul_f32 v[78:79], v[78:79], v[190:191] op_sel_hi:[1,0]
	v_pk_mul_f32 v[76:77], v[76:77], v[190:191] op_sel_hi:[1,0]
	v_pk_mul_f32 v[74:75], v[74:75], v[190:191] op_sel_hi:[1,0]
	v_pk_mul_f32 v[72:73], v[72:73], v[190:191] op_sel_hi:[1,0]
	v_pk_mul_f32 v[70:71], v[70:71], v[190:191] op_sel_hi:[1,0]
	v_pk_mul_f32 v[68:69], v[68:69], v[190:191] op_sel_hi:[1,0]
	v_pk_mul_f32 v[66:67], v[66:67], v[190:191] op_sel_hi:[1,0]
	v_pk_mul_f32 v[64:65], v[64:65], v[190:191] op_sel_hi:[1,0]
	v_pk_mul_f32 v[62:63], v[62:63], v[190:191] op_sel_hi:[1,0]
	v_pk_mul_f32 v[60:61], v[60:61], v[190:191] op_sel_hi:[1,0]
	v_pk_mul_f32 v[58:59], v[58:59], v[190:191] op_sel_hi:[1,0]
	v_pk_mul_f32 v[56:57], v[56:57], v[190:191] op_sel_hi:[1,0]
	v_pk_mul_f32 v[54:55], v[54:55], v[190:191] op_sel_hi:[1,0]
	v_pk_mul_f32 v[52:53], v[52:53], v[190:191] op_sel_hi:[1,0]
	v_pk_mul_f32 v[50:51], v[50:51], v[190:191] op_sel_hi:[1,0]
	v_pk_mul_f32 v[48:49], v[48:49], v[190:191] op_sel_hi:[1,0]
	v_pk_mul_f32 v[46:47], v[46:47], v[190:191] op_sel_hi:[1,0]
	v_pk_mul_f32 v[44:45], v[44:45], v[190:191] op_sel_hi:[1,0]
	v_pk_mul_f32 v[42:43], v[42:43], v[190:191] op_sel_hi:[1,0]
	v_pk_mul_f32 v[40:41], v[40:41], v[190:191] op_sel_hi:[1,0]
	v_pk_mul_f32 v[38:39], v[38:39], v[190:191] op_sel_hi:[1,0]
	v_pk_mul_f32 v[36:37], v[36:37], v[190:191] op_sel_hi:[1,0]
	v_pk_mul_f32 v[34:35], v[34:35], v[190:191] op_sel_hi:[1,0]
	v_pk_mul_f32 v[32:33], v[32:33], v[190:191] op_sel_hi:[1,0]
	v_pk_mul_f32 v[30:31], v[30:31], v[190:191] op_sel_hi:[1,0]
	v_pk_mul_f32 v[28:29], v[28:29], v[190:191] op_sel_hi:[1,0]
	v_pk_mul_f32 v[26:27], v[26:27], v[190:191] op_sel_hi:[1,0]
	v_pk_mul_f32 v[24:25], v[24:25], v[190:191] op_sel_hi:[1,0]
	v_pk_mul_f32 v[22:23], v[22:23], v[190:191] op_sel_hi:[1,0]
	v_pk_mul_f32 v[20:21], v[20:21], v[190:191] op_sel_hi:[1,0]
	v_pk_mul_f32 v[18:19], v[18:19], v[190:191] op_sel_hi:[1,0]
	v_pk_mul_f32 v[16:17], v[16:17], v[190:191] op_sel_hi:[1,0]
	v_pk_mul_f32 v[14:15], v[14:15], v[190:191] op_sel_hi:[1,0]
	v_pk_mul_f32 v[12:13], v[12:13], v[190:191] op_sel_hi:[1,0]
	v_pk_mul_f32 v[10:11], v[10:11], v[190:191] op_sel_hi:[1,0]
	v_pk_mul_f32 v[8:9], v[8:9], v[190:191] op_sel_hi:[1,0]
	v_pk_mul_f32 v[6:7], v[6:7], v[190:191] op_sel_hi:[1,0]
	v_pk_mul_f32 v[4:5], v[4:5], v[190:191] op_sel_hi:[1,0]
	v_pk_mul_f32 v[2:3], v[2:3], v[190:191] op_sel_hi:[1,0]
	v_pk_mul_f32 v[0:1], v[0:1], v[190:191] op_sel_hi:[1,0]
	v_mul_f32_e32 v202, v202, v190
	v_mov_b32_e32 v190, v246

.Latt_pv1_4:
	s_waitcnt lgkmcnt(8)
	v_mfma_f32_32x32x16_bf16 v[112:127], v[238:241], v[242:245], v[112:127]
	ds_read_b64_tr_b16 v[238:239], v218 offset:16640
	ds_read_b64_tr_b16 v[240:241], v218 offset:20736
	s_waitcnt lgkmcnt(8)
	v_mfma_f32_32x32x16_bf16 v[96:111], v[206:209], v[242:245], v[96:111]
	ds_read_b64_tr_b16 v[206:207], v219 offset:16640
	ds_read_b64_tr_b16 v[208:209], v219 offset:20736
	s_cmp_lg_u64 s[18:19], 0
	s_cbranch_scc1 .Latt_nd0_4
	s_sub_i32 s100, s76, 1
	s_cmp_eq_u32 s76, 0
	s_cselect_b32 s100, 2, s100
	s_lshl_b32 s101, s100, 14
	s_add_i32 m0, s73, s101
	s_nop 0
	global_load_lds_dwordx4 v178, s[14:15]

.Latt_nd1_4:
	s_waitcnt lgkmcnt(8)
	v_mfma_f32_32x32x16_bf16 v[48:63], v[214:217], v[242:245], v[48:63]
	ds_read_b64_tr_b16 v[214:215], v218 offset:24576
	ds_read_b64_tr_b16 v[216:217], v218 offset:28672
	s_waitcnt lgkmcnt(8)
	v_mfma_f32_32x32x16_bf16 v[32:47], v[238:241], v[242:245], v[32:47]
	ds_read_b64_tr_b16 v[238:239], v219 offset:24576
	ds_read_b64_tr_b16 v[240:241], v219 offset:28672
	s_cmp_lg_u64 s[18:19], 0
	s_cbranch_scc1 .Latt_nd2_4
	s_lshl_b32 s101, s100, 15
	s_add_i32 m0, s74, s101
	s_add_u32 s100, s14, 0x1000
	s_addc_u32 s101, s15, 0
	global_load_lds_dwordx4 v182, s[100:101]

.LBB0_1820:
	s_cmp_gt_i32 s4, s72
	s_cbranch_scc1 .LBB0_1831
	s_add_i32 s100, s4, 63
	s_cmp_le_i32 s100, s71
	s_cbranch_scc0 .Latt_slow_5
	s_lshl_b32 s98, s33, 14
	s_lshl_b32 s99, s33, 15
	s_add_i32 s99, s99, 0xc000
	v_add_u32_e32 v206, s98, v196
	ds_read_b128 v[206:209], v206
	v_add_u32_e32 v210, s98, v197
	ds_read_b128 v[210:213], v210
	v_add_u32_e32 v214, s98, v198
	ds_read_b128 v[214:217], v214
	v_add_u32_e32 v238, s98, v199
	ds_read_b128 v[238:241], v238
	v_add_u32_e32 v242, s98, v200
	ds_read_b128 v[242:245], v242
	v_add_u32_e32 v250, s98, v201
	ds_read_b128 v[250:253], v250
	v_add_u32_e32 v222, s98, v202
	ds_read_b128 v[222:225], v222
	v_add_u32_e32 v226, s98, v203
	ds_read_b128 v[226:229], v226
	v_bfe_u32 v246, v204, 2, 2
	v_bfe_u32 v247, v204, 5, 1
	v_lshl_or_b32 v247, v247, 2, v246
	v_and_b32_e32 v249, 3, v204
	v_and_b32_e32 v254, 16, v204
	v_lshl_or_b32 v249, v249, 2, v254
	v_lshlrev_b32_e32 v249, 1, v249
	v_lshl_add_u32 v247, v247, 9, v249
	v_add_u32_e32 v247, s99, v247
	v_lshlrev_b32_e32 v246, 6, v246
	v_add_u32_e32 v205, v247, v246
	v_xor_b32_e32 v249, 64, v246
	v_add_u32_e32 v218, v247, v249
	v_xor_b32_e32 v249, 0x80, v246
	v_add_u32_e32 v219, v247, v249
	v_xor_b32_e32 v249, 0xc0, v246
	v_add_u32_e32 v221, v247, v249
	s_waitcnt lgkmcnt(7)
	v_mfma_f32_32x32x16_bf16 v[128:143], v[206:209], v[144:147], 0
	v_add_u32_e32 v206, s98, v196
	ds_read_b128 v[206:209], v206 offset:8192
	s_waitcnt lgkmcnt(7)
	v_mfma_f32_32x32x16_bf16 v[128:143], v[210:213], v[148:151], v[128:143]
	v_add_u32_e32 v210, s98, v197
	ds_read_b128 v[210:213], v210 offset:8192
	s_waitcnt lgkmcnt(7)
	v_mfma_f32_32x32x16_bf16 v[128:143], v[214:217], v[152:155], v[128:143]
	v_add_u32_e32 v214, s98, v198
	ds_read_b128 v[214:217], v214 offset:8192
	s_waitcnt lgkmcnt(7)
	v_mfma_f32_32x32x16_bf16 v[128:143], v[238:241], v[156:159], v[128:143]
	v_add_u32_e32 v238, s98, v199
	ds_read_b128 v[238:241], v238 offset:8192
	s_waitcnt lgkmcnt(7)
	v_mfma_f32_32x32x16_bf16 v[128:143], v[242:245], v[160:163], v[128:143]
	v_add_u32_e32 v242, s98, v200
	ds_read_b128 v[242:245], v242 offset:8192
	s_waitcnt lgkmcnt(7)
	v_mfma_f32_32x32x16_bf16 v[128:143], v[250:253], v[164:167], v[128:143]
	v_add_u32_e32 v250, s98, v201
	ds_read_b128 v[250:253], v250 offset:8192
	s_waitcnt lgkmcnt(7)
	v_mfma_f32_32x32x16_bf16 v[128:143], v[222:225], v[168:171], v[128:143]
	s_waitcnt lgkmcnt(6)
	v_mfma_f32_32x32x16_bf16 v[128:143], v[226:229], v[172:175], v[128:143]
	s_waitcnt lgkmcnt(5)
	v_mfma_f32_32x32x16_bf16 v[222:237], v[206:209], v[144:147], 0
	v_add_u32_e32 v206, s98, v202
	ds_read_b128 v[206:209], v206 offset:8192
	s_nop 7
	v_max3_f32 v246, v128, v129, v130
	v_max3_f32 v247, v131, v132, v133
	v_max3_f32 v246, v246, v134, v135
	v_max3_f32 v247, v247, v136, v137
	v_max3_f32 v246, v246, v138, v139
	v_max3_f32 v247, v247, v140, v141
	v_max3_f32 v246, v246, v142, v143
	s_waitcnt lgkmcnt(5)
	v_mfma_f32_32x32x16_bf16 v[222:237], v[210:213], v[148:151], v[222:237]
	v_add_u32_e32 v210, s98, v203
	ds_read_b128 v[210:213], v210 offset:8192
	v_max_f32_e32 v246, v246, v247
	v_mov_b32_e32 v247, v246
	v_add_f32_e32 v249, 0x41000000, v190
	s_nop 1
	v_permlane32_swap_b32_e32 v246, v247
	v_max_f32_e32 v246, v246, v247
	v_cmp_gt_f32_e32 vcc, v246, v249
	s_cbranch_vccz .Latt_nr0_5
	v_max_f32_e32 v246, v190, v246
	v_sub_f32_e32 v190, v190, v246
	v_exp_f32_e32 v190, v190
	s_nop 0
	v_pk_mul_f32 v[126:127], v[126:127], v[190:191] op_sel_hi:[1,0]
	v_pk_mul_f32 v[124:125], v[124:125], v[190:191] op_sel_hi:[1,0]
	v_pk_mul_f32 v[122:123], v[122:123], v[190:191] op_sel_hi:[1,0]
	v_pk_mul_f32 v[120:121], v[120:121], v[190:191] op_sel_hi:[1,0]
	v_pk_mul_f32 v[118:119], v[118:119], v[190:191] op_sel_hi:[1,0]
	v_pk_mul_f32 v[116:117], v[116:117], v[190:191] op_sel_hi:[1,0]
	v_pk_mul_f32 v[114:115], v[114:115], v[190:191] op_sel_hi:[1,0]
	v_pk_mul_f32 v[112:113], v[112:113], v[190:191] op_sel_hi:[1,0]
	v_pk_mul_f32 v[110:111], v[110:111], v[190:191] op_sel_hi:[1,0]
	v_pk_mul_f32 v[108:109], v[108:109], v[190:191] op_sel_hi:[1,0]
	v_pk_mul_f32 v[106:107], v[106:107], v[190:191] op_sel_hi:[1,0]
	v_pk_mul_f32 v[104:105], v[104:105], v[190:191] op_sel_hi:[1,0]
	v_pk_mul_f32 v[102:103], v[102:103], v[190:191] op_sel_hi:[1,0]
	v_pk_mul_f32 v[100:101], v[100:101], v[190:191] op_sel_hi:[1,0]
	v_pk_mul_f32 v[98:99], v[98:99], v[190:191] op_sel_hi:[1,0]
	v_pk_mul_f32 v[96:97], v[96:97], v[190:191] op_sel_hi:[1,0]
	v_pk_mul_f32 v[94:95], v[94:95], v[190:191] op_sel_hi:[1,0]
	v_pk_mul_f32 v[92:93], v[92:93], v[190:191] op_sel_hi:[1,0]
	v_pk_mul_f32 v[90:91], v[90:91], v[190:191] op_sel_hi:[1,0]
	v_pk_mul_f32 v[88:89], v[88:89], v[190:191] op_sel_hi:[1,0]
	v_pk_mul_f32 v[86:87], v[86:87], v[190:191] op_sel_hi:[1,0]
	v_pk_mul_f32 v[84:85], v[84:85], v[190:191] op_sel_hi:[1,0]
	v_pk_mul_f32 v[82:83], v[82:83], v[190:191] op_sel_hi:[1,0]
	v_pk_mul_f32 v[80:81], v[80:81], v[190:191] op_sel_hi:[1,0]
	v_pk_mul_f32 v[78:79], v[78:79], v[190:191] op_sel_hi:[1,0]
	v_pk_mul_f32 v[76:77], v[76:77], v[190:191] op_sel_hi:[1,0]
	v_pk_mul_f32 v[74:75], v[74:75], v[190:191] op_sel_hi:[1,0]
	v_pk_mul_f32 v[72:73], v[72:73], v[190:191] op_sel_hi:[1,0]
	v_pk_mul_f32 v[70:71], v[70:71], v[190:191] op_sel_hi:[1,0]
	v_pk_mul_f32 v[68:69], v[68:69], v[190:191] op_sel_hi:[1,0]
	v_pk_mul_f32 v[66:67], v[66:67], v[190:191] op_sel_hi:[1,0]
	v_pk_mul_f32 v[64:65], v[64:65], v[190:191] op_sel_hi:[1,0]
	v_pk_mul_f32 v[62:63], v[62:63], v[190:191] op_sel_hi:[1,0]
	v_pk_mul_f32 v[60:61], v[60:61], v[190:191] op_sel_hi:[1,0]
	v_pk_mul_f32 v[58:59], v[58:59], v[190:191] op_sel_hi:[1,0]
	v_pk_mul_f32 v[56:57], v[56:57], v[190:191] op_sel_hi:[1,0]
	v_pk_mul_f32 v[54:55], v[54:55], v[190:191] op_sel_hi:[1,0]
	v_pk_mul_f32 v[52:53], v[52:53], v[190:191] op_sel_hi:[1,0]
	v_pk_mul_f32 v[50:51], v[50:51], v[190:191] op_sel_hi:[1,0]
	v_pk_mul_f32 v[48:49], v[48:49], v[190:191] op_sel_hi:[1,0]
	v_pk_mul_f32 v[46:47], v[46:47], v[190:191] op_sel_hi:[1,0]
	v_pk_mul_f32 v[44:45], v[44:45], v[190:191] op_sel_hi:[1,0]
	v_pk_mul_f32 v[42:43], v[42:43], v[190:191] op_sel_hi:[1,0]
	v_pk_mul_f32 v[40:41], v[40:41], v[190:191] op_sel_hi:[1,0]
	v_pk_mul_f32 v[38:39], v[38:39], v[190:191] op_sel_hi:[1,0]
	v_pk_mul_f32 v[36:37], v[36:37], v[190:191] op_sel_hi:[1,0]
	v_pk_mul_f32 v[34:35], v[34:35], v[190:191] op_sel_hi:[1,0]
	v_pk_mul_f32 v[32:33], v[32:33], v[190:191] op_sel_hi:[1,0]
	v_pk_mul_f32 v[30:31], v[30:31], v[190:191] op_sel_hi:[1,0]
	v_pk_mul_f32 v[28:29], v[28:29], v[190:191] op_sel_hi:[1,0]
	v_pk_mul_f32 v[26:27], v[26:27], v[190:191] op_sel_hi:[1,0]
	v_pk_mul_f32 v[24:25], v[24:25], v[190:191] op_sel_hi:[1,0]
	v_pk_mul_f32 v[22:23], v[22:23], v[190:191] op_sel_hi:[1,0]
	v_pk_mul_f32 v[20:21], v[20:21], v[190:191] op_sel_hi:[1,0]
	v_pk_mul_f32 v[18:19], v[18:19], v[190:191] op_sel_hi:[1,0]
	v_pk_mul_f32 v[16:17], v[16:17], v[190:191] op_sel_hi:[1,0]
	v_pk_mul_f32 v[14:15], v[14:15], v[190:191] op_sel_hi:[1,0]
	v_pk_mul_f32 v[12:13], v[12:13], v[190:191] op_sel_hi:[1,0]
	v_pk_mul_f32 v[10:11], v[10:11], v[190:191] op_sel_hi:[1,0]
	v_pk_mul_f32 v[8:9], v[8:9], v[190:191] op_sel_hi:[1,0]
	v_pk_mul_f32 v[6:7], v[6:7], v[190:191] op_sel_hi:[1,0]
	v_pk_mul_f32 v[4:5], v[4:5], v[190:191] op_sel_hi:[1,0]
	v_pk_mul_f32 v[2:3], v[2:3], v[190:191] op_sel_hi:[1,0]
	v_pk_mul_f32 v[0:1], v[0:1], v[190:191] op_sel_hi:[1,0]
	v_mul_f32_e32 v195, v195, v190
	v_mov_b32_e32 v190, v246

.Latt_pv1_5:
	s_waitcnt lgkmcnt(8)
	v_mfma_f32_32x32x16_bf16 v[112:127], v[238:241], v[242:245], v[112:127]
	ds_read_b64_tr_b16 v[238:239], v218 offset:16640
	ds_read_b64_tr_b16 v[240:241], v218 offset:20736
	s_waitcnt lgkmcnt(8)
	v_mfma_f32_32x32x16_bf16 v[96:111], v[206:209], v[242:245], v[96:111]
	ds_read_b64_tr_b16 v[206:207], v219 offset:16640
	ds_read_b64_tr_b16 v[208:209], v219 offset:20736
	s_cmp_lg_u64 s[18:19], 0
	s_cbranch_scc1 .Latt_nd0_5
	s_sub_i32 s100, s33, 1
	s_cmp_eq_u32 s33, 0
	s_cselect_b32 s100, 2, s100
	s_lshl_b32 s101, s100, 14
	s_add_i32 m0, s73, s101
	s_nop 0
	global_load_lds_dwordx4 v178, s[12:13]

.Latt_nd1_5:
	s_waitcnt lgkmcnt(8)
	v_mfma_f32_32x32x16_bf16 v[48:63], v[214:217], v[242:245], v[48:63]
	ds_read_b64_tr_b16 v[214:215], v218 offset:24576
	ds_read_b64_tr_b16 v[216:217], v218 offset:28672
	s_waitcnt lgkmcnt(8)
	v_mfma_f32_32x32x16_bf16 v[32:47], v[238:241], v[242:245], v[32:47]
	ds_read_b64_tr_b16 v[238:239], v219 offset:24576
	ds_read_b64_tr_b16 v[240:241], v219 offset:28672
	s_cmp_lg_u64 s[18:19], 0
	s_cbranch_scc1 .Latt_nd2_5
	s_lshl_b32 s101, s100, 15
	s_add_i32 m0, s74, s101
	s_add_u32 s100, s12, 0xf00
	s_addc_u32 s101, s13, 0
	global_load_lds_dwordx4 v182, s[100:101]

.LBB0_1839:
	s_cmp_gt_i32 s72, s69
	s_cbranch_scc1 .LBB0_1850
	s_add_i32 s100, s72, 63
	s_cmp_le_i32 s100, s68
	s_cbranch_scc0 .Latt_slow_6
	s_lshl_b32 s98, s34, 14
	s_lshl_b32 s99, s34, 15
	s_add_i32 s99, s99, 0xc000
	v_add_u32_e32 v206, s98, v195
	ds_read_b128 v[206:209], v206
	v_add_u32_e32 v210, s98, v196
	ds_read_b128 v[210:213], v210
	v_add_u32_e32 v214, s98, v197
	ds_read_b128 v[214:217], v214
	v_add_u32_e32 v238, s98, v198
	ds_read_b128 v[238:241], v238
	v_add_u32_e32 v242, s98, v199
	ds_read_b128 v[242:245], v242
	v_add_u32_e32 v250, s98, v200
	ds_read_b128 v[250:253], v250
	v_add_u32_e32 v222, s98, v201
	ds_read_b128 v[222:225], v222
	v_add_u32_e32 v226, s98, v202
	ds_read_b128 v[226:229], v226
	v_bfe_u32 v246, v204, 2, 2
	v_bfe_u32 v247, v204, 5, 1
	v_lshl_or_b32 v247, v247, 2, v246
	v_and_b32_e32 v249, 3, v204
	v_and_b32_e32 v254, 16, v204
	v_lshl_or_b32 v249, v249, 2, v254
	v_lshlrev_b32_e32 v249, 1, v249
	v_lshl_add_u32 v247, v247, 9, v249
	v_add_u32_e32 v247, s99, v247
	v_lshlrev_b32_e32 v246, 6, v246
	v_add_u32_e32 v205, v247, v246
	v_xor_b32_e32 v249, 64, v246
	v_add_u32_e32 v218, v247, v249
	v_xor_b32_e32 v249, 0x80, v246
	v_add_u32_e32 v219, v247, v249
	v_xor_b32_e32 v249, 0xc0, v246
	v_add_u32_e32 v221, v247, v249
	s_waitcnt lgkmcnt(7)
	v_mfma_f32_32x32x16_bf16 v[128:143], v[206:209], v[144:147], 0
	v_add_u32_e32 v206, s98, v195
	ds_read_b128 v[206:209], v206 offset:8192
	s_waitcnt lgkmcnt(7)
	v_mfma_f32_32x32x16_bf16 v[128:143], v[210:213], v[148:151], v[128:143]
	v_add_u32_e32 v210, s98, v196
	ds_read_b128 v[210:213], v210 offset:8192
	s_waitcnt lgkmcnt(7)
	v_mfma_f32_32x32x16_bf16 v[128:143], v[214:217], v[152:155], v[128:143]
	v_add_u32_e32 v214, s98, v197
	ds_read_b128 v[214:217], v214 offset:8192
	s_waitcnt lgkmcnt(7)
	v_mfma_f32_32x32x16_bf16 v[128:143], v[238:241], v[156:159], v[128:143]
	v_add_u32_e32 v238, s98, v198
	ds_read_b128 v[238:241], v238 offset:8192
	s_waitcnt lgkmcnt(7)
	v_mfma_f32_32x32x16_bf16 v[128:143], v[242:245], v[160:163], v[128:143]
	v_add_u32_e32 v242, s98, v199
	ds_read_b128 v[242:245], v242 offset:8192
	s_waitcnt lgkmcnt(7)
	v_mfma_f32_32x32x16_bf16 v[128:143], v[250:253], v[164:167], v[128:143]
	v_add_u32_e32 v250, s98, v200
	ds_read_b128 v[250:253], v250 offset:8192
	s_waitcnt lgkmcnt(7)
	v_mfma_f32_32x32x16_bf16 v[128:143], v[222:225], v[168:171], v[128:143]
	s_waitcnt lgkmcnt(6)
	v_mfma_f32_32x32x16_bf16 v[128:143], v[226:229], v[172:175], v[128:143]
	s_waitcnt lgkmcnt(5)
	v_mfma_f32_32x32x16_bf16 v[222:237], v[206:209], v[144:147], 0
	v_add_u32_e32 v206, s98, v201
	ds_read_b128 v[206:209], v206 offset:8192
	s_nop 7
	v_max3_f32 v246, v128, v129, v130
	v_max3_f32 v247, v131, v132, v133
	v_max3_f32 v246, v246, v134, v135
	v_max3_f32 v247, v247, v136, v137
	v_max3_f32 v246, v246, v138, v139
	v_max3_f32 v247, v247, v140, v141
	v_max3_f32 v246, v246, v142, v143
	s_waitcnt lgkmcnt(5)
	v_mfma_f32_32x32x16_bf16 v[222:237], v[210:213], v[148:151], v[222:237]
	v_add_u32_e32 v210, s98, v202
	ds_read_b128 v[210:213], v210 offset:8192
	v_max_f32_e32 v246, v246, v247
	v_mov_b32_e32 v247, v246
	v_add_f32_e32 v249, 0x41000000, v190
	s_nop 1
	v_permlane32_swap_b32_e32 v246, v247
	v_max_f32_e32 v246, v246, v247
	v_cmp_gt_f32_e32 vcc, v246, v249
	s_cbranch_vccz .Latt_nr0_6
	v_max_f32_e32 v246, v190, v246
	v_sub_f32_e32 v190, v190, v246
	v_exp_f32_e32 v190, v190
	s_nop 0
	v_pk_mul_f32 v[126:127], v[126:127], v[190:191] op_sel_hi:[1,0]
	v_pk_mul_f32 v[124:125], v[124:125], v[190:191] op_sel_hi:[1,0]
	v_pk_mul_f32 v[122:123], v[122:123], v[190:191] op_sel_hi:[1,0]
	v_pk_mul_f32 v[120:121], v[120:121], v[190:191] op_sel_hi:[1,0]
	v_pk_mul_f32 v[118:119], v[118:119], v[190:191] op_sel_hi:[1,0]
	v_pk_mul_f32 v[116:117], v[116:117], v[190:191] op_sel_hi:[1,0]
	v_pk_mul_f32 v[114:115], v[114:115], v[190:191] op_sel_hi:[1,0]
	v_pk_mul_f32 v[112:113], v[112:113], v[190:191] op_sel_hi:[1,0]
	v_pk_mul_f32 v[110:111], v[110:111], v[190:191] op_sel_hi:[1,0]
	v_pk_mul_f32 v[108:109], v[108:109], v[190:191] op_sel_hi:[1,0]
	v_pk_mul_f32 v[106:107], v[106:107], v[190:191] op_sel_hi:[1,0]
	v_pk_mul_f32 v[104:105], v[104:105], v[190:191] op_sel_hi:[1,0]
	v_pk_mul_f32 v[102:103], v[102:103], v[190:191] op_sel_hi:[1,0]
	v_pk_mul_f32 v[100:101], v[100:101], v[190:191] op_sel_hi:[1,0]
	v_pk_mul_f32 v[98:99], v[98:99], v[190:191] op_sel_hi:[1,0]
	v_pk_mul_f32 v[96:97], v[96:97], v[190:191] op_sel_hi:[1,0]
	v_pk_mul_f32 v[94:95], v[94:95], v[190:191] op_sel_hi:[1,0]
	v_pk_mul_f32 v[92:93], v[92:93], v[190:191] op_sel_hi:[1,0]
	v_pk_mul_f32 v[90:91], v[90:91], v[190:191] op_sel_hi:[1,0]
	v_pk_mul_f32 v[88:89], v[88:89], v[190:191] op_sel_hi:[1,0]
	v_pk_mul_f32 v[86:87], v[86:87], v[190:191] op_sel_hi:[1,0]
	v_pk_mul_f32 v[84:85], v[84:85], v[190:191] op_sel_hi:[1,0]
	v_pk_mul_f32 v[82:83], v[82:83], v[190:191] op_sel_hi:[1,0]
	v_pk_mul_f32 v[80:81], v[80:81], v[190:191] op_sel_hi:[1,0]
	v_pk_mul_f32 v[78:79], v[78:79], v[190:191] op_sel_hi:[1,0]
	v_pk_mul_f32 v[76:77], v[76:77], v[190:191] op_sel_hi:[1,0]
	v_pk_mul_f32 v[74:75], v[74:75], v[190:191] op_sel_hi:[1,0]
	v_pk_mul_f32 v[72:73], v[72:73], v[190:191] op_sel_hi:[1,0]
	v_pk_mul_f32 v[70:71], v[70:71], v[190:191] op_sel_hi:[1,0]
	v_pk_mul_f32 v[68:69], v[68:69], v[190:191] op_sel_hi:[1,0]
	v_pk_mul_f32 v[66:67], v[66:67], v[190:191] op_sel_hi:[1,0]
	v_pk_mul_f32 v[64:65], v[64:65], v[190:191] op_sel_hi:[1,0]
	v_pk_mul_f32 v[62:63], v[62:63], v[190:191] op_sel_hi:[1,0]
	v_pk_mul_f32 v[60:61], v[60:61], v[190:191] op_sel_hi:[1,0]
	v_pk_mul_f32 v[58:59], v[58:59], v[190:191] op_sel_hi:[1,0]
	v_pk_mul_f32 v[56:57], v[56:57], v[190:191] op_sel_hi:[1,0]
	v_pk_mul_f32 v[54:55], v[54:55], v[190:191] op_sel_hi:[1,0]
	v_pk_mul_f32 v[52:53], v[52:53], v[190:191] op_sel_hi:[1,0]
	v_pk_mul_f32 v[50:51], v[50:51], v[190:191] op_sel_hi:[1,0]
	v_pk_mul_f32 v[48:49], v[48:49], v[190:191] op_sel_hi:[1,0]
	v_pk_mul_f32 v[46:47], v[46:47], v[190:191] op_sel_hi:[1,0]
	v_pk_mul_f32 v[44:45], v[44:45], v[190:191] op_sel_hi:[1,0]
	v_pk_mul_f32 v[42:43], v[42:43], v[190:191] op_sel_hi:[1,0]
	v_pk_mul_f32 v[40:41], v[40:41], v[190:191] op_sel_hi:[1,0]
	v_pk_mul_f32 v[38:39], v[38:39], v[190:191] op_sel_hi:[1,0]
	v_pk_mul_f32 v[36:37], v[36:37], v[190:191] op_sel_hi:[1,0]
	v_pk_mul_f32 v[34:35], v[34:35], v[190:191] op_sel_hi:[1,0]
	v_pk_mul_f32 v[32:33], v[32:33], v[190:191] op_sel_hi:[1,0]
	v_pk_mul_f32 v[30:31], v[30:31], v[190:191] op_sel_hi:[1,0]
	v_pk_mul_f32 v[28:29], v[28:29], v[190:191] op_sel_hi:[1,0]
	v_pk_mul_f32 v[26:27], v[26:27], v[190:191] op_sel_hi:[1,0]
	v_pk_mul_f32 v[24:25], v[24:25], v[190:191] op_sel_hi:[1,0]
	v_pk_mul_f32 v[22:23], v[22:23], v[190:191] op_sel_hi:[1,0]
	v_pk_mul_f32 v[20:21], v[20:21], v[190:191] op_sel_hi:[1,0]
	v_pk_mul_f32 v[18:19], v[18:19], v[190:191] op_sel_hi:[1,0]
	v_pk_mul_f32 v[16:17], v[16:17], v[190:191] op_sel_hi:[1,0]
	v_pk_mul_f32 v[14:15], v[14:15], v[190:191] op_sel_hi:[1,0]
	v_pk_mul_f32 v[12:13], v[12:13], v[190:191] op_sel_hi:[1,0]
	v_pk_mul_f32 v[10:11], v[10:11], v[190:191] op_sel_hi:[1,0]
	v_pk_mul_f32 v[8:9], v[8:9], v[190:191] op_sel_hi:[1,0]
	v_pk_mul_f32 v[6:7], v[6:7], v[190:191] op_sel_hi:[1,0]
	v_pk_mul_f32 v[4:5], v[4:5], v[190:191] op_sel_hi:[1,0]
	v_pk_mul_f32 v[2:3], v[2:3], v[190:191] op_sel_hi:[1,0]
	v_pk_mul_f32 v[0:1], v[0:1], v[190:191] op_sel_hi:[1,0]
	v_mul_f32_e32 v203, v203, v190
	v_mov_b32_e32 v190, v246

.Latt_pv1_6:
	s_waitcnt lgkmcnt(8)
	v_mfma_f32_32x32x16_bf16 v[112:127], v[238:241], v[242:245], v[112:127]
	ds_read_b64_tr_b16 v[238:239], v218 offset:16640
	ds_read_b64_tr_b16 v[240:241], v218 offset:20736
	s_waitcnt lgkmcnt(8)
	v_mfma_f32_32x32x16_bf16 v[96:111], v[206:209], v[242:245], v[96:111]
	ds_read_b64_tr_b16 v[206:207], v219 offset:16640
	ds_read_b64_tr_b16 v[208:209], v219 offset:20736
	s_cmp_lg_u64 s[12:13], 0
	s_cbranch_scc1 .Latt_nd0_6
	s_sub_i32 s100, s34, 1
	s_cmp_eq_u32 s34, 0
	s_cselect_b32 s100, 2, s100
	s_lshl_b32 s101, s100, 14
	s_add_i32 m0, s36, s101
	s_nop 0
	global_load_lds_dwordx4 v178, s[20:21]
.Latt_nd0_6:
	s_waitcnt lgkmcnt(8)
	v_mfma_f32_32x32x16_bf16 v[80:95], v[210:213], v[242:245], v[80:95]
	ds_read_b64_tr_b16 v[210:211], v221 offset:16640
	ds_read_b64_tr_b16 v[212:213], v221 offset:20736
	s_waitcnt lgkmcnt(8)
	v_mfma_f32_32x32x16_bf16 v[64:79], v[128:131], v[242:245], v[64:79]
	ds_read_b64_tr_b16 v[222:223], v205 offset:24576
	ds_read_b64_tr_b16 v[224:225], v205 offset:28672
	s_cmp_lg_u64 s[12:13], 0
	s_cbranch_scc1 .Latt_nd1_6
	s_add_i32 m0, m0, 0x400
	s_nop 0
	global_load_lds_dwordx4 v180, s[20:21]
.Latt_nd1_6:
	s_waitcnt lgkmcnt(8)
	v_mfma_f32_32x32x16_bf16 v[48:63], v[214:217], v[242:245], v[48:63]
	ds_read_b64_tr_b16 v[214:215], v218 offset:24576
	ds_read_b64_tr_b16 v[216:217], v218 offset:28672
	s_waitcnt lgkmcnt(8)
	v_mfma_f32_32x32x16_bf16 v[32:47], v[238:241], v[242:245], v[32:47]
	ds_read_b64_tr_b16 v[238:239], v219 offset:24576
	ds_read_b64_tr_b16 v[240:241], v219 offset:28672
	s_cmp_lg_u64 s[12:13], 0
	s_cbranch_scc1 .Latt_nd2_6
	s_lshl_b32 s101, s100, 15
	s_add_i32 m0, s37, s101
	s_add_u32 s100, s20, 0x1000
	s_addc_u32 s101, s21, 0
	global_load_lds_dwordx4 v182, s[100:101]

.LBB0_1858:
	s_cmp_gt_i32 s14, s69
	s_cbranch_scc1 .LBB0_1869
	s_add_i32 s100, s14, 63
	s_cmp_le_i32 s100, s68
	s_cbranch_scc0 .Latt_slow_7
	s_lshl_b32 s98, s11, 14
	s_lshl_b32 s99, s11, 15
	s_add_i32 s99, s99, 0xc000
	v_add_u32_e32 v206, s98, v196
	ds_read_b128 v[206:209], v206
	v_add_u32_e32 v210, s98, v197
	ds_read_b128 v[210:213], v210
	v_add_u32_e32 v214, s98, v198
	ds_read_b128 v[214:217], v214
	v_add_u32_e32 v238, s98, v199
	ds_read_b128 v[238:241], v238
	v_add_u32_e32 v242, s98, v200
	ds_read_b128 v[242:245], v242
	v_add_u32_e32 v250, s98, v201
	ds_read_b128 v[250:253], v250
	v_add_u32_e32 v222, s98, v202
	ds_read_b128 v[222:225], v222
	v_add_u32_e32 v226, s98, v203
	ds_read_b128 v[226:229], v226
	v_bfe_u32 v246, v204, 2, 2
	v_bfe_u32 v247, v204, 5, 1
	v_lshl_or_b32 v247, v247, 2, v246
	v_and_b32_e32 v249, 3, v204
	v_and_b32_e32 v254, 16, v204
	v_lshl_or_b32 v249, v249, 2, v254
	v_lshlrev_b32_e32 v249, 1, v249
	v_lshl_add_u32 v247, v247, 9, v249
	v_add_u32_e32 v247, s99, v247
	v_lshlrev_b32_e32 v246, 6, v246
	v_add_u32_e32 v205, v247, v246
	v_xor_b32_e32 v249, 64, v246
	v_add_u32_e32 v218, v247, v249
	v_xor_b32_e32 v249, 0x80, v246
	v_add_u32_e32 v219, v247, v249
	v_xor_b32_e32 v249, 0xc0, v246
	v_add_u32_e32 v221, v247, v249
	s_waitcnt lgkmcnt(7)
	v_mfma_f32_32x32x16_bf16 v[128:143], v[206:209], v[144:147], 0
	v_add_u32_e32 v206, s98, v196
	ds_read_b128 v[206:209], v206 offset:8192
	s_waitcnt lgkmcnt(7)
	v_mfma_f32_32x32x16_bf16 v[128:143], v[210:213], v[148:151], v[128:143]
	v_add_u32_e32 v210, s98, v197
	ds_read_b128 v[210:213], v210 offset:8192
	s_waitcnt lgkmcnt(7)
	v_mfma_f32_32x32x16_bf16 v[128:143], v[214:217], v[152:155], v[128:143]
	v_add_u32_e32 v214, s98, v198
	ds_read_b128 v[214:217], v214 offset:8192
	s_waitcnt lgkmcnt(7)
	v_mfma_f32_32x32x16_bf16 v[128:143], v[238:241], v[156:159], v[128:143]
	v_add_u32_e32 v238, s98, v199
	ds_read_b128 v[238:241], v238 offset:8192
	s_waitcnt lgkmcnt(7)
	v_mfma_f32_32x32x16_bf16 v[128:143], v[242:245], v[160:163], v[128:143]
	v_add_u32_e32 v242, s98, v200
	ds_read_b128 v[242:245], v242 offset:8192
	s_waitcnt lgkmcnt(7)
	v_mfma_f32_32x32x16_bf16 v[128:143], v[250:253], v[164:167], v[128:143]
	v_add_u32_e32 v250, s98, v201
	ds_read_b128 v[250:253], v250 offset:8192
	s_waitcnt lgkmcnt(7)
	v_mfma_f32_32x32x16_bf16 v[128:143], v[222:225], v[168:171], v[128:143]
	s_waitcnt lgkmcnt(6)
	v_mfma_f32_32x32x16_bf16 v[128:143], v[226:229], v[172:175], v[128:143]
	s_waitcnt lgkmcnt(5)
	v_mfma_f32_32x32x16_bf16 v[222:237], v[206:209], v[144:147], 0
	v_add_u32_e32 v206, s98, v202
	ds_read_b128 v[206:209], v206 offset:8192
	s_nop 7
	v_max3_f32 v246, v128, v129, v130
	v_max3_f32 v247, v131, v132, v133
	v_max3_f32 v246, v246, v134, v135
	v_max3_f32 v247, v247, v136, v137
	v_max3_f32 v246, v246, v138, v139
	v_max3_f32 v247, v247, v140, v141
	v_max3_f32 v246, v246, v142, v143
	s_waitcnt lgkmcnt(5)
	v_mfma_f32_32x32x16_bf16 v[222:237], v[210:213], v[148:151], v[222:237]
	v_add_u32_e32 v210, s98, v203
	ds_read_b128 v[210:213], v210 offset:8192
	v_max_f32_e32 v246, v246, v247
	v_mov_b32_e32 v247, v246
	v_add_f32_e32 v249, 0x41000000, v190
	s_nop 1
	v_permlane32_swap_b32_e32 v246, v247
	v_max_f32_e32 v246, v246, v247
	v_cmp_gt_f32_e32 vcc, v246, v249
	s_cbranch_vccz .Latt_nr0_7
	v_max_f32_e32 v246, v190, v246
	v_sub_f32_e32 v190, v190, v246
	v_exp_f32_e32 v190, v190
	s_nop 0
	v_pk_mul_f32 v[126:127], v[126:127], v[190:191] op_sel_hi:[1,0]
	v_pk_mul_f32 v[124:125], v[124:125], v[190:191] op_sel_hi:[1,0]
	v_pk_mul_f32 v[122:123], v[122:123], v[190:191] op_sel_hi:[1,0]
	v_pk_mul_f32 v[120:121], v[120:121], v[190:191] op_sel_hi:[1,0]
	v_pk_mul_f32 v[118:119], v[118:119], v[190:191] op_sel_hi:[1,0]
	v_pk_mul_f32 v[116:117], v[116:117], v[190:191] op_sel_hi:[1,0]
	v_pk_mul_f32 v[114:115], v[114:115], v[190:191] op_sel_hi:[1,0]
	v_pk_mul_f32 v[112:113], v[112:113], v[190:191] op_sel_hi:[1,0]
	v_pk_mul_f32 v[110:111], v[110:111], v[190:191] op_sel_hi:[1,0]
	v_pk_mul_f32 v[108:109], v[108:109], v[190:191] op_sel_hi:[1,0]
	v_pk_mul_f32 v[106:107], v[106:107], v[190:191] op_sel_hi:[1,0]
	v_pk_mul_f32 v[104:105], v[104:105], v[190:191] op_sel_hi:[1,0]
	v_pk_mul_f32 v[102:103], v[102:103], v[190:191] op_sel_hi:[1,0]
	v_pk_mul_f32 v[100:101], v[100:101], v[190:191] op_sel_hi:[1,0]
	v_pk_mul_f32 v[98:99], v[98:99], v[190:191] op_sel_hi:[1,0]
	v_pk_mul_f32 v[96:97], v[96:97], v[190:191] op_sel_hi:[1,0]
	v_pk_mul_f32 v[94:95], v[94:95], v[190:191] op_sel_hi:[1,0]
	v_pk_mul_f32 v[92:93], v[92:93], v[190:191] op_sel_hi:[1,0]
	v_pk_mul_f32 v[90:91], v[90:91], v[190:191] op_sel_hi:[1,0]
	v_pk_mul_f32 v[88:89], v[88:89], v[190:191] op_sel_hi:[1,0]
	v_pk_mul_f32 v[86:87], v[86:87], v[190:191] op_sel_hi:[1,0]
	v_pk_mul_f32 v[84:85], v[84:85], v[190:191] op_sel_hi:[1,0]
	v_pk_mul_f32 v[82:83], v[82:83], v[190:191] op_sel_hi:[1,0]
	v_pk_mul_f32 v[80:81], v[80:81], v[190:191] op_sel_hi:[1,0]
	v_pk_mul_f32 v[78:79], v[78:79], v[190:191] op_sel_hi:[1,0]
	v_pk_mul_f32 v[76:77], v[76:77], v[190:191] op_sel_hi:[1,0]
	v_pk_mul_f32 v[74:75], v[74:75], v[190:191] op_sel_hi:[1,0]
	v_pk_mul_f32 v[72:73], v[72:73], v[190:191] op_sel_hi:[1,0]
	v_pk_mul_f32 v[70:71], v[70:71], v[190:191] op_sel_hi:[1,0]
	v_pk_mul_f32 v[68:69], v[68:69], v[190:191] op_sel_hi:[1,0]
	v_pk_mul_f32 v[66:67], v[66:67], v[190:191] op_sel_hi:[1,0]
	v_pk_mul_f32 v[64:65], v[64:65], v[190:191] op_sel_hi:[1,0]
	v_pk_mul_f32 v[62:63], v[62:63], v[190:191] op_sel_hi:[1,0]
	v_pk_mul_f32 v[60:61], v[60:61], v[190:191] op_sel_hi:[1,0]
	v_pk_mul_f32 v[58:59], v[58:59], v[190:191] op_sel_hi:[1,0]
	v_pk_mul_f32 v[56:57], v[56:57], v[190:191] op_sel_hi:[1,0]
	v_pk_mul_f32 v[54:55], v[54:55], v[190:191] op_sel_hi:[1,0]
	v_pk_mul_f32 v[52:53], v[52:53], v[190:191] op_sel_hi:[1,0]
	v_pk_mul_f32 v[50:51], v[50:51], v[190:191] op_sel_hi:[1,0]
	v_pk_mul_f32 v[48:49], v[48:49], v[190:191] op_sel_hi:[1,0]
	v_pk_mul_f32 v[46:47], v[46:47], v[190:191] op_sel_hi:[1,0]
	v_pk_mul_f32 v[44:45], v[44:45], v[190:191] op_sel_hi:[1,0]
	v_pk_mul_f32 v[42:43], v[42:43], v[190:191] op_sel_hi:[1,0]
	v_pk_mul_f32 v[40:41], v[40:41], v[190:191] op_sel_hi:[1,0]
	v_pk_mul_f32 v[38:39], v[38:39], v[190:191] op_sel_hi:[1,0]
	v_pk_mul_f32 v[36:37], v[36:37], v[190:191] op_sel_hi:[1,0]
	v_pk_mul_f32 v[34:35], v[34:35], v[190:191] op_sel_hi:[1,0]
	v_pk_mul_f32 v[32:33], v[32:33], v[190:191] op_sel_hi:[1,0]
	v_pk_mul_f32 v[30:31], v[30:31], v[190:191] op_sel_hi:[1,0]
	v_pk_mul_f32 v[28:29], v[28:29], v[190:191] op_sel_hi:[1,0]
	v_pk_mul_f32 v[26:27], v[26:27], v[190:191] op_sel_hi:[1,0]
	v_pk_mul_f32 v[24:25], v[24:25], v[190:191] op_sel_hi:[1,0]
	v_pk_mul_f32 v[22:23], v[22:23], v[190:191] op_sel_hi:[1,0]
	v_pk_mul_f32 v[20:21], v[20:21], v[190:191] op_sel_hi:[1,0]
	v_pk_mul_f32 v[18:19], v[18:19], v[190:191] op_sel_hi:[1,0]
	v_pk_mul_f32 v[16:17], v[16:17], v[190:191] op_sel_hi:[1,0]
	v_pk_mul_f32 v[14:15], v[14:15], v[190:191] op_sel_hi:[1,0]
	v_pk_mul_f32 v[12:13], v[12:13], v[190:191] op_sel_hi:[1,0]
	v_pk_mul_f32 v[10:11], v[10:11], v[190:191] op_sel_hi:[1,0]
	v_pk_mul_f32 v[8:9], v[8:9], v[190:191] op_sel_hi:[1,0]
	v_pk_mul_f32 v[6:7], v[6:7], v[190:191] op_sel_hi:[1,0]
	v_pk_mul_f32 v[4:5], v[4:5], v[190:191] op_sel_hi:[1,0]
	v_pk_mul_f32 v[2:3], v[2:3], v[190:191] op_sel_hi:[1,0]
	v_pk_mul_f32 v[0:1], v[0:1], v[190:191] op_sel_hi:[1,0]
	v_mul_f32_e32 v195, v195, v190
	v_mov_b32_e32 v190, v246

.Latt_pv1_7:
	s_waitcnt lgkmcnt(8)
	v_mfma_f32_32x32x16_bf16 v[112:127], v[238:241], v[242:245], v[112:127]
	ds_read_b64_tr_b16 v[238:239], v218 offset:16640
	ds_read_b64_tr_b16 v[240:241], v218 offset:20736
	s_waitcnt lgkmcnt(8)
	v_mfma_f32_32x32x16_bf16 v[96:111], v[206:209], v[242:245], v[96:111]
	ds_read_b64_tr_b16 v[206:207], v219 offset:16640
	ds_read_b64_tr_b16 v[208:209], v219 offset:20736
	s_cmp_lg_u64 s[8:9], 0
	s_cbranch_scc1 .Latt_nd0_7
	s_sub_i32 s100, s11, 1
	s_cmp_eq_u32 s11, 0
	s_cselect_b32 s100, 2, s100
	s_lshl_b32 s101, s100, 14
	s_add_i32 m0, s36, s101
	s_nop 0
	global_load_lds_dwordx4 v178, s[22:23]
.Latt_nd0_7:
	s_waitcnt lgkmcnt(8)
	v_mfma_f32_32x32x16_bf16 v[80:95], v[210:213], v[242:245], v[80:95]
	ds_read_b64_tr_b16 v[210:211], v221 offset:16640
	ds_read_b64_tr_b16 v[212:213], v221 offset:20736
	s_waitcnt lgkmcnt(8)
	v_mfma_f32_32x32x16_bf16 v[64:79], v[128:131], v[242:245], v[64:79]
	ds_read_b64_tr_b16 v[222:223], v205 offset:24576
	ds_read_b64_tr_b16 v[224:225], v205 offset:28672
	s_cmp_lg_u64 s[8:9], 0
	s_cbranch_scc1 .Latt_nd1_7
	s_add_i32 m0, m0, 0x400
	s_nop 0
	global_load_lds_dwordx4 v180, s[22:23]
.Latt_nd1_7:
	s_waitcnt lgkmcnt(8)
	v_mfma_f32_32x32x16_bf16 v[48:63], v[214:217], v[242:245], v[48:63]
	ds_read_b64_tr_b16 v[214:215], v218 offset:24576
	ds_read_b64_tr_b16 v[216:217], v218 offset:28672
	s_waitcnt lgkmcnt(8)
	v_mfma_f32_32x32x16_bf16 v[32:47], v[238:241], v[242:245], v[32:47]
	ds_read_b64_tr_b16 v[238:239], v219 offset:24576
	ds_read_b64_tr_b16 v[240:241], v219 offset:28672
	s_cmp_lg_u64 s[8:9], 0
	s_cbranch_scc1 .Latt_nd2_7
	s_lshl_b32 s101, s100, 15
	s_add_i32 m0, s37, s101
	s_add_u32 s100, s22, 0xf00
	s_addc_u32 s101, s23, 0
	global_load_lds_dwordx4 v182, s[100:101]
